# GEMM K-loops: s_setprio 1 during the MFMA stretches, 0 around the load/LDS-DMA issue burst and the end-of-iteration wait
# baseline (speedup 1.0000x reference)
; #define MFMA16(a, b, c) __builtin_amdgcn_mfma_f32_16x16x32_bf16((a), (b), (c), 0, 0, 0)
; template <class Epi>
; DEVI void gemm_tile256b(const bf16_t* __restrict__ A, int lda, const bf16_t* __restrict__ Bt, int K,
;                         int m0, int n0, char* smem, Epi epi) {
;     ...
;   for (int kt = 0; kt < nk; ++kt) {
;     const char* base = smem + (kt & 1) * 32768;
;     const bool more = kt + 1 < nk;
;     if (more) {
; #pragma unroll
;       for (int i = 0; i < 8; ++i) ra[i] = *(const u32x4*)(ag + (size_t)(i * 32) * lda + (kt + 1) * 64);
;     }
; #pragma unroll
;     for (int i = 0; i < 4; ++i) b1[i] = *(const bf16x8*)(bp + ((size_t)i * kb32 + kt * 2 + 1) * 512);
;     {
;       bf16x8 af[8];
; #pragma unroll
;       for (int i = 0; i < 8; ++i) af[i] = *(const bf16x8*)(base + a_rd + i * 2048);
; #pragma unroll
;       for (int mi = 0; mi < 8; ++mi)
; #pragma unroll
;         for (int ni = 0; ni < 4; ++ni) acc[mi][ni] = MFMA16(b0[ni], af[mi], acc[mi][ni]);
;     }
;     if (more) {
; #pragma unroll
;       for (int i = 0; i < 4; ++i) b0[i] = *(const bf16x8*)(bp + ((size_t)i * kb32 + kt * 2 + 2) * 512);
;     }
;     {
;       bf16x8 af[8];
; #pragma unroll
;       for (int i = 0; i < 8; ++i) af[i] = *(const bf16x8*)(base + ((a_rd + i * 2048) ^ 64));
; #pragma unroll
;       for (int mi = 0; mi < 8; ++mi)
; #pragma unroll
;         for (int ni = 0; ni < 4; ++ni) acc[mi][ni] = MFMA16(b1[ni], af[mi], acc[mi][ni]);
;     }
;     if (more) {
;       char* nb = smem + ((kt + 1) & 1) * 32768 + lds_w;
; #pragma unroll
;       for (int i = 0; i < 8; ++i) *(u32x4*)(nb + i * 4096) = ra[i];
;     }
;     __syncthreads();
;   }
.LBB0_50:
	s_setprio 1
	s_add_i32 s13, s1, 0xffff8000
	s_and_b32 s13, s13, 0x8000
	s_add_i32 s13, s13, 32
	v_add_u32_e32 v0, s13, v172
	ds_read_b128 v[146:149], v0
	ds_read_b128 v[150:153], v0 offset:2048
	v_lshl_add_u64 v[154:155], v[164:165], 0, s[28:29]
	v_add_co_u32_e32 v156, vcc, s34, v154
	s_waitcnt vmcnt(3) lgkmcnt(1)
	v_mfma_f32_16x16x32_bf16 v[122:125], v[10:13], v[146:149], v[122:125]
	v_addc_co_u32_e32 v157, vcc, 0, v155, vcc
	v_add_co_u32_e32 v158, vcc, s35, v154
	s_waitcnt vmcnt(2)
	v_mfma_f32_16x16x32_bf16 v[118:121], v[14:17], v[146:149], v[118:121]
	v_addc_co_u32_e32 v159, vcc, 0, v155, vcc
	v_add_co_u32_e32 v160, vcc, s38, v154
	s_waitcnt vmcnt(1)
	v_mfma_f32_16x16x32_bf16 v[114:117], v[6:9], v[146:149], v[114:117]
	v_addc_co_u32_e32 v161, vcc, 0, v155, vcc
	v_add_co_u32_e32 v182, vcc, s39, v154
	s_waitcnt vmcnt(0)
	v_mfma_f32_16x16x32_bf16 v[106:109], v[2:5], v[146:149], v[106:109]
	v_addc_co_u32_e32 v183, vcc, 0, v155, vcc
	v_lshl_add_u64 v[164:165], v[164:165], 0, s[64:65]
	s_waitcnt lgkmcnt(0)
	v_mfma_f32_16x16x32_bf16 v[102:105], v[10:13], v[150:153], v[102:105]
	v_mfma_f32_16x16x32_bf16 v[98:101], v[14:17], v[150:153], v[98:101]
	v_mfma_f32_16x16x32_bf16 v[82:85], v[6:9], v[150:153], v[82:85]
	v_mfma_f32_16x16x32_bf16 v[74:77], v[2:5], v[150:153], v[74:77]
	ds_read_b128 v[146:149], v0 offset:4096
	ds_read_b128 v[150:153], v0 offset:6144
	s_waitcnt lgkmcnt(1)
	v_mfma_f32_16x16x32_bf16 v[70:73], v[10:13], v[146:149], v[70:73]
	v_mfma_f32_16x16x32_bf16 v[66:69], v[14:17], v[146:149], v[66:69]
	v_mfma_f32_16x16x32_bf16 v[62:65], v[6:9], v[146:149], v[62:65]
	v_mfma_f32_16x16x32_bf16 v[54:57], v[2:5], v[146:149], v[54:57]
	s_waitcnt lgkmcnt(0)
	v_mfma_f32_16x16x32_bf16 v[42:45], v[10:13], v[150:153], v[42:45]
	v_mfma_f32_16x16x32_bf16 v[30:33], v[14:17], v[150:153], v[30:33]
	v_mfma_f32_16x16x32_bf16 v[34:37], v[6:9], v[150:153], v[34:37]
	v_mfma_f32_16x16x32_bf16 v[38:41], v[2:5], v[150:153], v[38:41]
	ds_read_b128 v[146:149], v0 offset:8192
	ds_read_b128 v[150:153], v0 offset:10240
	s_waitcnt lgkmcnt(1)
	v_mfma_f32_16x16x32_bf16 v[18:21], v[10:13], v[146:149], v[18:21]
	v_mfma_f32_16x16x32_bf16 v[26:29], v[14:17], v[146:149], v[26:29]
	v_mfma_f32_16x16x32_bf16 v[22:25], v[6:9], v[146:149], v[22:25]
	v_mfma_f32_16x16x32_bf16 v[50:53], v[2:5], v[146:149], v[50:53]
	s_waitcnt lgkmcnt(0)
	v_mfma_f32_16x16x32_bf16 v[58:61], v[10:13], v[150:153], v[58:61]
	v_mfma_f32_16x16x32_bf16 v[46:49], v[14:17], v[150:153], v[46:49]
	v_mfma_f32_16x16x32_bf16 v[94:97], v[6:9], v[150:153], v[94:97]
	v_mfma_f32_16x16x32_bf16 v[110:113], v[2:5], v[150:153], v[110:113]
	ds_read_b128 v[146:149], v0 offset:12288
	ds_read_b128 v[150:153], v0 offset:14336
	v_add_u32_e32 v0, s13, v171
	s_waitcnt lgkmcnt(1)
	v_mfma_f32_16x16x32_bf16 v[78:81], v[10:13], v[146:149], v[78:81]
	v_mfma_f32_16x16x32_bf16 v[90:93], v[14:17], v[146:149], v[90:93]
	v_mfma_f32_16x16x32_bf16 v[86:89], v[6:9], v[146:149], v[86:89]
	v_mfma_f32_16x16x32_bf16 v[142:145], v[2:5], v[146:149], v[142:145]
	s_setprio 0
	global_load_dwordx4 v[146:149], v[156:157], off offset:1024
	ds_read_b128 v[174:177], v0
	ds_read_b128 v[178:181], v0 offset:2048
	s_waitcnt lgkmcnt(2)
	v_mfma_f32_16x16x32_bf16 v[138:141], v[10:13], v[150:153], v[138:141]
	global_load_dwordx4 v[10:13], v[156:157], off offset:2048
	v_mfma_f32_16x16x32_bf16 v[134:137], v[14:17], v[150:153], v[134:137]
	v_mfma_f32_16x16x32_bf16 v[130:133], v[6:9], v[150:153], v[130:133]
	v_mfma_f32_16x16x32_bf16 v[126:129], v[2:5], v[150:153], v[126:129]
	global_load_dwordx4 v[150:153], v[158:159], off offset:1024
	global_load_dwordx4 v[14:17], v[158:159], off offset:2048
	global_load_dwordx4 v[154:157], v[160:161], off offset:1024
	global_load_dwordx4 v[6:9], v[160:161], off offset:2048
	s_nop 0
	global_load_dwordx4 v[158:161], v[182:183], off offset:1024
	global_load_dwordx4 v[2:5], v[182:183], off offset:2048
	v_lshrrev_b32_e32 v195, 6, v206
	v_lshl_add_u64 v[190:191], v[166:167], 0, s[28:29]
	v_lshrrev_b32_e32 v194, 3, v206
	v_readfirstlane_b32 s99, v195
	v_and_b32_e32 v194, 7, v194
	s_and_b32 s98, s1, 0x8000
	v_lshlrev_b32_e32 v194, 4, v194
	s_lshl_b32 s99, s99, 10
	v_xor_b32_e32 v190, v194, v190
	s_add_u32 s98, s98, s99
	s_add_u32 s98, s98, 32
	s_mov_b32 s101, 0
	s_add_u32 s100, s18, 0x80
	v_lshl_add_u64 v[192:193], v[190:191], 0, s[100:101]
	s_mov_b32 m0, s98
	s_nop 0
	global_load_lds_dwordx4 v[192:193], off
	s_mov_b32 s100, 0x9c63080
	v_lshl_add_u64 v[192:193], v[190:191], 0, s[100:101]
	s_add_u32 m0, s98, 0x1000
	s_nop 0
	global_load_lds_dwordx4 v[192:193], off
	s_mov_b32 s100, 0x9c73080
	v_lshl_add_u64 v[192:193], v[190:191], 0, s[100:101]
	s_add_u32 m0, s98, 0x2000
	s_nop 0
	global_load_lds_dwordx4 v[192:193], off
	s_add_u32 s100, s24, 0x80
	v_lshl_add_u64 v[192:193], v[190:191], 0, s[100:101]
	s_add_u32 m0, s98, 0x3000
	s_nop 0
	global_load_lds_dwordx4 v[192:193], off
	s_mov_b32 s100, 0x9c93080
	v_lshl_add_u64 v[192:193], v[190:191], 0, s[100:101]
	s_add_u32 m0, s98, 0x4000
	s_nop 0
	global_load_lds_dwordx4 v[192:193], off
	s_mov_b32 s100, 0x9ca3080
	v_lshl_add_u64 v[192:193], v[190:191], 0, s[100:101]
	s_add_u32 m0, s98, 0x5000
	s_nop 0
	global_load_lds_dwordx4 v[192:193], off
	s_add_u32 s100, s25, 0x80
	v_lshl_add_u64 v[192:193], v[190:191], 0, s[100:101]
	s_add_u32 m0, s98, 0x6000
	s_nop 0
	global_load_lds_dwordx4 v[192:193], off
	s_mov_b32 s100, 0x9cc3080
	v_lshl_add_u64 v[192:193], v[190:191], 0, s[100:101]
	s_add_u32 m0, s98, 0x7000
	s_nop 0
	global_load_lds_dwordx4 v[192:193], off
	s_setprio 1
	s_waitcnt vmcnt(15) lgkmcnt(1)
	v_mfma_f32_16x16x32_bf16 v[122:125], v[146:149], v[174:177], v[122:125]
	s_nop 0
	s_waitcnt vmcnt(13)
; #define MFMA16(a, b, c) __builtin_amdgcn_mfma_f32_16x16x32_bf16((a), (b), (c), 0, 0, 0)
; template <class Epi>
; DEVI void gemm_tile256b(const bf16_t* __restrict__ A, int lda, const bf16_t* __restrict__ Bt, int K,
;                         int m0, int n0, char* smem, Epi epi) {
;     ...
;   for (int kt = 0; kt < nk; ++kt) {
;     const char* base = smem + (kt & 1) * 32768;
;     const bool more = kt + 1 < nk;
;     if (more) {
; #pragma unroll
;       for (int i = 0; i < 8; ++i) ra[i] = *(const u32x4*)(ag + (size_t)(i * 32) * lda + (kt + 1) * 64);
;     }
; #pragma unroll
;     for (int i = 0; i < 4; ++i) b1[i] = *(const bf16x8*)(bp + ((size_t)i * kb32 + kt * 2 + 1) * 512);
;     {
;       bf16x8 af[8];
; #pragma unroll
;       for (int i = 0; i < 8; ++i) af[i] = *(const bf16x8*)(base + a_rd + i * 2048);
; #pragma unroll
;       for (int mi = 0; mi < 8; ++mi)
; #pragma unroll
;         for (int ni = 0; ni < 4; ++ni) acc[mi][ni] = MFMA16(b0[ni], af[mi], acc[mi][ni]);
;     }
;     if (more) {
; #pragma unroll
;       for (int i = 0; i < 4; ++i) b0[i] = *(const bf16x8*)(bp + ((size_t)i * kb32 + kt * 2 + 2) * 512);
;     }
;     {
;       bf16x8 af[8];
; #pragma unroll
;       for (int i = 0; i < 8; ++i) af[i] = *(const bf16x8*)(base + ((a_rd + i * 2048) ^ 64));
; #pragma unroll
;       for (int mi = 0; mi < 8; ++mi)
; #pragma unroll
;         for (int ni = 0; ni < 4; ++ni) acc[mi][ni] = MFMA16(b1[ni], af[mi], acc[mi][ni]);
;     }
;     if (more) {
;       char* nb = smem + ((kt + 1) & 1) * 32768 + lds_w;
; #pragma unroll
;       for (int i = 0; i < 8; ++i) *(u32x4*)(nb + i * 4096) = ra[i];
;     }
;     __syncthreads();
;   }
	v_mfma_f32_16x16x32_bf16 v[118:121], v[150:153], v[174:177], v[118:121]
	s_waitcnt vmcnt(11)
	v_mfma_f32_16x16x32_bf16 v[114:117], v[154:157], v[174:177], v[114:117]
	s_waitcnt vmcnt(9)
	v_mfma_f32_16x16x32_bf16 v[106:109], v[158:161], v[174:177], v[106:109]
	s_waitcnt lgkmcnt(0)
	v_mfma_f32_16x16x32_bf16 v[102:105], v[146:149], v[178:181], v[102:105]
	v_mfma_f32_16x16x32_bf16 v[98:101], v[150:153], v[178:181], v[98:101]
	s_nop 0
	v_mfma_f32_16x16x32_bf16 v[82:85], v[154:157], v[178:181], v[82:85]
	s_nop 0
	v_mfma_f32_16x16x32_bf16 v[74:77], v[158:161], v[178:181], v[74:77]
	ds_read_b128 v[174:177], v0 offset:4096
	ds_read_b128 v[178:181], v0 offset:6144
	s_waitcnt lgkmcnt(1)
	v_mfma_f32_16x16x32_bf16 v[70:73], v[146:149], v[174:177], v[70:73]
	s_and_b32 s13, s1, 0x8000
	v_mfma_f32_16x16x32_bf16 v[66:69], v[150:153], v[174:177], v[66:69]
	s_add_i32 s1, s1, 0x8000
	v_lshl_add_u64 v[166:167], v[166:167], 0, s[60:61]
	s_cmp_eq_u32 s1, 0x80000
	v_mfma_f32_16x16x32_bf16 v[62:65], v[154:157], v[174:177], v[62:65]
	v_mfma_f32_16x16x32_bf16 v[54:57], v[158:161], v[174:177], v[54:57]
	s_waitcnt lgkmcnt(0)
	v_mfma_f32_16x16x32_bf16 v[42:45], v[146:149], v[178:181], v[42:45]
	v_mfma_f32_16x16x32_bf16 v[30:33], v[150:153], v[178:181], v[30:33]
	v_mfma_f32_16x16x32_bf16 v[34:37], v[154:157], v[178:181], v[34:37]
	v_mfma_f32_16x16x32_bf16 v[38:41], v[158:161], v[178:181], v[38:41]
	ds_read_b128 v[174:177], v0 offset:8192
	ds_read_b128 v[178:181], v0 offset:10240
	s_waitcnt lgkmcnt(1)
	v_mfma_f32_16x16x32_bf16 v[18:21], v[146:149], v[174:177], v[18:21]
	v_mfma_f32_16x16x32_bf16 v[26:29], v[150:153], v[174:177], v[26:29]
	v_mfma_f32_16x16x32_bf16 v[22:25], v[154:157], v[174:177], v[22:25]
	v_mfma_f32_16x16x32_bf16 v[50:53], v[158:161], v[174:177], v[50:53]
	s_waitcnt lgkmcnt(0)
	v_mfma_f32_16x16x32_bf16 v[58:61], v[146:149], v[178:181], v[58:61]
	v_mfma_f32_16x16x32_bf16 v[46:49], v[150:153], v[178:181], v[46:49]
	v_mfma_f32_16x16x32_bf16 v[94:97], v[154:157], v[178:181], v[94:97]
	v_mfma_f32_16x16x32_bf16 v[110:113], v[158:161], v[178:181], v[110:113]
	ds_read_b128 v[178:181], v0 offset:12288
	ds_read_b128 v[182:185], v0 offset:14336
	s_nop 0
	s_nop 0
	s_nop 0
	s_nop 0
	s_nop 0
	s_waitcnt lgkmcnt(1)
	v_mfma_f32_16x16x32_bf16 v[78:81], v[146:149], v[178:181], v[78:81]
	v_mfma_f32_16x16x32_bf16 v[90:93], v[150:153], v[178:181], v[90:93]
	v_mfma_f32_16x16x32_bf16 v[86:89], v[154:157], v[178:181], v[86:89]
	s_setprio 0
	s_waitcnt vmcnt(0) lgkmcnt(0)
	s_barrier
	v_mfma_f32_16x16x32_bf16 v[142:145], v[158:161], v[178:181], v[142:145]
	v_mfma_f32_16x16x32_bf16 v[138:141], v[146:149], v[182:185], v[138:141]
	v_mfma_f32_16x16x32_bf16 v[134:137], v[150:153], v[182:185], v[134:137]
	v_mfma_f32_16x16x32_bf16 v[130:133], v[154:157], v[182:185], v[130:133]
	v_mfma_f32_16x16x32_bf16 v[126:129], v[158:161], v[182:185], v[126:129]
	s_cmp_eq_u32 s1, 0x80000
	s_cbranch_scc0 .LBB0_50
	s_setprio 0
	v_add_u32_e32 v0, 32, v172
	ds_read_b128 v[146:149], v0 offset:32768
	ds_read_b128 v[150:153], v0 offset:34816
	s_waitcnt lgkmcnt(1)
	v_mfma_f32_16x16x32_bf16 v[122:125], v[10:13], v[146:149], v[122:125]
	v_mfma_f32_16x16x32_bf16 v[118:121], v[14:17], v[146:149], v[118:121]
	v_mfma_f32_16x16x32_bf16 v[114:117], v[6:9], v[146:149], v[114:117]
	v_mfma_f32_16x16x32_bf16 v[106:109], v[2:5], v[146:149], v[106:109]
	s_waitcnt lgkmcnt(0)
	v_mfma_f32_16x16x32_bf16 v[102:105], v[10:13], v[150:153], v[102:105]
	v_mfma_f32_16x16x32_bf16 v[98:101], v[14:17], v[150:153], v[98:101]
	v_mfma_f32_16x16x32_bf16 v[82:85], v[6:9], v[150:153], v[82:85]
	v_mfma_f32_16x16x32_bf16 v[74:77], v[2:5], v[150:153], v[74:77]
	ds_read_b128 v[146:149], v0 offset:36864
	ds_read_b128 v[150:153], v0 offset:38912
	s_waitcnt lgkmcnt(1)
	v_mfma_f32_16x16x32_bf16 v[70:73], v[10:13], v[146:149], v[70:73]
	v_mfma_f32_16x16x32_bf16 v[66:69], v[14:17], v[146:149], v[66:69]
	v_mfma_f32_16x16x32_bf16 v[62:65], v[6:9], v[146:149], v[62:65]
	v_mfma_f32_16x16x32_bf16 v[54:57], v[2:5], v[146:149], v[54:57]
	s_waitcnt lgkmcnt(0)
	v_mfma_f32_16x16x32_bf16 v[42:45], v[10:13], v[150:153], v[42:45]
	v_mfma_f32_16x16x32_bf16 v[30:33], v[14:17], v[150:153], v[30:33]
	v_mfma_f32_16x16x32_bf16 v[34:37], v[6:9], v[150:153], v[34:37]
	v_mfma_f32_16x16x32_bf16 v[38:41], v[2:5], v[150:153], v[38:41]
	ds_read_b128 v[146:149], v0 offset:40960
	ds_read_b128 v[150:153], v0 offset:43008
	s_waitcnt lgkmcnt(1)
	v_mfma_f32_16x16x32_bf16 v[18:21], v[10:13], v[146:149], v[18:21]
	v_mfma_f32_16x16x32_bf16 v[26:29], v[14:17], v[146:149], v[26:29]
	v_mfma_f32_16x16x32_bf16 v[22:25], v[6:9], v[146:149], v[22:25]
	v_mfma_f32_16x16x32_bf16 v[50:53], v[2:5], v[146:149], v[50:53]
	s_waitcnt lgkmcnt(0)
	v_mfma_f32_16x16x32_bf16 v[146:149], v[10:13], v[150:153], v[58:61]
	v_mfma_f32_16x16x32_bf16 v[154:157], v[14:17], v[150:153], v[46:49]
	s_nop 2
	ds_read_b128 v[46:49], v0 offset:45056
	ds_read_b128 v[58:61], v0 offset:47104
	v_add_u32_e32 v0, 32, v171
	s_waitcnt lgkmcnt(1)
	v_mfma_f32_16x16x32_bf16 v[164:167], v[10:13], v[46:49], v[78:81]
	s_nop 2
	v_add_co_u32_e32 v78, vcc, 0x7000, v162
	v_mfma_f32_16x16x32_bf16 v[172:175], v[14:17], v[46:49], v[90:93]
	s_nop 0
	v_addc_co_u32_e32 v79, vcc, 0, v163, vcc
	v_mfma_f32_16x16x32_bf16 v[176:179], v[6:9], v[46:49], v[86:89]
	v_mfma_f32_16x16x32_bf16 v[142:145], v[2:5], v[46:49], v[142:145]
	v_add_co_u32_e32 v46, vcc, 0xf000, v162
	s_nop 1
	v_addc_co_u32_e32 v47, vcc, 0, v163, vcc
	s_waitcnt lgkmcnt(0)
; #define MFMA16(a, b, c) __builtin_amdgcn_mfma_f32_16x16x32_bf16((a), (b), (c), 0, 0, 0)
; template <class Epi>
; DEVI void gemm_tile256b(const bf16_t* __restrict__ A, int lda, const bf16_t* __restrict__ Bt, int K,
;                         int m0, int n0, char* smem, Epi epi) {
;     ...
;     for (int i = 0; i < 4; ++i) b1[i] = *(const bf16x8*)(bp + ((size_t)i * kb32 + kt * 2 + 1) * 512);
;     {
;       bf16x8 af[8];
; #pragma unroll
;       for (int i = 0; i < 8; ++i) af[i] = *(const bf16x8*)(base + a_rd + i * 2048);
; #pragma unroll
;       for (int mi = 0; mi < 8; ++mi)
; #pragma unroll
;         for (int ni = 0; ni < 4; ++ni) acc[mi][ni] = MFMA16(b0[ni], af[mi], acc[mi][ni]);
;     }
;     if (more) {
; #pragma unroll
;       for (int i = 0; i < 4; ++i) b0[i] = *(const bf16x8*)(bp + ((size_t)i * kb32 + kt * 2 + 2) * 512);
;     }
;     {
;       bf16x8 af[8];
; #pragma unroll
;       for (int i = 0; i < 8; ++i) af[i] = *(const bf16x8*)(base + ((a_rd + i * 2048) ^ 64));
; #pragma unroll
;       for (int mi = 0; mi < 8; ++mi)
; #pragma unroll
;         for (int ni = 0; ni < 4; ++ni) acc[mi][ni] = MFMA16(b1[ni], af[mi], acc[mi][ni]);
;     }
;     if (more) {
;       char* nb = smem + ((kt + 1) & 1) * 32768 + lds_w;
; #pragma unroll
;       for (int i = 0; i < 8; ++i) *(u32x4*)(nb + i * 4096) = ra[i];
;     }
;     __syncthreads();
;   }
; #pragma unroll
;   for (int mi = 0; mi < 8; ++mi)
; #pragma unroll
;     for (int ni = 0; ni < 4; ++ni)
;       epi(m0 + wm * 128 + mi * 16 + l15, n0 + wn * 64 + ni * 16 + quad * 4, acc[mi][ni]);
;   DEVI void operator()(int m, int n, f32x4 v) const {
;     if (m >= L) return;
;     float* h = hfrow(p, m) + n;
;     const float* src = (first && m >= 16) ? p.in[0] + (size_t)(m - 16) * 1024 + n : h;
;     f32x4 o = *(const f32x4*)src;
;     o = o * ALPHA + v;
;     *(f32x4*)h = o;
	v_mfma_f32_16x16x32_bf16 v[10:13], v[10:13], v[58:61], v[138:141]
	global_load_dwordx4 v[180:183], v[46:47], off offset:3072
	s_nop 1
	global_load_dwordx4 v[138:141], v[78:79], off offset:3072
	v_add_co_u32_e32 v78, vcc, 0x17000, v162
	v_mfma_f32_16x16x32_bf16 v[158:161], v[6:9], v[150:153], v[94:97]
	s_nop 0
	v_addc_co_u32_e32 v79, vcc, 0, v163, vcc
	v_mfma_f32_16x16x32_bf16 v[150:153], v[2:5], v[150:153], v[110:113]
	v_mfma_f32_16x16x32_bf16 v[134:137], v[14:17], v[58:61], v[134:137]
	ds_read_b128 v[14:17], v0 offset:32768
	v_mfma_f32_16x16x32_bf16 v[6:9], v[6:9], v[58:61], v[130:133]
	v_mfma_f32_16x16x32_bf16 v[2:5], v[2:5], v[58:61], v[126:129]
	v_add_co_u32_e32 v58, vcc, 0x1f000, v162
	s_nop 0
	global_load_dwordx4 v[130:133], v[78:79], off offset:3072
	v_addc_co_u32_e32 v59, vcc, 0, v163, vcc
	global_load_dwordx4 v[190:193], v[58:59], off offset:3072
	ds_read_b128 v[46:49], v0 offset:34816
	s_waitcnt vmcnt(2) lgkmcnt(1)
	v_mfma_f32_16x16x32_bf16 v[126:129], v[138:141], v[14:17], v[122:125]
	v_mfma_f32_16x16x32_bf16 v[122:125], v[180:183], v[14:17], v[118:121]
	s_waitcnt vmcnt(1)
	v_mfma_f32_16x16x32_bf16 v[118:121], v[130:133], v[14:17], v[114:117]
	s_waitcnt vmcnt(0)
	v_mfma_f32_16x16x32_bf16 v[114:117], v[190:193], v[14:17], v[106:109]
	s_waitcnt lgkmcnt(0)
	v_mfma_f32_16x16x32_bf16 v[110:113], v[138:141], v[46:49], v[102:105]
	v_mfma_f32_16x16x32_bf16 v[106:109], v[180:183], v[46:49], v[98:101]
	v_mfma_f32_16x16x32_bf16 v[102:105], v[130:133], v[46:49], v[82:85]
	v_mfma_f32_16x16x32_bf16 v[98:101], v[190:193], v[46:49], v[74:77]
	ds_read_b128 v[14:17], v0 offset:36864
	ds_read_b128 v[46:49], v0 offset:38912
	s_waitcnt lgkmcnt(1)
	v_mfma_f32_16x16x32_bf16 v[94:97], v[138:141], v[14:17], v[70:73]
	v_mfma_f32_16x16x32_bf16 v[90:93], v[180:183], v[14:17], v[66:69]
	v_mfma_f32_16x16x32_bf16 v[86:89], v[130:133], v[14:17], v[62:65]
	v_mfma_f32_16x16x32_bf16 v[82:85], v[190:193], v[14:17], v[54:57]
	s_waitcnt lgkmcnt(0)
	v_mfma_f32_16x16x32_bf16 v[74:77], v[180:183], v[46:49], v[30:33]
	ds_read_b128 v[14:17], v0 offset:40960
	s_nop 1
	ds_read_b128 v[30:33], v0 offset:43008
	v_mfma_f32_16x16x32_bf16 v[78:81], v[138:141], v[46:49], v[42:45]
	v_mfma_f32_16x16x32_bf16 v[70:73], v[130:133], v[46:49], v[34:37]
	v_mfma_f32_16x16x32_bf16 v[66:69], v[190:193], v[46:49], v[38:41]
	s_waitcnt lgkmcnt(1)
	v_mfma_f32_16x16x32_bf16 v[62:65], v[138:141], v[14:17], v[18:21]
	v_mfma_f32_16x16x32_bf16 v[58:61], v[180:183], v[14:17], v[26:29]
	v_mfma_f32_16x16x32_bf16 v[54:57], v[130:133], v[14:17], v[22:25]
	v_mfma_f32_16x16x32_bf16 v[50:53], v[190:193], v[14:17], v[50:53]
	s_waitcnt lgkmcnt(0)
	v_mfma_f32_16x16x32_bf16 v[46:49], v[138:141], v[30:33], v[146:149]
	ds_read_b128 v[14:17], v0 offset:45056
	s_nop 1
	ds_read_b128 v[146:149], v0 offset:47104
	v_and_b32_e32 v0, 0xffffff80, v168
	s_waitcnt lgkmcnt(0)
	v_mfma_f32_16x16x32_bf16 v[42:45], v[180:183], v[30:33], v[154:157]
	s_barrier
	v_mfma_f32_16x16x32_bf16 v[38:41], v[130:133], v[30:33], v[158:161]
	v_mfma_f32_16x16x32_bf16 v[34:37], v[190:193], v[30:33], v[150:153]
	v_mfma_f32_16x16x32_bf16 v[30:33], v[138:141], v[14:17], v[164:167]
	v_mfma_f32_16x16x32_bf16 v[26:29], v[180:183], v[14:17], v[172:175]
	v_mfma_f32_16x16x32_bf16 v[22:25], v[130:133], v[14:17], v[176:179]
	v_mfma_f32_16x16x32_bf16 v[18:21], v[190:193], v[14:17], v[142:145]
	v_mfma_f32_16x16x32_bf16 v[14:17], v[138:141], v[146:149], v[10:13]
	v_mfma_f32_16x16x32_bf16 v[10:13], v[180:183], v[146:149], v[134:137]
	v_mfma_f32_16x16x32_bf16 v[6:9], v[130:133], v[146:149], v[6:9]
	s_nop 1
	v_add_u32_e32 v134, s0, v0
	v_and_or_b32 v132, v168, 15, v134
	v_lshl_or_b32 v130, v169, 2, v170
	v_mfma_f32_16x16x32_bf16 v[2:5], v[190:193], v[146:149], v[2:5]
	s_movk_i32 s0, 0x4010
	v_cmp_gt_i32_e32 vcc, s0, v132
	v_ashrrev_i32_e32 v131, 31, v130
	s_and_saveexec_b64 s[38:39], vcc
	s_cbranch_execz .LBB0_53
	v_lshlrev_b32_e32 v136, 10, v132
	v_add_u32_e32 v0, -16, v132
	v_ashrrev_i32_e32 v137, 31, v136
	v_lshlrev_b64 v[138:139], 12, v[0:1]
	v_lshl_add_u64 v[136:137], v[136:137], 2, s[16:17]
	v_lshl_add_u64 v[140:141], s[26:27], 0, v[138:139]
	v_cmp_gt_i32_e64 s[0:1], 16, v132
	v_readlane_b32 s68, v248, 63
	v_readlane_b32 s69, v247, 0
	v_cndmask_b32_e64 v137, v141, v137, s[0:1]
	v_cndmask_b32_e64 v136, v140, v136, s[0:1]
	v_lshlrev_b64 v[140:141], 2, v[130:131]
	v_cmp_lt_i32_e32 vcc, 15, v132
	v_lshl_add_u64 v[142:143], v[136:137], 0, v[140:141]
	v_lshl_add_u64 v[136:137], s[68:69], 0, v[138:139]
	v_lshl_add_u64 v[136:137], v[136:137], 0, v[140:141]
	s_and_b64 vcc, s[36:37], vcc
	v_cndmask_b32_e32 v141, v143, v137, vcc
	v_cndmask_b32_e32 v140, v142, v136, vcc
	global_load_dwordx4 v[136:139], v[140:141], off
	v_readlane_b32 s70, v247, 1
	v_readlane_b32 s71, v247, 2
	v_readlane_b32 s72, v247, 3
	v_readlane_b32 s73, v247, 4
	v_readlane_b32 s74, v247, 5
	v_readlane_b32 s75, v247, 6
	v_readlane_b32 s76, v247, 7
	v_readlane_b32 s77, v247, 8
	v_readlane_b32 s78, v247, 9
	v_readlane_b32 s79, v247, 10
	v_readlane_b32 s80, v247, 11
	v_readlane_b32 s81, v247, 12
	v_readlane_b32 s82, v247, 13
	v_readlane_b32 s83, v247, 14
	s_waitcnt vmcnt(0)
	v_pk_fma_f32 v[128:129], v[138:139], s[66:67], v[128:129] op_sel_hi:[1,0,1]
	v_pk_fma_f32 v[126:127], v[136:137], s[66:67], v[126:127] op_sel_hi:[1,0,1]
	global_store_dwordx4 v[142:143], v[126:129], off
	global_load_dwordx4 v[126:129], v[140:141], off offset:64
	s_waitcnt vmcnt(0)
	v_pk_fma_f32 v[124:125], v[128:129], s[66:67], v[124:125] op_sel_hi:[1,0,1]
	v_pk_fma_f32 v[122:123], v[126:127], s[66:67], v[122:123] op_sel_hi:[1,0,1]
	global_store_dwordx4 v[142:143], v[122:125], off offset:64
	global_load_dwordx4 v[122:125], v[140:141], off offset:128
	s_waitcnt vmcnt(0)
	v_pk_fma_f32 v[120:121], v[124:125], s[66:67], v[120:121] op_sel_hi:[1,0,1]
	v_pk_fma_f32 v[118:119], v[122:123], s[66:67], v[118:119] op_sel_hi:[1,0,1]
	global_store_dwordx4 v[142:143], v[118:121], off offset:128
	global_load_dwordx4 v[118:121], v[140:141], off offset:192
	s_waitcnt vmcnt(0)
	v_pk_fma_f32 v[116:117], v[120:121], s[66:67], v[116:117] op_sel_hi:[1,0,1]
	v_pk_fma_f32 v[114:115], v[118:119], s[66:67], v[114:115] op_sel_hi:[1,0,1]
	global_store_dwordx4 v[142:143], v[114:117], off offset:192

; #define MFMA16(a, b, c) __builtin_amdgcn_mfma_f32_16x16x32_bf16((a), (b), (c), 0, 0, 0)
; template <class Epi>
; DEVI void gemm_tile256b(const bf16_t* __restrict__ A, int lda, const bf16_t* __restrict__ Bt, int K,
;                         int m0, int n0, char* smem, Epi epi) {
;     ...
;   for (int kt = 0; kt < nk; ++kt) {
;     const char* base = smem + (kt & 1) * 32768;
;     const bool more = kt + 1 < nk;
;     if (more) {
; #pragma unroll
;       for (int i = 0; i < 8; ++i) ra[i] = *(const u32x4*)(ag + (size_t)(i * 32) * lda + (kt + 1) * 64);
;     }
; #pragma unroll
;     for (int i = 0; i < 4; ++i) b1[i] = *(const bf16x8*)(bp + ((size_t)i * kb32 + kt * 2 + 1) * 512);
;     {
;       bf16x8 af[8];
; #pragma unroll
;       for (int i = 0; i < 8; ++i) af[i] = *(const bf16x8*)(base + a_rd + i * 2048);
; #pragma unroll
;       for (int mi = 0; mi < 8; ++mi)
; #pragma unroll
;         for (int ni = 0; ni < 4; ++ni) acc[mi][ni] = MFMA16(b0[ni], af[mi], acc[mi][ni]);
;     }
;     if (more) {
; #pragma unroll
;       for (int i = 0; i < 4; ++i) b0[i] = *(const bf16x8*)(bp + ((size_t)i * kb32 + kt * 2 + 2) * 512);
;     }
;     {
;       bf16x8 af[8];
; #pragma unroll
;       for (int i = 0; i < 8; ++i) af[i] = *(const bf16x8*)(base + ((a_rd + i * 2048) ^ 64));
; #pragma unroll
;       for (int mi = 0; mi < 8; ++mi)
; #pragma unroll
;         for (int ni = 0; ni < 4; ++ni) acc[mi][ni] = MFMA16(b1[ni], af[mi], acc[mi][ni]);
;     }
;     if (more) {
;       char* nb = smem + ((kt + 1) & 1) * 32768 + lds_w;
; #pragma unroll
;       for (int i = 0; i < 8; ++i) *(u32x4*)(nb + i * 4096) = ra[i];
;     }
;     __syncthreads();
;   }
.LBB0_324:
	s_setprio 1
	s_add_i32 s13, s1, 0xffff8000
	s_and_b32 s13, s13, 0x8000
	s_add_i32 s13, s13, 32
	v_add_u32_e32 v0, s13, v172
	ds_read_b128 v[146:149], v0
	ds_read_b128 v[150:153], v0 offset:2048
	v_lshl_add_u64 v[154:155], v[164:165], 0, s[28:29]
	v_add_co_u32_e32 v156, vcc, s24, v154
	s_waitcnt vmcnt(3) lgkmcnt(1)
	v_mfma_f32_16x16x32_bf16 v[122:125], v[10:13], v[146:149], v[122:125]
	v_addc_co_u32_e32 v157, vcc, 0, v155, vcc
	v_add_co_u32_e32 v158, vcc, s25, v154
	s_waitcnt vmcnt(2)
	v_mfma_f32_16x16x32_bf16 v[118:121], v[14:17], v[146:149], v[118:121]
	v_addc_co_u32_e32 v159, vcc, 0, v155, vcc
	v_add_co_u32_e32 v160, vcc, s34, v154
	s_waitcnt vmcnt(1)
	v_mfma_f32_16x16x32_bf16 v[114:117], v[6:9], v[146:149], v[114:117]
	v_addc_co_u32_e32 v161, vcc, 0, v155, vcc
	v_add_co_u32_e32 v182, vcc, s35, v154
	s_waitcnt vmcnt(0)
	v_mfma_f32_16x16x32_bf16 v[106:109], v[2:5], v[146:149], v[106:109]
	v_addc_co_u32_e32 v183, vcc, 0, v155, vcc
	v_lshl_add_u64 v[164:165], v[164:165], 0, s[64:65]
	s_waitcnt lgkmcnt(0)
	v_mfma_f32_16x16x32_bf16 v[102:105], v[10:13], v[150:153], v[102:105]
	v_mfma_f32_16x16x32_bf16 v[98:101], v[14:17], v[150:153], v[98:101]
	v_mfma_f32_16x16x32_bf16 v[82:85], v[6:9], v[150:153], v[82:85]
	v_mfma_f32_16x16x32_bf16 v[74:77], v[2:5], v[150:153], v[74:77]
	ds_read_b128 v[146:149], v0 offset:4096
	ds_read_b128 v[150:153], v0 offset:6144
	s_waitcnt lgkmcnt(1)
	v_mfma_f32_16x16x32_bf16 v[70:73], v[10:13], v[146:149], v[70:73]
	v_mfma_f32_16x16x32_bf16 v[66:69], v[14:17], v[146:149], v[66:69]
	v_mfma_f32_16x16x32_bf16 v[62:65], v[6:9], v[146:149], v[62:65]
	v_mfma_f32_16x16x32_bf16 v[54:57], v[2:5], v[146:149], v[54:57]
	s_waitcnt lgkmcnt(0)
	v_mfma_f32_16x16x32_bf16 v[42:45], v[10:13], v[150:153], v[42:45]
	v_mfma_f32_16x16x32_bf16 v[30:33], v[14:17], v[150:153], v[30:33]
	v_mfma_f32_16x16x32_bf16 v[38:41], v[6:9], v[150:153], v[38:41]
	v_mfma_f32_16x16x32_bf16 v[26:29], v[2:5], v[150:153], v[26:29]
	ds_read_b128 v[146:149], v0 offset:8192
	ds_read_b128 v[150:153], v0 offset:10240
	s_waitcnt lgkmcnt(1)
	v_mfma_f32_16x16x32_bf16 v[22:25], v[10:13], v[146:149], v[22:25]
	v_mfma_f32_16x16x32_bf16 v[18:21], v[14:17], v[146:149], v[18:21]
	v_mfma_f32_16x16x32_bf16 v[34:37], v[6:9], v[146:149], v[34:37]
	v_mfma_f32_16x16x32_bf16 v[46:49], v[2:5], v[146:149], v[46:49]
	s_waitcnt lgkmcnt(0)
	v_mfma_f32_16x16x32_bf16 v[50:53], v[10:13], v[150:153], v[50:53]
	v_mfma_f32_16x16x32_bf16 v[58:61], v[14:17], v[150:153], v[58:61]
	v_mfma_f32_16x16x32_bf16 v[94:97], v[6:9], v[150:153], v[94:97]
	v_mfma_f32_16x16x32_bf16 v[110:113], v[2:5], v[150:153], v[110:113]
	ds_read_b128 v[146:149], v0 offset:12288
	ds_read_b128 v[150:153], v0 offset:14336
	v_add_u32_e32 v0, s13, v171
	s_waitcnt lgkmcnt(1)
	v_mfma_f32_16x16x32_bf16 v[78:81], v[10:13], v[146:149], v[78:81]
	v_mfma_f32_16x16x32_bf16 v[90:93], v[14:17], v[146:149], v[90:93]
	v_mfma_f32_16x16x32_bf16 v[86:89], v[6:9], v[146:149], v[86:89]
	v_mfma_f32_16x16x32_bf16 v[142:145], v[2:5], v[146:149], v[142:145]
	s_setprio 0
	global_load_dwordx4 v[146:149], v[156:157], off offset:1024
	ds_read_b128 v[174:177], v0
	ds_read_b128 v[178:181], v0 offset:2048
	s_waitcnt lgkmcnt(2)
	v_mfma_f32_16x16x32_bf16 v[138:141], v[10:13], v[150:153], v[138:141]
	global_load_dwordx4 v[10:13], v[156:157], off offset:2048
	v_mfma_f32_16x16x32_bf16 v[134:137], v[14:17], v[150:153], v[134:137]
	v_mfma_f32_16x16x32_bf16 v[130:133], v[6:9], v[150:153], v[130:133]
	v_mfma_f32_16x16x32_bf16 v[126:129], v[2:5], v[150:153], v[126:129]
	global_load_dwordx4 v[150:153], v[158:159], off offset:1024
	global_load_dwordx4 v[14:17], v[158:159], off offset:2048
	global_load_dwordx4 v[154:157], v[160:161], off offset:1024
	global_load_dwordx4 v[6:9], v[160:161], off offset:2048
	s_nop 0
	global_load_dwordx4 v[158:161], v[182:183], off offset:1024
	global_load_dwordx4 v[2:5], v[182:183], off offset:2048
	v_lshrrev_b32_e32 v195, 6, v206
	v_lshl_add_u64 v[190:191], v[166:167], 0, s[28:29]
	v_lshrrev_b32_e32 v194, 3, v206
	v_readfirstlane_b32 s99, v195
	v_and_b32_e32 v194, 7, v194
	s_and_b32 s98, s1, 0x8000
	v_lshlrev_b32_e32 v194, 4, v194
	s_lshl_b32 s99, s99, 10
	v_xor_b32_e32 v190, v194, v190
	s_add_u32 s98, s98, s99
	s_add_u32 s98, s98, 32
	s_mov_b32 s101, 0
	s_add_u32 s100, s16, 0x80
	v_lshl_add_u64 v[192:193], v[190:191], 0, s[100:101]
	s_mov_b32 m0, s98
	s_nop 0
	global_load_lds_dwordx4 v[192:193], off
	s_add_u32 s100, s17, 0x80
	v_lshl_add_u64 v[192:193], v[190:191], 0, s[100:101]
	s_add_u32 m0, s98, 0x1000
	s_nop 0
	global_load_lds_dwordx4 v[192:193], off
	s_add_u32 s100, s18, 0x80
	v_lshl_add_u64 v[192:193], v[190:191], 0, s[100:101]
	s_add_u32 m0, s98, 0x2000
	s_nop 0
	global_load_lds_dwordx4 v[192:193], off
	s_mov_b32 s100, 0x9ce3080
	v_lshl_add_u64 v[192:193], v[190:191], 0, s[100:101]
	s_add_u32 m0, s98, 0x3000
	s_nop 0
	global_load_lds_dwordx4 v[192:193], off
	s_mov_b32 s100, 0x9d13080
	v_lshl_add_u64 v[192:193], v[190:191], 0, s[100:101]
	s_add_u32 m0, s98, 0x4000
	s_nop 0
	global_load_lds_dwordx4 v[192:193], off
	s_mov_b32 s100, 0x9d43080
	v_lshl_add_u64 v[192:193], v[190:191], 0, s[100:101]
	s_add_u32 m0, s98, 0x5000
	s_nop 0
	global_load_lds_dwordx4 v[192:193], off
	s_mov_b32 s100, 0x9d73080
	v_lshl_add_u64 v[192:193], v[190:191], 0, s[100:101]
	s_add_u32 m0, s98, 0x6000
	s_nop 0
	global_load_lds_dwordx4 v[192:193], off
	s_mov_b32 s100, 0x9da3080
	v_lshl_add_u64 v[192:193], v[190:191], 0, s[100:101]
	s_add_u32 m0, s98, 0x7000
	s_nop 0
	global_load_lds_dwordx4 v[192:193], off
	s_setprio 1
	s_waitcnt vmcnt(15) lgkmcnt(1)
	v_mfma_f32_16x16x32_bf16 v[122:125], v[146:149], v[174:177], v[122:125]
	s_waitcnt vmcnt(13)
; #define MFMA16(a, b, c) __builtin_amdgcn_mfma_f32_16x16x32_bf16((a), (b), (c), 0, 0, 0)
; template <class Epi>
; DEVI void gemm_tile256b(const bf16_t* __restrict__ A, int lda, const bf16_t* __restrict__ Bt, int K,
;                         int m0, int n0, char* smem, Epi epi) {
;     ...
;   for (int kt = 0; kt < nk; ++kt) {
;     const char* base = smem + (kt & 1) * 32768;
;     const bool more = kt + 1 < nk;
;     if (more) {
; #pragma unroll
;       for (int i = 0; i < 8; ++i) ra[i] = *(const u32x4*)(ag + (size_t)(i * 32) * lda + (kt + 1) * 64);
;     }
; #pragma unroll
;     for (int i = 0; i < 4; ++i) b1[i] = *(const bf16x8*)(bp + ((size_t)i * kb32 + kt * 2 + 1) * 512);
;     {
;       bf16x8 af[8];
; #pragma unroll
;       for (int i = 0; i < 8; ++i) af[i] = *(const bf16x8*)(base + a_rd + i * 2048);
; #pragma unroll
;       for (int mi = 0; mi < 8; ++mi)
; #pragma unroll
;         for (int ni = 0; ni < 4; ++ni) acc[mi][ni] = MFMA16(b0[ni], af[mi], acc[mi][ni]);
;     }
;     if (more) {
; #pragma unroll
;       for (int i = 0; i < 4; ++i) b0[i] = *(const bf16x8*)(bp + ((size_t)i * kb32 + kt * 2 + 2) * 512);
;     }
;     {
;       bf16x8 af[8];
; #pragma unroll
;       for (int i = 0; i < 8; ++i) af[i] = *(const bf16x8*)(base + ((a_rd + i * 2048) ^ 64));
; #pragma unroll
;       for (int mi = 0; mi < 8; ++mi)
; #pragma unroll
;         for (int ni = 0; ni < 4; ++ni) acc[mi][ni] = MFMA16(b1[ni], af[mi], acc[mi][ni]);
;     }
;     if (more) {
;       char* nb = smem + ((kt + 1) & 1) * 32768 + lds_w;
; #pragma unroll
;       for (int i = 0; i < 8; ++i) *(u32x4*)(nb + i * 4096) = ra[i];
;     }
;     __syncthreads();
;   }
	v_mfma_f32_16x16x32_bf16 v[118:121], v[150:153], v[174:177], v[118:121]
	s_waitcnt vmcnt(11)
	v_mfma_f32_16x16x32_bf16 v[114:117], v[154:157], v[174:177], v[114:117]
	s_waitcnt vmcnt(9)
	v_mfma_f32_16x16x32_bf16 v[106:109], v[158:161], v[174:177], v[106:109]
	s_waitcnt lgkmcnt(0)
	v_mfma_f32_16x16x32_bf16 v[102:105], v[146:149], v[178:181], v[102:105]
	v_mfma_f32_16x16x32_bf16 v[98:101], v[150:153], v[178:181], v[98:101]
	v_mfma_f32_16x16x32_bf16 v[82:85], v[154:157], v[178:181], v[82:85]
	s_nop 0
	v_mfma_f32_16x16x32_bf16 v[74:77], v[158:161], v[178:181], v[74:77]
	ds_read_b128 v[174:177], v0 offset:4096
	ds_read_b128 v[178:181], v0 offset:6144
	s_waitcnt lgkmcnt(1)
	v_mfma_f32_16x16x32_bf16 v[70:73], v[146:149], v[174:177], v[70:73]
	v_mfma_f32_16x16x32_bf16 v[66:69], v[150:153], v[174:177], v[66:69]
	s_and_b32 s13, s1, 0x8000
	v_mfma_f32_16x16x32_bf16 v[62:65], v[154:157], v[174:177], v[62:65]
	s_add_i32 s1, s1, 0x8000
	v_mfma_f32_16x16x32_bf16 v[54:57], v[158:161], v[174:177], v[54:57]
	v_lshl_add_u64 v[166:167], v[166:167], 0, s[60:61]
	s_cmp_eq_u32 s1, 0x80000
	s_waitcnt lgkmcnt(0)
	v_mfma_f32_16x16x32_bf16 v[42:45], v[146:149], v[178:181], v[42:45]
	v_mfma_f32_16x16x32_bf16 v[30:33], v[150:153], v[178:181], v[30:33]
	v_mfma_f32_16x16x32_bf16 v[38:41], v[154:157], v[178:181], v[38:41]
	v_mfma_f32_16x16x32_bf16 v[26:29], v[158:161], v[178:181], v[26:29]
	ds_read_b128 v[174:177], v0 offset:8192
	ds_read_b128 v[178:181], v0 offset:10240
	s_waitcnt lgkmcnt(1)
	v_mfma_f32_16x16x32_bf16 v[22:25], v[146:149], v[174:177], v[22:25]
	v_mfma_f32_16x16x32_bf16 v[18:21], v[150:153], v[174:177], v[18:21]
	v_mfma_f32_16x16x32_bf16 v[34:37], v[154:157], v[174:177], v[34:37]
	v_mfma_f32_16x16x32_bf16 v[46:49], v[158:161], v[174:177], v[46:49]
	s_waitcnt lgkmcnt(0)
	v_mfma_f32_16x16x32_bf16 v[50:53], v[146:149], v[178:181], v[50:53]
	v_mfma_f32_16x16x32_bf16 v[58:61], v[150:153], v[178:181], v[58:61]
	v_mfma_f32_16x16x32_bf16 v[94:97], v[154:157], v[178:181], v[94:97]
	v_mfma_f32_16x16x32_bf16 v[110:113], v[158:161], v[178:181], v[110:113]
	ds_read_b128 v[178:181], v0 offset:12288
	ds_read_b128 v[182:185], v0 offset:14336
	s_nop 0
	s_nop 0
	s_nop 0
	s_nop 0
	s_nop 0
	s_waitcnt lgkmcnt(1)
	v_mfma_f32_16x16x32_bf16 v[78:81], v[146:149], v[178:181], v[78:81]
	v_mfma_f32_16x16x32_bf16 v[90:93], v[150:153], v[178:181], v[90:93]
	v_mfma_f32_16x16x32_bf16 v[86:89], v[154:157], v[178:181], v[86:89]
	s_setprio 0
	s_waitcnt vmcnt(0) lgkmcnt(0)
	s_barrier
	v_mfma_f32_16x16x32_bf16 v[142:145], v[158:161], v[178:181], v[142:145]
	v_mfma_f32_16x16x32_bf16 v[138:141], v[146:149], v[182:185], v[138:141]
	v_mfma_f32_16x16x32_bf16 v[134:137], v[150:153], v[182:185], v[134:137]
	v_mfma_f32_16x16x32_bf16 v[130:133], v[154:157], v[182:185], v[130:133]
	v_mfma_f32_16x16x32_bf16 v[126:129], v[158:161], v[182:185], v[126:129]
	s_cmp_eq_u32 s1, 0x80000
	s_cbranch_scc0 .LBB0_324
	s_setprio 0
	v_add_u32_e32 v0, 32, v172
	ds_read_b128 v[146:149], v0 offset:32768
	ds_read_b128 v[150:153], v0 offset:34816
	s_waitcnt lgkmcnt(1)
	v_mfma_f32_16x16x32_bf16 v[122:125], v[10:13], v[146:149], v[122:125]
	v_mfma_f32_16x16x32_bf16 v[118:121], v[14:17], v[146:149], v[118:121]
	v_mfma_f32_16x16x32_bf16 v[114:117], v[6:9], v[146:149], v[114:117]
	v_mfma_f32_16x16x32_bf16 v[106:109], v[2:5], v[146:149], v[106:109]
	s_waitcnt lgkmcnt(0)
	v_mfma_f32_16x16x32_bf16 v[102:105], v[10:13], v[150:153], v[102:105]
	v_mfma_f32_16x16x32_bf16 v[98:101], v[14:17], v[150:153], v[98:101]
	v_mfma_f32_16x16x32_bf16 v[82:85], v[6:9], v[150:153], v[82:85]
	v_mfma_f32_16x16x32_bf16 v[74:77], v[2:5], v[150:153], v[74:77]
	ds_read_b128 v[146:149], v0 offset:36864
	ds_read_b128 v[150:153], v0 offset:38912
	s_waitcnt lgkmcnt(1)
	v_mfma_f32_16x16x32_bf16 v[70:73], v[10:13], v[146:149], v[70:73]
	v_mfma_f32_16x16x32_bf16 v[66:69], v[14:17], v[146:149], v[66:69]
	v_mfma_f32_16x16x32_bf16 v[62:65], v[6:9], v[146:149], v[62:65]
	v_mfma_f32_16x16x32_bf16 v[54:57], v[2:5], v[146:149], v[54:57]
	s_waitcnt lgkmcnt(0)
	v_mfma_f32_16x16x32_bf16 v[42:45], v[10:13], v[150:153], v[42:45]
	v_mfma_f32_16x16x32_bf16 v[30:33], v[14:17], v[150:153], v[30:33]
	v_mfma_f32_16x16x32_bf16 v[38:41], v[6:9], v[150:153], v[38:41]
	v_mfma_f32_16x16x32_bf16 v[26:29], v[2:5], v[150:153], v[26:29]
	ds_read_b128 v[146:149], v0 offset:40960
	ds_read_b128 v[150:153], v0 offset:43008
	s_waitcnt lgkmcnt(1)
	v_mfma_f32_16x16x32_bf16 v[22:25], v[10:13], v[146:149], v[22:25]
	v_mfma_f32_16x16x32_bf16 v[18:21], v[14:17], v[146:149], v[18:21]
	v_mfma_f32_16x16x32_bf16 v[34:37], v[6:9], v[146:149], v[34:37]
	v_mfma_f32_16x16x32_bf16 v[46:49], v[2:5], v[146:149], v[46:49]
	s_waitcnt lgkmcnt(0)
	v_mfma_f32_16x16x32_bf16 v[146:149], v[10:13], v[150:153], v[50:53]
	v_mfma_f32_16x16x32_bf16 v[154:157], v[14:17], v[150:153], v[58:61]
	s_nop 1
	ds_read_b128 v[50:53], v0 offset:45056
	ds_read_b128 v[58:61], v0 offset:47104
	v_add_u32_e32 v0, 32, v171
	s_waitcnt lgkmcnt(1)
	v_mfma_f32_16x16x32_bf16 v[164:167], v[10:13], v[50:53], v[78:81]
	s_nop 2
	v_add_co_u32_e32 v78, vcc, 0x7000, v162
	v_mfma_f32_16x16x32_bf16 v[172:175], v[14:17], v[50:53], v[90:93]
	s_nop 0
	v_addc_co_u32_e32 v79, vcc, 0, v163, vcc
	v_mfma_f32_16x16x32_bf16 v[176:179], v[6:9], v[50:53], v[86:89]
	v_mfma_f32_16x16x32_bf16 v[142:145], v[2:5], v[50:53], v[142:145]
	v_add_co_u32_e32 v50, vcc, 0xf000, v162
	s_nop 1
	v_addc_co_u32_e32 v51, vcc, 0, v163, vcc
	s_waitcnt lgkmcnt(0)
; #define MFMA16(a, b, c) __builtin_amdgcn_mfma_f32_16x16x32_bf16((a), (b), (c), 0, 0, 0)
; template <class Epi>
; DEVI void gemm_tile256b(const bf16_t* __restrict__ A, int lda, const bf16_t* __restrict__ Bt, int K,
;                         int m0, int n0, char* smem, Epi epi) {
;     ...
;     for (int i = 0; i < 4; ++i) b1[i] = *(const bf16x8*)(bp + ((size_t)i * kb32 + kt * 2 + 1) * 512);
;     {
;       bf16x8 af[8];
; #pragma unroll
;       for (int i = 0; i < 8; ++i) af[i] = *(const bf16x8*)(base + a_rd + i * 2048);
; #pragma unroll
;       for (int mi = 0; mi < 8; ++mi)
; #pragma unroll
;         for (int ni = 0; ni < 4; ++ni) acc[mi][ni] = MFMA16(b0[ni], af[mi], acc[mi][ni]);
;     }
;     if (more) {
; #pragma unroll
;       for (int i = 0; i < 4; ++i) b0[i] = *(const bf16x8*)(bp + ((size_t)i * kb32 + kt * 2 + 2) * 512);
;     }
;     {
;       bf16x8 af[8];
; #pragma unroll
;       for (int i = 0; i < 8; ++i) af[i] = *(const bf16x8*)(base + ((a_rd + i * 2048) ^ 64));
; #pragma unroll
;       for (int mi = 0; mi < 8; ++mi)
; #pragma unroll
;         for (int ni = 0; ni < 4; ++ni) acc[mi][ni] = MFMA16(b1[ni], af[mi], acc[mi][ni]);
;     }
;     if (more) {
;       char* nb = smem + ((kt + 1) & 1) * 32768 + lds_w;
; #pragma unroll
;       for (int i = 0; i < 8; ++i) *(u32x4*)(nb + i * 4096) = ra[i];
;     }
;     __syncthreads();
;   }
; #pragma unroll
;   for (int mi = 0; mi < 8; ++mi)
; #pragma unroll
;     for (int ni = 0; ni < 4; ++ni)
;       epi(m0 + wm * 128 + mi * 16 + l15, n0 + wn * 64 + ni * 16 + quad * 4, acc[mi][ni]);
;   DEVI void operator()(int m, int n, f32x4 v) const {
;     if (m >= L) return;
;     float* h = hfrow(p, m) + n;
;     const float* src = (first && m >= 16) ? p.in[0] + (size_t)(m - 16) * 1024 + n : h;
;     f32x4 o = *(const f32x4*)src;
;     o = o * ALPHA + v;
;     *(f32x4*)h = o;
	v_mfma_f32_16x16x32_bf16 v[10:13], v[10:13], v[58:61], v[138:141]
	global_load_dwordx4 v[180:183], v[50:51], off offset:3072
	s_nop 1
	global_load_dwordx4 v[138:141], v[78:79], off offset:3072
	v_add_co_u32_e32 v78, vcc, 0x17000, v162
	v_mfma_f32_16x16x32_bf16 v[158:161], v[6:9], v[150:153], v[94:97]
	s_nop 0
	v_addc_co_u32_e32 v79, vcc, 0, v163, vcc
	v_mfma_f32_16x16x32_bf16 v[150:153], v[2:5], v[150:153], v[110:113]
	v_mfma_f32_16x16x32_bf16 v[134:137], v[14:17], v[58:61], v[134:137]
	ds_read_b128 v[14:17], v0 offset:32768
	v_mfma_f32_16x16x32_bf16 v[6:9], v[6:9], v[58:61], v[130:133]
	v_mfma_f32_16x16x32_bf16 v[2:5], v[2:5], v[58:61], v[126:129]
	v_add_co_u32_e32 v58, vcc, 0x1f000, v162
	s_nop 0
	global_load_dwordx4 v[130:133], v[78:79], off offset:3072
	v_addc_co_u32_e32 v59, vcc, 0, v163, vcc
	global_load_dwordx4 v[190:193], v[58:59], off offset:3072
	ds_read_b128 v[50:53], v0 offset:34816
	s_waitcnt vmcnt(2) lgkmcnt(1)
	v_mfma_f32_16x16x32_bf16 v[126:129], v[138:141], v[14:17], v[122:125]
	v_mfma_f32_16x16x32_bf16 v[122:125], v[180:183], v[14:17], v[118:121]
	s_waitcnt vmcnt(1)
	v_mfma_f32_16x16x32_bf16 v[118:121], v[130:133], v[14:17], v[114:117]
	s_waitcnt vmcnt(0)
	v_mfma_f32_16x16x32_bf16 v[114:117], v[190:193], v[14:17], v[106:109]
	s_waitcnt lgkmcnt(0)
	v_mfma_f32_16x16x32_bf16 v[110:113], v[138:141], v[50:53], v[102:105]
	v_mfma_f32_16x16x32_bf16 v[106:109], v[180:183], v[50:53], v[98:101]
	v_mfma_f32_16x16x32_bf16 v[102:105], v[130:133], v[50:53], v[82:85]
	v_mfma_f32_16x16x32_bf16 v[98:101], v[190:193], v[50:53], v[74:77]
	ds_read_b128 v[14:17], v0 offset:36864
	ds_read_b128 v[50:53], v0 offset:38912
	s_waitcnt lgkmcnt(1)
	v_mfma_f32_16x16x32_bf16 v[94:97], v[138:141], v[14:17], v[70:73]
	v_mfma_f32_16x16x32_bf16 v[90:93], v[180:183], v[14:17], v[66:69]
	v_mfma_f32_16x16x32_bf16 v[86:89], v[130:133], v[14:17], v[62:65]
	v_mfma_f32_16x16x32_bf16 v[82:85], v[190:193], v[14:17], v[54:57]
	s_waitcnt lgkmcnt(0)
	v_mfma_f32_16x16x32_bf16 v[66:69], v[190:193], v[50:53], v[26:29]
	ds_read_b128 v[14:17], v0 offset:40960
	s_nop 1
	ds_read_b128 v[26:29], v0 offset:43008
	v_mfma_f32_16x16x32_bf16 v[78:81], v[138:141], v[50:53], v[42:45]
	v_mfma_f32_16x16x32_bf16 v[74:77], v[180:183], v[50:53], v[30:33]
	v_mfma_f32_16x16x32_bf16 v[70:73], v[130:133], v[50:53], v[38:41]
	s_waitcnt lgkmcnt(1)
	v_mfma_f32_16x16x32_bf16 v[62:65], v[138:141], v[14:17], v[22:25]
	v_mfma_f32_16x16x32_bf16 v[58:61], v[180:183], v[14:17], v[18:21]
	v_mfma_f32_16x16x32_bf16 v[54:57], v[130:133], v[14:17], v[34:37]
	v_mfma_f32_16x16x32_bf16 v[50:53], v[190:193], v[14:17], v[46:49]
	s_waitcnt lgkmcnt(0)
	v_mfma_f32_16x16x32_bf16 v[46:49], v[138:141], v[26:29], v[146:149]
	ds_read_b128 v[14:17], v0 offset:45056
	s_nop 1
	ds_read_b128 v[146:149], v0 offset:47104
	v_and_b32_e32 v0, 0xffffff80, v168
	v_add_u32_e32 v0, s0, v0
	v_mfma_f32_16x16x32_bf16 v[42:45], v[180:183], v[26:29], v[154:157]
	s_movk_i32 s0, 0x4010
	s_waitcnt lgkmcnt(0)
	s_barrier
	v_mfma_f32_16x16x32_bf16 v[38:41], v[130:133], v[26:29], v[158:161]
	v_mfma_f32_16x16x32_bf16 v[34:37], v[190:193], v[26:29], v[150:153]
	v_mfma_f32_16x16x32_bf16 v[30:33], v[138:141], v[14:17], v[164:167]
	v_mfma_f32_16x16x32_bf16 v[26:29], v[180:183], v[14:17], v[172:175]
	v_mfma_f32_16x16x32_bf16 v[22:25], v[130:133], v[14:17], v[176:179]
	v_mfma_f32_16x16x32_bf16 v[18:21], v[190:193], v[14:17], v[142:145]
	v_mfma_f32_16x16x32_bf16 v[14:17], v[138:141], v[146:149], v[10:13]
	v_mfma_f32_16x16x32_bf16 v[10:13], v[180:183], v[146:149], v[134:137]
	v_mfma_f32_16x16x32_bf16 v[6:9], v[130:133], v[146:149], v[6:9]
	v_and_or_b32 v132, v168, 15, v0
	v_lshl_or_b32 v130, v169, 2, v170
	v_cmp_gt_i32_e32 vcc, s0, v132
	v_mfma_f32_16x16x32_bf16 v[2:5], v[190:193], v[146:149], v[2:5]
	v_ashrrev_i32_e32 v131, 31, v130
	s_and_saveexec_b64 s[0:1], vcc
	s_cbranch_execz .LBB0_327
	v_lshlrev_b32_e32 v134, 10, v132
	v_add_u32_e32 v136, -16, v132
	v_mov_b32_e32 v137, v1
	v_ashrrev_i32_e32 v135, 31, v134
	v_lshlrev_b64 v[136:137], 12, v[136:137]
	v_lshl_add_u64 v[134:135], v[134:135], 2, s[10:11]
	v_lshl_add_u64 v[136:137], s[26:27], 0, v[136:137]
	v_cmp_gt_i32_e32 vcc, 16, v132
	s_nop 1
	v_cndmask_b32_e32 v135, v137, v135, vcc
	v_cndmask_b32_e32 v134, v136, v134, vcc
	v_lshl_add_u64 v[138:139], v[130:131], 2, v[134:135]
	global_load_dwordx4 v[134:137], v[138:139], off
	s_waitcnt vmcnt(0)
	v_pk_fma_f32 v[128:129], v[136:137], s[66:67], v[128:129] op_sel_hi:[1,0,1]
	v_pk_fma_f32 v[126:127], v[134:135], s[66:67], v[126:127] op_sel_hi:[1,0,1]
	global_store_dwordx4 v[138:139], v[126:129], off
	global_load_dwordx4 v[126:129], v[138:139], off offset:64
	s_waitcnt vmcnt(0)
	v_pk_fma_f32 v[124:125], v[128:129], s[66:67], v[124:125] op_sel_hi:[1,0,1]
	v_pk_fma_f32 v[122:123], v[126:127], s[66:67], v[122:123] op_sel_hi:[1,0,1]
	global_store_dwordx4 v[138:139], v[122:125], off offset:64
	global_load_dwordx4 v[122:125], v[138:139], off offset:128
	s_waitcnt vmcnt(0)
	v_pk_fma_f32 v[120:121], v[124:125], s[66:67], v[120:121] op_sel_hi:[1,0,1]
	v_pk_fma_f32 v[118:119], v[122:123], s[66:67], v[118:119] op_sel_hi:[1,0,1]
	global_store_dwordx4 v[138:139], v[118:121], off offset:128
	global_load_dwordx4 v[118:121], v[138:139], off offset:192
	s_waitcnt vmcnt(0)
	v_pk_fma_f32 v[116:117], v[120:121], s[66:67], v[116:117] op_sel_hi:[1,0,1]
	v_pk_fma_f32 v[114:115], v[118:119], s[66:67], v[114:115] op_sel_hi:[1,0,1]
	global_store_dwordx4 v[138:139], v[114:117], off offset:192

; #define MFMA16(a, b, c) __builtin_amdgcn_mfma_f32_16x16x32_bf16((a), (b), (c), 0, 0, 0)
; template <class Epi>
; DEVI void gemm_tile256b(const bf16_t* __restrict__ A, int lda, const bf16_t* __restrict__ Bt, int K,
;                         int m0, int n0, char* smem, Epi epi) {
;     ...
;   for (int kt = 0; kt < nk; ++kt) {
;     const char* base = smem + (kt & 1) * 32768;
;     const bool more = kt + 1 < nk;
;     if (more) {
; #pragma unroll
;       for (int i = 0; i < 8; ++i) ra[i] = *(const u32x4*)(ag + (size_t)(i * 32) * lda + (kt + 1) * 64);
;     }
; #pragma unroll
;     for (int i = 0; i < 4; ++i) b1[i] = *(const bf16x8*)(bp + ((size_t)i * kb32 + kt * 2 + 1) * 512);
;     {
;       bf16x8 af[8];
; #pragma unroll
;       for (int i = 0; i < 8; ++i) af[i] = *(const bf16x8*)(base + a_rd + i * 2048);
; #pragma unroll
;       for (int mi = 0; mi < 8; ++mi)
; #pragma unroll
;         for (int ni = 0; ni < 4; ++ni) acc[mi][ni] = MFMA16(b0[ni], af[mi], acc[mi][ni]);
;     }
;     if (more) {
; #pragma unroll
;       for (int i = 0; i < 4; ++i) b0[i] = *(const bf16x8*)(bp + ((size_t)i * kb32 + kt * 2 + 2) * 512);
;     }
;     {
;       bf16x8 af[8];
; #pragma unroll
;       for (int i = 0; i < 8; ++i) af[i] = *(const bf16x8*)(base + ((a_rd + i * 2048) ^ 64));
; #pragma unroll
;       for (int mi = 0; mi < 8; ++mi)
; #pragma unroll
;         for (int ni = 0; ni < 4; ++ni) acc[mi][ni] = MFMA16(b1[ni], af[mi], acc[mi][ni]);
;     }
;     if (more) {
;       char* nb = smem + ((kt + 1) & 1) * 32768 + lds_w;
; #pragma unroll
;       for (int i = 0; i < 8; ++i) *(u32x4*)(nb + i * 4096) = ra[i];
;     }
;     __syncthreads();
;   }
.LBB0_363:
	s_setprio 1
	s_add_i32 s13, s1, 0xffff8000
	s_and_b32 s13, s13, 0x8000
	s_add_i32 s13, s13, 32
	v_add_u32_e32 v154, s13, v172
	ds_read_b128 v[146:149], v154
	ds_read_b128 v[150:153], v154 offset:2048
	s_mov_b32 s16, 0x2680000
	v_add_u32_e32 v173, s13, v170
	s_waitcnt vmcnt(3) lgkmcnt(1)
	v_mfma_f32_16x16x32_bf16 v[134:137], v[10:13], v[146:149], v[134:137]
	s_and_b32 s13, s1, 0x8000
	s_add_i32 s1, s1, 0x8000
	v_lshl_add_u64 v[166:167], v[166:167], 0, s[60:61]
	s_waitcnt vmcnt(2)
	v_mfma_f32_16x16x32_bf16 v[130:133], v[14:17], v[146:149], v[130:133]
	s_cmp_eq_u32 s1, 0x80000
	s_waitcnt vmcnt(1)
	v_mfma_f32_16x16x32_bf16 v[126:129], v[2:5], v[146:149], v[126:129]
	s_waitcnt vmcnt(0)
	v_mfma_f32_16x16x32_bf16 v[122:125], v[6:9], v[146:149], v[122:125]
	s_waitcnt lgkmcnt(0)
	v_mfma_f32_16x16x32_bf16 v[114:117], v[10:13], v[150:153], v[114:117]
	v_mfma_f32_16x16x32_bf16 v[110:113], v[14:17], v[150:153], v[110:113]
	v_mfma_f32_16x16x32_bf16 v[106:109], v[2:5], v[150:153], v[106:109]
	v_mfma_f32_16x16x32_bf16 v[102:105], v[6:9], v[150:153], v[102:105]
	ds_read_b128 v[146:149], v154 offset:4096
	ds_read_b128 v[150:153], v154 offset:6144
	s_waitcnt lgkmcnt(1)
	v_mfma_f32_16x16x32_bf16 v[98:101], v[10:13], v[146:149], v[98:101]
	v_mfma_f32_16x16x32_bf16 v[94:97], v[14:17], v[146:149], v[94:97]
	v_mfma_f32_16x16x32_bf16 v[86:89], v[2:5], v[146:149], v[86:89]
	v_mfma_f32_16x16x32_bf16 v[82:85], v[6:9], v[146:149], v[82:85]
	s_waitcnt lgkmcnt(0)
	v_mfma_f32_16x16x32_bf16 v[74:77], v[10:13], v[150:153], v[74:77]
	v_mfma_f32_16x16x32_bf16 v[70:73], v[14:17], v[150:153], v[70:73]
	v_mfma_f32_16x16x32_bf16 v[62:65], v[2:5], v[150:153], v[62:65]
	v_mfma_f32_16x16x32_bf16 v[66:69], v[6:9], v[150:153], v[66:69]
	ds_read_b128 v[146:149], v154 offset:8192
	ds_read_b128 v[150:153], v154 offset:10240
	s_waitcnt lgkmcnt(1)
	v_mfma_f32_16x16x32_bf16 v[46:49], v[10:13], v[146:149], v[46:49]
	v_mfma_f32_16x16x32_bf16 v[50:53], v[14:17], v[146:149], v[50:53]
	v_mfma_f32_16x16x32_bf16 v[58:61], v[2:5], v[146:149], v[58:61]
	v_mfma_f32_16x16x32_bf16 v[54:57], v[6:9], v[146:149], v[54:57]
	s_waitcnt lgkmcnt(0)
	v_mfma_f32_16x16x32_bf16 v[26:29], v[10:13], v[150:153], v[26:29]
	v_mfma_f32_16x16x32_bf16 v[22:25], v[14:17], v[150:153], v[22:25]
	v_mfma_f32_16x16x32_bf16 v[18:21], v[2:5], v[150:153], v[18:21]
	v_mfma_f32_16x16x32_bf16 v[42:45], v[6:9], v[150:153], v[42:45]
	ds_read_b128 v[146:149], v154 offset:12288
	ds_read_b128 v[150:153], v154 offset:14336
	v_lshl_add_u64 v[154:155], v[164:165], 0, s[28:29]
	v_add_co_u32_e32 v156, vcc, s16, v154
	s_mov_b32 s16, 0x2688000
	s_nop 0
	v_addc_co_u32_e32 v157, vcc, 0, v155, vcc
	v_add_co_u32_e32 v158, vcc, s16, v154
	s_waitcnt lgkmcnt(1)
	v_mfma_f32_16x16x32_bf16 v[34:37], v[10:13], v[146:149], v[34:37]
	v_addc_co_u32_e32 v159, vcc, 0, v155, vcc
	s_mov_b32 s16, 0x2690000
	v_mfma_f32_16x16x32_bf16 v[38:41], v[14:17], v[146:149], v[38:41]
	v_add_co_u32_e32 v160, vcc, s16, v154
	s_mov_b32 s16, 0x2698000
	v_mfma_f32_16x16x32_bf16 v[30:33], v[2:5], v[146:149], v[30:33]
	v_addc_co_u32_e32 v161, vcc, 0, v155, vcc
	v_add_co_u32_e32 v182, vcc, s16, v154
	v_mfma_f32_16x16x32_bf16 v[142:145], v[6:9], v[146:149], v[142:145]
	s_setprio 0
	global_load_dwordx4 v[146:149], v[156:157], off offset:1024
	v_addc_co_u32_e32 v183, vcc, 0, v155, vcc
	s_waitcnt lgkmcnt(0)
	v_mfma_f32_16x16x32_bf16 v[138:141], v[10:13], v[150:153], v[138:141]
	ds_read_b128 v[174:177], v173
	ds_read_b128 v[178:181], v173 offset:2048
	global_load_dwordx4 v[10:13], v[156:157], off offset:2048
	v_mfma_f32_16x16x32_bf16 v[118:121], v[14:17], v[150:153], v[118:121]
	s_nop 0
	v_mfma_f32_16x16x32_bf16 v[90:93], v[2:5], v[150:153], v[90:93]
	s_nop 0
	v_mfma_f32_16x16x32_bf16 v[78:81], v[6:9], v[150:153], v[78:81]
	global_load_dwordx4 v[150:153], v[158:159], off offset:1024
	global_load_dwordx4 v[14:17], v[158:159], off offset:2048
	global_load_dwordx4 v[154:157], v[160:161], off offset:1024
	global_load_dwordx4 v[2:5], v[160:161], off offset:2048
	s_nop 0
	global_load_dwordx4 v[158:161], v[182:183], off offset:1024
	global_load_dwordx4 v[6:9], v[182:183], off offset:2048
	v_lshrrev_b32_e32 v195, 6, v206
	v_lshl_add_u64 v[190:191], v[166:167], 0, s[28:29]
	v_lshrrev_b32_e32 v194, 3, v206
	v_readfirstlane_b32 s99, v195
	v_and_b32_e32 v194, 7, v194
	s_and_b32 s98, s1, 0x8000
	s_xor_b32 s98, s98, 0x8000
	v_lshlrev_b32_e32 v194, 4, v194
	s_lshl_b32 s99, s99, 10
	v_xor_b32_e32 v190, v194, v190
	s_add_u32 s98, s98, s99
	s_add_u32 s98, s98, 32
	s_mov_b32 s101, 0
	s_mov_b32 s100, 0x0
	v_lshl_add_u64 v[192:193], v[190:191], 0, s[100:101]
	s_mov_b32 m0, s98
	s_nop 0
	global_load_lds_dwordx4 v[192:193], off
	s_add_u32 s100, s54, 0x0
	v_lshl_add_u64 v[192:193], v[190:191], 0, s[100:101]
	s_add_u32 m0, s98, 0x1000
	s_nop 0
	global_load_lds_dwordx4 v[192:193], off
	s_add_u32 s100, s53, 0x0
	v_lshl_add_u64 v[192:193], v[190:191], 0, s[100:101]
	s_add_u32 m0, s98, 0x2000
	s_nop 0
	global_load_lds_dwordx4 v[192:193], off
	s_add_u32 s100, s52, 0x0
	v_lshl_add_u64 v[192:193], v[190:191], 0, s[100:101]
	s_add_u32 m0, s98, 0x3000
	s_nop 0
	global_load_lds_dwordx4 v[192:193], off
	s_add_u32 s100, s56, 0x0
	v_lshl_add_u64 v[192:193], v[190:191], 0, s[100:101]
	s_add_u32 m0, s98, 0x4000
	s_nop 0
	global_load_lds_dwordx4 v[192:193], off
	s_add_u32 s100, s57, 0x0
	v_lshl_add_u64 v[192:193], v[190:191], 0, s[100:101]
	s_add_u32 m0, s98, 0x5000
	s_nop 0
	global_load_lds_dwordx4 v[192:193], off
	s_add_u32 s100, s3, 0x0
	v_lshl_add_u64 v[192:193], v[190:191], 0, s[100:101]
	s_add_u32 m0, s98, 0x6000
	s_nop 0
	global_load_lds_dwordx4 v[192:193], off
	s_add_u32 s100, s19, 0x0
	v_lshl_add_u64 v[192:193], v[190:191], 0, s[100:101]
	s_add_u32 m0, s98, 0x7000
	s_nop 0
	global_load_lds_dwordx4 v[192:193], off
	s_setprio 1
	s_waitcnt vmcnt(15) lgkmcnt(1)
; #define MFMA16(a, b, c) __builtin_amdgcn_mfma_f32_16x16x32_bf16((a), (b), (c), 0, 0, 0)
; template <class Epi>
; DEVI void gemm_tile256b(const bf16_t* __restrict__ A, int lda, const bf16_t* __restrict__ Bt, int K,
;                         int m0, int n0, char* smem, Epi epi) {
;     ...
;   for (int kt = 0; kt < nk; ++kt) {
;     const char* base = smem + (kt & 1) * 32768;
;     const bool more = kt + 1 < nk;
;     if (more) {
; #pragma unroll
;       for (int i = 0; i < 8; ++i) ra[i] = *(const u32x4*)(ag + (size_t)(i * 32) * lda + (kt + 1) * 64);
;     }
; #pragma unroll
;     for (int i = 0; i < 4; ++i) b1[i] = *(const bf16x8*)(bp + ((size_t)i * kb32 + kt * 2 + 1) * 512);
;     {
;       bf16x8 af[8];
; #pragma unroll
;       for (int i = 0; i < 8; ++i) af[i] = *(const bf16x8*)(base + a_rd + i * 2048);
; #pragma unroll
;       for (int mi = 0; mi < 8; ++mi)
; #pragma unroll
;         for (int ni = 0; ni < 4; ++ni) acc[mi][ni] = MFMA16(b0[ni], af[mi], acc[mi][ni]);
;     }
;     if (more) {
; #pragma unroll
;       for (int i = 0; i < 4; ++i) b0[i] = *(const bf16x8*)(bp + ((size_t)i * kb32 + kt * 2 + 2) * 512);
;     }
;     {
;       bf16x8 af[8];
; #pragma unroll
;       for (int i = 0; i < 8; ++i) af[i] = *(const bf16x8*)(base + ((a_rd + i * 2048) ^ 64));
; #pragma unroll
;       for (int mi = 0; mi < 8; ++mi)
; #pragma unroll
;         for (int ni = 0; ni < 4; ++ni) acc[mi][ni] = MFMA16(b1[ni], af[mi], acc[mi][ni]);
;     }
;     if (more) {
;       char* nb = smem + ((kt + 1) & 1) * 32768 + lds_w;
; #pragma unroll
;       for (int i = 0; i < 8; ++i) *(u32x4*)(nb + i * 4096) = ra[i];
;     }
;     __syncthreads();
;   }
	v_mfma_f32_16x16x32_bf16 v[134:137], v[146:149], v[174:177], v[134:137]
	s_waitcnt vmcnt(13)
	v_mfma_f32_16x16x32_bf16 v[130:133], v[150:153], v[174:177], v[130:133]
	s_waitcnt vmcnt(11)
	v_mfma_f32_16x16x32_bf16 v[126:129], v[154:157], v[174:177], v[126:129]
	s_waitcnt vmcnt(9)
	v_mfma_f32_16x16x32_bf16 v[122:125], v[158:161], v[174:177], v[122:125]
	s_waitcnt lgkmcnt(0)
	v_mfma_f32_16x16x32_bf16 v[114:117], v[146:149], v[178:181], v[114:117]
	v_lshl_add_u64 v[164:165], v[164:165], 0, s[64:65]
	v_mfma_f32_16x16x32_bf16 v[110:113], v[150:153], v[178:181], v[110:113]
	v_mfma_f32_16x16x32_bf16 v[106:109], v[154:157], v[178:181], v[106:109]
	v_mfma_f32_16x16x32_bf16 v[102:105], v[158:161], v[178:181], v[102:105]
	ds_read_b128 v[174:177], v173 offset:4096
	ds_read_b128 v[178:181], v173 offset:6144
	s_waitcnt lgkmcnt(1)
	v_mfma_f32_16x16x32_bf16 v[98:101], v[146:149], v[174:177], v[98:101]
	v_mfma_f32_16x16x32_bf16 v[94:97], v[150:153], v[174:177], v[94:97]
	v_mfma_f32_16x16x32_bf16 v[86:89], v[154:157], v[174:177], v[86:89]
	v_mfma_f32_16x16x32_bf16 v[82:85], v[158:161], v[174:177], v[82:85]
	s_waitcnt lgkmcnt(0)
	v_mfma_f32_16x16x32_bf16 v[74:77], v[146:149], v[178:181], v[74:77]
	v_mfma_f32_16x16x32_bf16 v[70:73], v[150:153], v[178:181], v[70:73]
	v_mfma_f32_16x16x32_bf16 v[62:65], v[154:157], v[178:181], v[62:65]
	v_mfma_f32_16x16x32_bf16 v[66:69], v[158:161], v[178:181], v[66:69]
	ds_read_b128 v[178:181], v173 offset:8192
	ds_read_b128 v[182:185], v173 offset:10240
	s_waitcnt lgkmcnt(1)
	v_mfma_f32_16x16x32_bf16 v[46:49], v[146:149], v[178:181], v[46:49]
	v_mfma_f32_16x16x32_bf16 v[50:53], v[150:153], v[178:181], v[50:53]
	v_mfma_f32_16x16x32_bf16 v[58:61], v[154:157], v[178:181], v[58:61]
	v_mfma_f32_16x16x32_bf16 v[54:57], v[158:161], v[178:181], v[54:57]
	s_waitcnt lgkmcnt(0)
	v_mfma_f32_16x16x32_bf16 v[26:29], v[146:149], v[182:185], v[26:29]
	v_mfma_f32_16x16x32_bf16 v[22:25], v[150:153], v[182:185], v[22:25]
	v_mfma_f32_16x16x32_bf16 v[18:21], v[154:157], v[182:185], v[18:21]
	v_mfma_f32_16x16x32_bf16 v[42:45], v[158:161], v[182:185], v[42:45]
	ds_read_b128 v[178:181], v173 offset:12288
	ds_read_b128 v[182:185], v173 offset:14336
	s_nop 0
	s_nop 0
	s_nop 0
	s_nop 0
	s_nop 0
	s_waitcnt lgkmcnt(1)
	v_mfma_f32_16x16x32_bf16 v[34:37], v[146:149], v[178:181], v[34:37]
	v_mfma_f32_16x16x32_bf16 v[38:41], v[150:153], v[178:181], v[38:41]
	v_mfma_f32_16x16x32_bf16 v[30:33], v[154:157], v[178:181], v[30:33]
	s_setprio 0
	s_waitcnt vmcnt(0) lgkmcnt(0)
	s_barrier
	v_mfma_f32_16x16x32_bf16 v[142:145], v[158:161], v[178:181], v[142:145]
	v_mfma_f32_16x16x32_bf16 v[138:141], v[146:149], v[182:185], v[138:141]
	v_mfma_f32_16x16x32_bf16 v[118:121], v[150:153], v[182:185], v[118:121]
	v_mfma_f32_16x16x32_bf16 v[90:93], v[154:157], v[182:185], v[90:93]
	v_mfma_f32_16x16x32_bf16 v[78:81], v[158:161], v[182:185], v[78:81]
	s_cmp_eq_u32 s1, 0x80000
	s_cbranch_scc0 .LBB0_363
	s_setprio 0
	v_add_u32_e32 v171, 32, v172
	ds_read_b128 v[146:149], v171 offset:32768
	s_movk_i32 s1, 0x7000
	v_add_u32_e32 v170, 32, v170
	s_waitcnt lgkmcnt(0)
	v_mfma_f32_16x16x32_bf16 v[134:137], v[10:13], v[146:149], v[134:137]
	v_mfma_f32_16x16x32_bf16 v[130:133], v[14:17], v[146:149], v[130:133]
	v_mfma_f32_16x16x32_bf16 v[126:129], v[2:5], v[146:149], v[126:129]
	v_mfma_f32_16x16x32_bf16 v[122:125], v[6:9], v[146:149], v[122:125]
	ds_read_b128 v[146:149], v171 offset:34816
	s_waitcnt lgkmcnt(0)
	v_mfma_f32_16x16x32_bf16 v[114:117], v[10:13], v[146:149], v[114:117]
	v_mfma_f32_16x16x32_bf16 v[150:153], v[14:17], v[146:149], v[110:113]
	v_mfma_f32_16x16x32_bf16 v[154:157], v[2:5], v[146:149], v[106:109]
	v_mfma_f32_16x16x32_bf16 v[146:149], v[6:9], v[146:149], v[102:105]
	s_nop 2
	ds_read_b128 v[102:105], v171 offset:36864
	s_waitcnt lgkmcnt(0)
	v_mfma_f32_16x16x32_bf16 v[164:167], v[14:17], v[102:105], v[94:97]
	s_nop 2
	ds_read_b128 v[94:97], v171 offset:38912
	s_waitcnt lgkmcnt(0)
	v_mfma_f32_16x16x32_bf16 v[74:77], v[10:13], v[94:97], v[74:77]
	v_mfma_f32_16x16x32_bf16 v[70:73], v[14:17], v[94:97], v[70:73]
	v_mfma_f32_16x16x32_bf16 v[62:65], v[2:5], v[94:97], v[62:65]
	v_mfma_f32_16x16x32_bf16 v[66:69], v[6:9], v[94:97], v[66:69]
	ds_read_b128 v[94:97], v171 offset:40960
	s_waitcnt lgkmcnt(0)
	v_mfma_f32_16x16x32_bf16 v[176:179], v[6:9], v[94:97], v[54:57]
	s_nop 2
	ds_read_b128 v[54:57], v171 offset:43008
	s_waitcnt lgkmcnt(0)
	v_mfma_f32_16x16x32_bf16 v[180:183], v[6:9], v[54:57], v[42:45]
	s_nop 2
	ds_read_b128 v[42:45], v171 offset:45056
	s_waitcnt lgkmcnt(0)
	v_mfma_f32_16x16x32_bf16 v[198:201], v[2:5], v[42:45], v[30:33]
	s_nop 2
	ds_read_b128 v[30:33], v171 offset:47104
	v_mfma_f32_16x16x32_bf16 v[158:161], v[10:13], v[102:105], v[98:101]
	v_mfma_f32_16x16x32_bf16 v[46:49], v[10:13], v[94:97], v[46:49]
	v_mfma_f32_16x16x32_bf16 v[50:53], v[14:17], v[94:97], v[50:53]
	v_mfma_f32_16x16x32_bf16 v[26:29], v[10:13], v[54:57], v[26:29]
	v_mfma_f32_16x16x32_bf16 v[22:25], v[14:17], v[54:57], v[22:25]
	v_mfma_f32_16x16x32_bf16 v[190:193], v[10:13], v[42:45], v[34:37]
	v_mfma_f32_16x16x32_bf16 v[194:197], v[14:17], v[42:45], v[38:41]
	s_waitcnt lgkmcnt(0)
; #define MFMA16(a, b, c) __builtin_amdgcn_mfma_f32_16x16x32_bf16((a), (b), (c), 0, 0, 0)
; template <class Epi>
; DEVI void gemm_tile256b(const bf16_t* __restrict__ A, int lda, const bf16_t* __restrict__ Bt, int K,
;                         int m0, int n0, char* smem, Epi epi) {
;     ...
;     for (int i = 0; i < 4; ++i) b1[i] = *(const bf16x8*)(bp + ((size_t)i * kb32 + kt * 2 + 1) * 512);
;     {
;       bf16x8 af[8];
; #pragma unroll
;       for (int i = 0; i < 8; ++i) af[i] = *(const bf16x8*)(base + a_rd + i * 2048);
; #pragma unroll
;       for (int mi = 0; mi < 8; ++mi)
; #pragma unroll
;         for (int ni = 0; ni < 4; ++ni) acc[mi][ni] = MFMA16(b0[ni], af[mi], acc[mi][ni]);
;     }
;     if (more) {
; #pragma unroll
;       for (int i = 0; i < 4; ++i) b0[i] = *(const bf16x8*)(bp + ((size_t)i * kb32 + kt * 2 + 2) * 512);
;     }
;     {
;       bf16x8 af[8];
; #pragma unroll
;       for (int i = 0; i < 8; ++i) af[i] = *(const bf16x8*)(base + ((a_rd + i * 2048) ^ 64));
; #pragma unroll
;       for (int mi = 0; mi < 8; ++mi)
; #pragma unroll
;         for (int ni = 0; ni < 4; ++ni) acc[mi][ni] = MFMA16(b1[ni], af[mi], acc[mi][ni]);
;     }
;     if (more) {
;       char* nb = smem + ((kt + 1) & 1) * 32768 + lds_w;
; #pragma unroll
;       for (int i = 0; i < 8; ++i) *(u32x4*)(nb + i * 4096) = ra[i];
;     }
;     __syncthreads();
;   }
; #pragma unroll
;   for (int mi = 0; mi < 8; ++mi)
; #pragma unroll
;     for (int ni = 0; ni < 4; ++ni)
;       epi(m0 + wm * 128 + mi * 16 + l15, n0 + wn * 64 + ni * 16 + quad * 4, acc[mi][ni]);
;   DEVI void operator()(int m, int n, f32x4 v) const {
;     if (m >= L) return;
;     *(u32x2*)(z + (size_t)m * 1024 + n) = u32x2{pack2(v[0], v[1]), pack2(v[2], v[3])};
	v_mfma_f32_16x16x32_bf16 v[10:13], v[10:13], v[30:33], v[138:141]
	v_mfma_f32_16x16x32_bf16 v[138:141], v[14:17], v[30:33], v[118:121]
	v_add_co_u32_e32 v14, vcc, s1, v162
	s_mov_b32 s1, 0xf000
	s_nop 0
	v_addc_co_u32_e32 v15, vcc, 0, v163, vcc
	global_load_dwordx4 v[14:17], v[14:15], off offset:3072
	v_mfma_f32_16x16x32_bf16 v[82:85], v[6:9], v[102:105], v[82:85]
	v_add_co_u32_e32 v34, vcc, s1, v162
	s_mov_b32 s1, 0x17000
	v_mfma_f32_16x16x32_bf16 v[142:145], v[6:9], v[42:45], v[142:145]
	v_addc_co_u32_e32 v35, vcc, 0, v163, vcc
	global_load_dwordx4 v[202:205], v[34:35], off offset:3072
	v_mfma_f32_16x16x32_bf16 v[226:229], v[6:9], v[30:33], v[78:81]
	ds_read_b128 v[6:9], v170 offset:32768
	v_mfma_f32_16x16x32_bf16 v[86:89], v[2:5], v[102:105], v[86:89]
	v_mfma_f32_16x16x32_bf16 v[172:175], v[2:5], v[94:97], v[58:61]
	v_mfma_f32_16x16x32_bf16 v[18:21], v[2:5], v[54:57], v[18:21]
	v_mfma_f32_16x16x32_bf16 v[2:5], v[2:5], v[30:33], v[90:93]
	v_add_co_u32_e32 v30, vcc, s1, v162
	s_mov_b32 s1, 0x1f000
	s_nop 0
	v_addc_co_u32_e32 v31, vcc, 0, v163, vcc
	s_waitcnt vmcnt(1) lgkmcnt(0)
	v_mfma_f32_16x16x32_bf16 v[110:113], v[14:17], v[6:9], v[134:137]
	s_nop 2
	global_load_dwordx4 v[134:137], v[30:31], off offset:3072
	v_add_co_u32_e32 v30, vcc, s1, v162
	s_waitcnt vmcnt(1)
	v_mfma_f32_16x16x32_bf16 v[106:109], v[202:205], v[6:9], v[130:133]
	v_addc_co_u32_e32 v31, vcc, 0, v163, vcc
	global_load_dwordx4 v[230:233], v[30:31], off offset:3072
	s_waitcnt vmcnt(1)
	v_mfma_f32_16x16x32_bf16 v[102:105], v[134:137], v[6:9], v[126:129]
	v_lshl_or_b32 v130, v168, 2, v169
	v_ashrrev_i32_e32 v131, 31, v130
	s_waitcnt vmcnt(0)
	v_mfma_f32_16x16x32_bf16 v[98:101], v[230:233], v[6:9], v[122:125]
	ds_read_b128 v[6:9], v170 offset:34816
	s_waitcnt lgkmcnt(0)
	v_mfma_f32_16x16x32_bf16 v[126:129], v[14:17], v[6:9], v[114:117]
	v_mfma_f32_16x16x32_bf16 v[122:125], v[202:205], v[6:9], v[150:153]
	v_mfma_f32_16x16x32_bf16 v[118:121], v[134:137], v[6:9], v[154:157]
	v_mfma_f32_16x16x32_bf16 v[114:117], v[230:233], v[6:9], v[146:149]
	ds_read_b128 v[6:9], v170 offset:36864
	s_waitcnt lgkmcnt(0)
	v_mfma_f32_16x16x32_bf16 v[94:97], v[14:17], v[6:9], v[158:161]
	v_mfma_f32_16x16x32_bf16 v[90:93], v[202:205], v[6:9], v[164:167]
	v_mfma_f32_16x16x32_bf16 v[86:89], v[134:137], v[6:9], v[86:89]
	v_mfma_f32_16x16x32_bf16 v[82:85], v[230:233], v[6:9], v[82:85]
	ds_read_b128 v[6:9], v170 offset:38912
	s_waitcnt lgkmcnt(0)
	v_mfma_f32_16x16x32_bf16 v[78:81], v[14:17], v[6:9], v[74:77]
	v_mfma_f32_16x16x32_bf16 v[74:77], v[202:205], v[6:9], v[70:73]
	v_mfma_f32_16x16x32_bf16 v[70:73], v[134:137], v[6:9], v[62:65]
	v_mfma_f32_16x16x32_bf16 v[66:69], v[230:233], v[6:9], v[66:69]
	ds_read_b128 v[6:9], v170 offset:40960
	s_waitcnt lgkmcnt(0)
	v_mfma_f32_16x16x32_bf16 v[62:65], v[14:17], v[6:9], v[46:49]
	v_mfma_f32_16x16x32_bf16 v[58:61], v[202:205], v[6:9], v[50:53]
	v_mfma_f32_16x16x32_bf16 v[54:57], v[134:137], v[6:9], v[172:175]
	v_mfma_f32_16x16x32_bf16 v[50:53], v[230:233], v[6:9], v[176:179]
	ds_read_b128 v[6:9], v170 offset:43008
	s_waitcnt lgkmcnt(0)
	v_mfma_f32_16x16x32_bf16 v[46:49], v[14:17], v[6:9], v[26:29]
	v_mfma_f32_16x16x32_bf16 v[42:45], v[202:205], v[6:9], v[22:25]
	v_mfma_f32_16x16x32_bf16 v[38:41], v[134:137], v[6:9], v[18:21]
	v_mfma_f32_16x16x32_bf16 v[34:37], v[230:233], v[6:9], v[180:183]
	ds_read_b128 v[6:9], v170 offset:45056
	s_waitcnt lgkmcnt(0)
	v_mfma_f32_16x16x32_bf16 v[18:21], v[230:233], v[6:9], v[142:145]
	s_nop 2
	ds_read_b128 v[142:145], v170 offset:47104
	s_waitcnt lgkmcnt(0)
	v_mfma_f32_16x16x32_bf16 v[30:33], v[14:17], v[6:9], v[190:193]
	s_barrier
	v_mfma_f32_16x16x32_bf16 v[14:17], v[14:17], v[142:145], v[10:13]
	s_nop 2
	v_and_b32_e32 v10, 0xffffff80, v0
	v_add_u32_e32 v10, s0, v10
	v_mfma_f32_16x16x32_bf16 v[26:29], v[202:205], v[6:9], v[194:197]
	v_and_or_b32 v132, v0, 15, v10
	s_movk_i32 s0, 0x4010
	v_cmp_gt_i32_e32 vcc, s0, v132
	v_mfma_f32_16x16x32_bf16 v[22:25], v[134:137], v[6:9], v[198:201]
	v_mfma_f32_16x16x32_bf16 v[6:9], v[202:205], v[142:145], v[138:141]
	v_mfma_f32_16x16x32_bf16 v[2:5], v[134:137], v[142:145], v[2:5]
	v_mfma_f32_16x16x32_bf16 v[10:13], v[230:233], v[142:145], v[226:229]
	s_and_saveexec_b64 s[0:1], vcc
	s_cbranch_execz .LBB0_366
	v_ashrrev_i32_e32 v133, 31, v132
	v_lshlrev_b64 v[134:135], 11, v[132:133]
	v_lshl_add_u64 v[134:135], s[10:11], 0, v[134:135]
	v_cvt_pk_bf16_f32 v110, v110, v111
	v_cvt_pk_bf16_f32 v111, v112, v113
	v_lshl_add_u64 v[112:113], v[130:131], 1, v[134:135]
	v_cvt_pk_bf16_f32 v106, v106, v107
	v_cvt_pk_bf16_f32 v107, v108, v109
	v_cvt_pk_bf16_f32 v102, v102, v103
	v_cvt_pk_bf16_f32 v103, v104, v105
	v_cvt_pk_bf16_f32 v98, v98, v99
	v_cvt_pk_bf16_f32 v99, v100, v101
	global_store_dwordx2 v[112:113], v[110:111], off
	global_store_dwordx2 v[112:113], v[106:107], off offset:32
	global_store_dwordx2 v[112:113], v[102:103], off offset:64
	global_store_dwordx2 v[112:113], v[98:99], off offset:96

; #define MFMA16(a, b, c) __builtin_amdgcn_mfma_f32_16x16x32_bf16((a), (b), (c), 0, 0, 0)
; template <class Epi>
; DEVI void gemm_tile256b(const bf16_t* __restrict__ A, int lda, const bf16_t* __restrict__ Bt, int K,
;                         int m0, int n0, char* smem, Epi epi) {
;     ...
;   for (int kt = 0; kt < nk; ++kt) {
;     const char* base = smem + (kt & 1) * 32768;
;     const bool more = kt + 1 < nk;
;     if (more) {
; #pragma unroll
;       for (int i = 0; i < 8; ++i) ra[i] = *(const u32x4*)(ag + (size_t)(i * 32) * lda + (kt + 1) * 64);
;     }
; #pragma unroll
;     for (int i = 0; i < 4; ++i) b1[i] = *(const bf16x8*)(bp + ((size_t)i * kb32 + kt * 2 + 1) * 512);
;     {
;       bf16x8 af[8];
; #pragma unroll
;       for (int i = 0; i < 8; ++i) af[i] = *(const bf16x8*)(base + a_rd + i * 2048);
; #pragma unroll
;       for (int mi = 0; mi < 8; ++mi)
; #pragma unroll
;         for (int ni = 0; ni < 4; ++ni) acc[mi][ni] = MFMA16(b0[ni], af[mi], acc[mi][ni]);
;     }
;     if (more) {
; #pragma unroll
;       for (int i = 0; i < 4; ++i) b0[i] = *(const bf16x8*)(bp + ((size_t)i * kb32 + kt * 2 + 2) * 512);
;     }
;     {
;       bf16x8 af[8];
; #pragma unroll
;       for (int i = 0; i < 8; ++i) af[i] = *(const bf16x8*)(base + ((a_rd + i * 2048) ^ 64));
; #pragma unroll
;       for (int mi = 0; mi < 8; ++mi)
; #pragma unroll
;         for (int ni = 0; ni < 4; ++ni) acc[mi][ni] = MFMA16(b1[ni], af[mi], acc[mi][ni]);
;     }
;     if (more) {
;       char* nb = smem + ((kt + 1) & 1) * 32768 + lds_w;
; #pragma unroll
;       for (int i = 0; i < 8; ++i) *(u32x4*)(nb + i * 4096) = ra[i];
;     }
;     __syncthreads();
;   }
.LBB0_421:
	s_setprio 1
	s_add_i32 s13, s1, 0xffff8000
	s_and_b32 s13, s13, 0x8000
	s_add_i32 s13, s13, 32
	v_add_u32_e32 v0, s13, v173
	ds_read_b128 v[146:149], v0
	ds_read_b128 v[150:153], v0 offset:2048
	v_lshl_add_u64 v[154:155], v[164:165], 0, s[28:29]
	v_add_co_u32_e32 v156, vcc, s16, v154
	s_waitcnt vmcnt(3) lgkmcnt(1)
	v_mfma_f32_16x16x32_bf16 v[130:133], v[10:13], v[146:149], v[130:133]
	v_addc_co_u32_e32 v157, vcc, 0, v155, vcc
	v_add_co_u32_e32 v158, vcc, s17, v154
	s_waitcnt vmcnt(2)
	v_mfma_f32_16x16x32_bf16 v[126:129], v[14:17], v[146:149], v[126:129]
	v_addc_co_u32_e32 v159, vcc, 0, v155, vcc
	v_add_co_u32_e32 v160, vcc, s18, v154
	s_waitcnt vmcnt(1)
	v_mfma_f32_16x16x32_bf16 v[122:125], v[6:9], v[146:149], v[122:125]
	v_addc_co_u32_e32 v161, vcc, 0, v155, vcc
	v_add_co_u32_e32 v182, vcc, s24, v154
	s_waitcnt vmcnt(0)
	v_mfma_f32_16x16x32_bf16 v[118:121], v[2:5], v[146:149], v[118:121]
	v_addc_co_u32_e32 v183, vcc, 0, v155, vcc
	s_waitcnt lgkmcnt(0)
	v_mfma_f32_16x16x32_bf16 v[114:117], v[10:13], v[150:153], v[114:117]
	v_lshl_add_u64 v[164:165], v[164:165], 0, s[64:65]
	v_mfma_f32_16x16x32_bf16 v[106:109], v[14:17], v[150:153], v[106:109]
	v_mfma_f32_16x16x32_bf16 v[102:105], v[6:9], v[150:153], v[102:105]
	s_nop 0
	v_mfma_f32_16x16x32_bf16 v[98:101], v[2:5], v[150:153], v[98:101]
	ds_read_b128 v[146:149], v0 offset:4096
	ds_read_b128 v[150:153], v0 offset:6144
	s_waitcnt lgkmcnt(1)
	v_mfma_f32_16x16x32_bf16 v[94:97], v[10:13], v[146:149], v[94:97]
	v_lshl_add_u64 v[166:167], v[166:167], 0, s[60:61]
	v_mfma_f32_16x16x32_bf16 v[86:89], v[14:17], v[146:149], v[86:89]
	v_mfma_f32_16x16x32_bf16 v[82:85], v[6:9], v[146:149], v[82:85]
	s_nop 0
	v_mfma_f32_16x16x32_bf16 v[78:81], v[2:5], v[146:149], v[78:81]
	s_nop 0
	s_waitcnt lgkmcnt(0)
	v_mfma_f32_16x16x32_bf16 v[74:77], v[10:13], v[150:153], v[74:77]
	v_mfma_f32_16x16x32_bf16 v[70:73], v[14:17], v[150:153], v[70:73]
	v_mfma_f32_16x16x32_bf16 v[62:65], v[6:9], v[150:153], v[62:65]
	v_mfma_f32_16x16x32_bf16 v[66:69], v[2:5], v[150:153], v[66:69]
	ds_read_b128 v[146:149], v0 offset:8192
	ds_read_b128 v[150:153], v0 offset:10240
	s_waitcnt lgkmcnt(1)
	v_mfma_f32_16x16x32_bf16 v[46:49], v[10:13], v[146:149], v[46:49]
	v_mfma_f32_16x16x32_bf16 v[50:53], v[14:17], v[146:149], v[50:53]
	v_mfma_f32_16x16x32_bf16 v[58:61], v[6:9], v[146:149], v[58:61]
	v_mfma_f32_16x16x32_bf16 v[54:57], v[2:5], v[146:149], v[54:57]
	s_waitcnt lgkmcnt(0)
	v_mfma_f32_16x16x32_bf16 v[26:29], v[10:13], v[150:153], v[26:29]
	v_mfma_f32_16x16x32_bf16 v[22:25], v[14:17], v[150:153], v[22:25]
	v_mfma_f32_16x16x32_bf16 v[18:21], v[6:9], v[150:153], v[18:21]
	v_mfma_f32_16x16x32_bf16 v[42:45], v[2:5], v[150:153], v[42:45]
	ds_read_b128 v[146:149], v0 offset:12288
	ds_read_b128 v[150:153], v0 offset:14336
	v_add_u32_e32 v0, s13, v171
	s_and_b32 s13, s1, 0x8000
	s_waitcnt lgkmcnt(1)
	v_mfma_f32_16x16x32_bf16 v[30:33], v[10:13], v[146:149], v[30:33]
	s_add_i32 s1, s1, 0x8000
	s_cmp_eq_u32 s1, 0x80000
	v_mfma_f32_16x16x32_bf16 v[38:41], v[14:17], v[146:149], v[38:41]
	v_mfma_f32_16x16x32_bf16 v[34:37], v[6:9], v[146:149], v[34:37]
	v_mfma_f32_16x16x32_bf16 v[142:145], v[2:5], v[146:149], v[142:145]
	s_setprio 0
	global_load_dwordx4 v[146:149], v[156:157], off offset:1024
	ds_read_b128 v[174:177], v0
	ds_read_b128 v[178:181], v0 offset:2048
	s_waitcnt lgkmcnt(2)
	v_mfma_f32_16x16x32_bf16 v[138:141], v[10:13], v[150:153], v[138:141]
	global_load_dwordx4 v[10:13], v[156:157], off offset:2048
	v_mfma_f32_16x16x32_bf16 v[134:137], v[14:17], v[150:153], v[134:137]
	v_mfma_f32_16x16x32_bf16 v[110:113], v[6:9], v[150:153], v[110:113]
	v_mfma_f32_16x16x32_bf16 v[90:93], v[2:5], v[150:153], v[90:93]
	global_load_dwordx4 v[150:153], v[158:159], off offset:1024
	global_load_dwordx4 v[14:17], v[158:159], off offset:2048
	global_load_dwordx4 v[154:157], v[160:161], off offset:1024
	global_load_dwordx4 v[6:9], v[160:161], off offset:2048
	s_nop 0
	global_load_dwordx4 v[158:161], v[182:183], off offset:1024
	global_load_dwordx4 v[2:5], v[182:183], off offset:2048
	v_lshrrev_b32_e32 v195, 6, v206
	v_lshl_add_u64 v[190:191], v[166:167], 0, s[28:29]
	v_lshrrev_b32_e32 v194, 3, v206
	v_readfirstlane_b32 s99, v195
	v_and_b32_e32 v194, 7, v194
	s_and_b32 s98, s1, 0x8000
	s_xor_b32 s98, s98, 0x8000
	v_lshlrev_b32_e32 v194, 4, v194
	s_lshl_b32 s99, s99, 10
	v_xor_b32_e32 v190, v194, v190
	s_add_u32 s98, s98, s99
	s_add_u32 s98, s98, 32
	s_mov_b32 s101, 0
	s_mov_b32 s100, 0x0
	v_lshl_add_u64 v[192:193], v[190:191], 0, s[100:101]
	s_mov_b32 m0, s98
	s_nop 0
	global_load_lds_dwordx4 v[192:193], off
	s_add_u32 s100, s54, 0x0
	v_lshl_add_u64 v[192:193], v[190:191], 0, s[100:101]
	s_add_u32 m0, s98, 0x1000
	s_nop 0
	global_load_lds_dwordx4 v[192:193], off
	s_add_u32 s100, s53, 0x0
	v_lshl_add_u64 v[192:193], v[190:191], 0, s[100:101]
	s_add_u32 m0, s98, 0x2000
	s_nop 0
	global_load_lds_dwordx4 v[192:193], off
	s_add_u32 s100, s52, 0x0
	v_lshl_add_u64 v[192:193], v[190:191], 0, s[100:101]
	s_add_u32 m0, s98, 0x3000
	s_nop 0
	global_load_lds_dwordx4 v[192:193], off
	s_add_u32 s100, s56, 0x0
	v_lshl_add_u64 v[192:193], v[190:191], 0, s[100:101]
	s_add_u32 m0, s98, 0x4000
	s_nop 0
	global_load_lds_dwordx4 v[192:193], off
	s_add_u32 s100, s57, 0x0
	v_lshl_add_u64 v[192:193], v[190:191], 0, s[100:101]
	s_add_u32 m0, s98, 0x5000
	s_nop 0
	global_load_lds_dwordx4 v[192:193], off
	s_add_u32 s100, s3, 0x0
	v_lshl_add_u64 v[192:193], v[190:191], 0, s[100:101]
	s_add_u32 m0, s98, 0x6000
	s_nop 0
	global_load_lds_dwordx4 v[192:193], off
	s_add_u32 s100, s19, 0x0
	v_lshl_add_u64 v[192:193], v[190:191], 0, s[100:101]
	s_add_u32 m0, s98, 0x7000
	s_nop 0
	global_load_lds_dwordx4 v[192:193], off
	s_setprio 1
	s_waitcnt vmcnt(15) lgkmcnt(1)
; #define MFMA16(a, b, c) __builtin_amdgcn_mfma_f32_16x16x32_bf16((a), (b), (c), 0, 0, 0)
; template <class Epi>
; DEVI void gemm_tile256b(const bf16_t* __restrict__ A, int lda, const bf16_t* __restrict__ Bt, int K,
;                         int m0, int n0, char* smem, Epi epi) {
;     ...
;   for (int kt = 0; kt < nk; ++kt) {
;     const char* base = smem + (kt & 1) * 32768;
;     const bool more = kt + 1 < nk;
;     if (more) {
; #pragma unroll
;       for (int i = 0; i < 8; ++i) ra[i] = *(const u32x4*)(ag + (size_t)(i * 32) * lda + (kt + 1) * 64);
;     }
; #pragma unroll
;     for (int i = 0; i < 4; ++i) b1[i] = *(const bf16x8*)(bp + ((size_t)i * kb32 + kt * 2 + 1) * 512);
;     {
;       bf16x8 af[8];
; #pragma unroll
;       for (int i = 0; i < 8; ++i) af[i] = *(const bf16x8*)(base + a_rd + i * 2048);
; #pragma unroll
;       for (int mi = 0; mi < 8; ++mi)
; #pragma unroll
;         for (int ni = 0; ni < 4; ++ni) acc[mi][ni] = MFMA16(b0[ni], af[mi], acc[mi][ni]);
;     }
;     if (more) {
; #pragma unroll
;       for (int i = 0; i < 4; ++i) b0[i] = *(const bf16x8*)(bp + ((size_t)i * kb32 + kt * 2 + 2) * 512);
;     }
;     {
;       bf16x8 af[8];
; #pragma unroll
;       for (int i = 0; i < 8; ++i) af[i] = *(const bf16x8*)(base + ((a_rd + i * 2048) ^ 64));
; #pragma unroll
;       for (int mi = 0; mi < 8; ++mi)
; #pragma unroll
;         for (int ni = 0; ni < 4; ++ni) acc[mi][ni] = MFMA16(b1[ni], af[mi], acc[mi][ni]);
;     }
;     if (more) {
;       char* nb = smem + ((kt + 1) & 1) * 32768 + lds_w;
; #pragma unroll
;       for (int i = 0; i < 8; ++i) *(u32x4*)(nb + i * 4096) = ra[i];
;     }
;     __syncthreads();
;   }
	v_mfma_f32_16x16x32_bf16 v[130:133], v[146:149], v[174:177], v[130:133]
	s_waitcnt vmcnt(13)
	v_mfma_f32_16x16x32_bf16 v[126:129], v[150:153], v[174:177], v[126:129]
	s_waitcnt vmcnt(11)
	v_mfma_f32_16x16x32_bf16 v[122:125], v[154:157], v[174:177], v[122:125]
	s_waitcnt vmcnt(9)
	v_mfma_f32_16x16x32_bf16 v[118:121], v[158:161], v[174:177], v[118:121]
	s_waitcnt lgkmcnt(0)
	v_mfma_f32_16x16x32_bf16 v[114:117], v[146:149], v[178:181], v[114:117]
	v_mfma_f32_16x16x32_bf16 v[106:109], v[150:153], v[178:181], v[106:109]
	v_mfma_f32_16x16x32_bf16 v[102:105], v[154:157], v[178:181], v[102:105]
	v_mfma_f32_16x16x32_bf16 v[98:101], v[158:161], v[178:181], v[98:101]
	ds_read_b128 v[174:177], v0 offset:4096
	ds_read_b128 v[178:181], v0 offset:6144
	s_waitcnt lgkmcnt(1)
	v_mfma_f32_16x16x32_bf16 v[94:97], v[146:149], v[174:177], v[94:97]
	v_mfma_f32_16x16x32_bf16 v[86:89], v[150:153], v[174:177], v[86:89]
	v_mfma_f32_16x16x32_bf16 v[82:85], v[154:157], v[174:177], v[82:85]
	v_mfma_f32_16x16x32_bf16 v[78:81], v[158:161], v[174:177], v[78:81]
	s_waitcnt lgkmcnt(0)
	v_mfma_f32_16x16x32_bf16 v[74:77], v[146:149], v[178:181], v[74:77]
	v_mfma_f32_16x16x32_bf16 v[70:73], v[150:153], v[178:181], v[70:73]
	v_mfma_f32_16x16x32_bf16 v[62:65], v[154:157], v[178:181], v[62:65]
	v_mfma_f32_16x16x32_bf16 v[66:69], v[158:161], v[178:181], v[66:69]
	ds_read_b128 v[178:181], v0 offset:8192
	ds_read_b128 v[182:185], v0 offset:10240
	s_waitcnt lgkmcnt(1)
	v_mfma_f32_16x16x32_bf16 v[46:49], v[146:149], v[178:181], v[46:49]
	v_mfma_f32_16x16x32_bf16 v[50:53], v[150:153], v[178:181], v[50:53]
	v_mfma_f32_16x16x32_bf16 v[58:61], v[154:157], v[178:181], v[58:61]
	v_mfma_f32_16x16x32_bf16 v[54:57], v[158:161], v[178:181], v[54:57]
	s_waitcnt lgkmcnt(0)
	v_mfma_f32_16x16x32_bf16 v[26:29], v[146:149], v[182:185], v[26:29]
	v_mfma_f32_16x16x32_bf16 v[22:25], v[150:153], v[182:185], v[22:25]
	v_mfma_f32_16x16x32_bf16 v[18:21], v[154:157], v[182:185], v[18:21]
	v_mfma_f32_16x16x32_bf16 v[42:45], v[158:161], v[182:185], v[42:45]
	ds_read_b128 v[178:181], v0 offset:12288
	ds_read_b128 v[182:185], v0 offset:14336
	s_nop 0
	s_nop 0
	s_nop 0
	s_nop 0
	s_nop 0
	s_waitcnt lgkmcnt(1)
	v_mfma_f32_16x16x32_bf16 v[30:33], v[146:149], v[178:181], v[30:33]
	v_mfma_f32_16x16x32_bf16 v[38:41], v[150:153], v[178:181], v[38:41]
	v_mfma_f32_16x16x32_bf16 v[34:37], v[154:157], v[178:181], v[34:37]
	s_setprio 0
	s_waitcnt vmcnt(0) lgkmcnt(0)
	s_barrier
	v_mfma_f32_16x16x32_bf16 v[142:145], v[158:161], v[178:181], v[142:145]
	v_mfma_f32_16x16x32_bf16 v[138:141], v[146:149], v[182:185], v[138:141]
	v_mfma_f32_16x16x32_bf16 v[134:137], v[150:153], v[182:185], v[134:137]
	v_mfma_f32_16x16x32_bf16 v[110:113], v[154:157], v[182:185], v[110:113]
	v_mfma_f32_16x16x32_bf16 v[90:93], v[158:161], v[182:185], v[90:93]
	s_cmp_eq_u32 s1, 0x80000
	s_cbranch_scc0 .LBB0_421
	s_setprio 0
	v_add_u32_e32 v0, 32, v173
	ds_read_b128 v[146:149], v0 offset:32768
	s_movk_i32 s1, 0x7000
	s_movk_i32 s13, 0x4000
	s_waitcnt lgkmcnt(0)
	v_mfma_f32_16x16x32_bf16 v[130:133], v[10:13], v[146:149], v[130:133]
	v_mfma_f32_16x16x32_bf16 v[150:153], v[14:17], v[146:149], v[126:129]
	v_mfma_f32_16x16x32_bf16 v[154:157], v[6:9], v[146:149], v[122:125]
	v_mfma_f32_16x16x32_bf16 v[146:149], v[2:5], v[146:149], v[118:121]
	s_nop 2
	ds_read_b128 v[118:121], v0 offset:34816
	s_waitcnt lgkmcnt(0)
	v_mfma_f32_16x16x32_bf16 v[158:161], v[10:13], v[118:121], v[114:117]
	s_nop 2
	ds_read_b128 v[114:117], v0 offset:36864
	s_waitcnt lgkmcnt(0)
	v_mfma_f32_16x16x32_bf16 v[94:97], v[10:13], v[114:117], v[94:97]
	v_mfma_f32_16x16x32_bf16 v[86:89], v[14:17], v[114:117], v[86:89]
	v_mfma_f32_16x16x32_bf16 v[82:85], v[6:9], v[114:117], v[82:85]
	v_mfma_f32_16x16x32_bf16 v[78:81], v[2:5], v[114:117], v[78:81]
	ds_read_b128 v[114:117], v0 offset:38912
	s_waitcnt lgkmcnt(0)
	v_mfma_f32_16x16x32_bf16 v[74:77], v[10:13], v[114:117], v[74:77]
	v_mfma_f32_16x16x32_bf16 v[70:73], v[14:17], v[114:117], v[70:73]
	v_mfma_f32_16x16x32_bf16 v[62:65], v[6:9], v[114:117], v[62:65]
	v_mfma_f32_16x16x32_bf16 v[66:69], v[2:5], v[114:117], v[66:69]
	ds_read_b128 v[114:117], v0 offset:40960
	s_waitcnt lgkmcnt(0)
	v_mfma_f32_16x16x32_bf16 v[172:175], v[2:5], v[114:117], v[54:57]
	s_nop 2
	ds_read_b128 v[54:57], v0 offset:43008
	s_waitcnt lgkmcnt(0)
	v_mfma_f32_16x16x32_bf16 v[176:179], v[2:5], v[54:57], v[42:45]
	s_nop 2
	ds_read_b128 v[42:45], v0 offset:45056
	s_waitcnt lgkmcnt(0)
	v_mfma_f32_16x16x32_bf16 v[190:193], v[6:9], v[42:45], v[34:37]
	s_nop 2
	ds_read_b128 v[34:37], v0 offset:47104
	v_add_u32_e32 v0, 32, v171
	v_mfma_f32_16x16x32_bf16 v[106:109], v[14:17], v[118:121], v[106:109]
	v_mfma_f32_16x16x32_bf16 v[50:53], v[14:17], v[114:117], v[50:53]
	v_mfma_f32_16x16x32_bf16 v[22:25], v[14:17], v[54:57], v[22:25]
	v_mfma_f32_16x16x32_bf16 v[180:183], v[14:17], v[42:45], v[38:41]
	s_waitcnt lgkmcnt(0)
; template <class Epi>
; DEVI void gemm_tile256b(const bf16_t* __restrict__ A, int lda, const bf16_t* __restrict__ Bt, int K,
;                         int m0, int n0, char* smem, Epi epi) {
;     ...
;     for (int i = 0; i < 4; ++i) b1[i] = *(const bf16x8*)(bp + ((size_t)i * kb32 + kt * 2 + 1) * 512);
;     {
;       bf16x8 af[8];
; #pragma unroll
;       for (int i = 0; i < 8; ++i) af[i] = *(const bf16x8*)(base + a_rd + i * 2048);
; #pragma unroll
;       for (int mi = 0; mi < 8; ++mi)
; #pragma unroll
;         for (int ni = 0; ni < 4; ++ni) acc[mi][ni] = MFMA16(b0[ni], af[mi], acc[mi][ni]);
;     }
;     if (more) {
; #pragma unroll
;       for (int i = 0; i < 4; ++i) b0[i] = *(const bf16x8*)(bp + ((size_t)i * kb32 + kt * 2 + 2) * 512);
;     }
;     {
;       bf16x8 af[8];
; #pragma unroll
;       for (int i = 0; i < 8; ++i) af[i] = *(const bf16x8*)(base + ((a_rd + i * 2048) ^ 64));
; #pragma unroll
;       for (int mi = 0; mi < 8; ++mi)
; #pragma unroll
;         for (int ni = 0; ni < 4; ++ni) acc[mi][ni] = MFMA16(b1[ni], af[mi], acc[mi][ni]);
;     }
;     if (more) {
;       char* nb = smem + ((kt + 1) & 1) * 32768 + lds_w;
; #pragma unroll
;       for (int i = 0; i < 8; ++i) *(u32x4*)(nb + i * 4096) = ra[i];
;     }
;     __syncthreads();
;   }
; #pragma unroll
;   for (int mi = 0; mi < 8; ++mi)
; #pragma unroll
;     for (int ni = 0; ni < 4; ++ni)
;       epi(m0 + wm * 128 + mi * 16 + l15, n0 + wn * 64 + ni * 16 + quad * 4, acc[mi][ni]);
;   DEVI void operator()(int m, int n, f32x4 v) const {
;     if (n < 1024) {
;       if (m >= L) return;
;       const bool isq = n < 512;
;       const int nn = n & 511;
;       const int h = nn >> 7, c = (nn >> 6) & 1, d = nn & 63;
;       const float s = isq ? (0.125f * LOG2E) : 1.0f;
;       bf16_t* dst = isq ? r0 + R0_Q + ((size_t)(h * 2 + c) * LR + m) * 64 + d
;                         : r0 + R0_K + (size_t)(h * 2 + c) * LR * 64 + wfm(m, d, 64);
;       *(u32x2*)dst = u32x2{pack2(v[0] * s, v[1] * s), pack2(v[2] * s, v[3] * s)};
;     } else if (n < 1536) {
;       const int nn = n - 1024;
;       bf16_t* dst = r0 + R0_VT + (size_t)nn * LR + m;
;       const bool ok = m < L;
; #pragma unroll
;       for (int i = 0; i < 4; ++i) {
;         dst[(size_t)i * LR] = ok ? f2bf(v[i]) : (bf16_t)0;
;         if (m >= 16384) {
;           dst[(size_t)i * LR + 16] = 0;
;           dst[(size_t)i * LR + 32] = 0;
	v_mfma_f32_16x16x32_bf16 v[134:137], v[14:17], v[34:37], v[134:137]
	v_add_co_u32_e32 v14, vcc, s1, v162
	s_mov_b32 s1, 0xf000
	s_nop 0
	v_addc_co_u32_e32 v15, vcc, 0, v163, vcc
	v_add_co_u32_e32 v38, vcc, s1, v162
	v_mfma_f32_16x16x32_bf16 v[46:49], v[10:13], v[114:117], v[46:49]
	s_nop 0
	v_addc_co_u32_e32 v39, vcc, 0, v163, vcc
	global_load_dwordx4 v[14:17], v[14:15], off offset:3072
	v_mfma_f32_16x16x32_bf16 v[26:29], v[10:13], v[54:57], v[26:29]
	s_mov_b32 s1, 0x17000
	v_mfma_f32_16x16x32_bf16 v[30:33], v[10:13], v[42:45], v[30:33]
	v_mfma_f32_16x16x32_bf16 v[10:13], v[10:13], v[34:37], v[138:141]
	s_nop 2
	global_load_dwordx4 v[138:141], v[38:39], off offset:3072
	v_mfma_f32_16x16x32_bf16 v[102:105], v[6:9], v[118:121], v[102:105]
	v_add_co_u32_e32 v38, vcc, s1, v162
	s_mov_b32 s1, 0x1f000
	v_mfma_f32_16x16x32_bf16 v[98:101], v[2:5], v[118:121], v[98:101]
	v_addc_co_u32_e32 v39, vcc, 0, v163, vcc
	global_load_dwordx4 v[198:201], v[38:39], off offset:3072
	v_mfma_f32_16x16x32_bf16 v[164:167], v[6:9], v[114:117], v[58:61]
	v_add_co_u32_e32 v38, vcc, s1, v162
	v_mfma_f32_16x16x32_bf16 v[18:21], v[6:9], v[54:57], v[18:21]
	s_nop 0
	v_addc_co_u32_e32 v39, vcc, 0, v163, vcc
	v_mfma_f32_16x16x32_bf16 v[194:197], v[2:5], v[42:45], v[142:145]
	v_mfma_f32_16x16x32_bf16 v[6:9], v[6:9], v[34:37], v[110:113]
	s_nop 1
	v_and_b32_e32 v142, 15, v170
	v_lshlrev_b32_e32 v143, 2, v169
	v_mfma_f32_16x16x32_bf16 v[2:5], v[2:5], v[34:37], v[90:93]
	ds_read_b128 v[34:37], v0 offset:32768
	s_waitcnt vmcnt(1) lgkmcnt(0)
	v_mfma_f32_16x16x32_bf16 v[122:125], v[138:141], v[34:37], v[150:153]
	s_nop 2
	global_load_dwordx4 v[150:153], v[38:39], off offset:3072
	v_mfma_f32_16x16x32_bf16 v[126:129], v[14:17], v[34:37], v[130:133]
	s_waitcnt vmcnt(1)
	v_mfma_f32_16x16x32_bf16 v[118:121], v[198:201], v[34:37], v[154:157]
	s_nop 0
	v_or_b32_e32 v130, v143, v168
	s_waitcnt vmcnt(0)
	v_mfma_f32_16x16x32_bf16 v[114:117], v[150:153], v[34:37], v[146:149]
	ds_read_b128 v[34:37], v0 offset:34816
	s_nop 1
	ds_read_b128 v[144:147], v0 offset:47104
	s_waitcnt lgkmcnt(1)
	v_mfma_f32_16x16x32_bf16 v[110:113], v[14:17], v[34:37], v[158:161]
	v_mfma_f32_16x16x32_bf16 v[106:109], v[138:141], v[34:37], v[106:109]
	v_mfma_f32_16x16x32_bf16 v[102:105], v[198:201], v[34:37], v[102:105]
	v_mfma_f32_16x16x32_bf16 v[98:101], v[150:153], v[34:37], v[98:101]
	ds_read_b128 v[34:37], v0 offset:36864
	s_waitcnt lgkmcnt(0)
	v_mfma_f32_16x16x32_bf16 v[94:97], v[14:17], v[34:37], v[94:97]
	v_mfma_f32_16x16x32_bf16 v[90:93], v[138:141], v[34:37], v[86:89]
	v_mfma_f32_16x16x32_bf16 v[86:89], v[198:201], v[34:37], v[82:85]
	v_mfma_f32_16x16x32_bf16 v[82:85], v[150:153], v[34:37], v[78:81]
	ds_read_b128 v[34:37], v0 offset:38912
	s_waitcnt lgkmcnt(0)
	v_mfma_f32_16x16x32_bf16 v[78:81], v[14:17], v[34:37], v[74:77]
	v_mfma_f32_16x16x32_bf16 v[74:77], v[138:141], v[34:37], v[70:73]
	v_mfma_f32_16x16x32_bf16 v[70:73], v[198:201], v[34:37], v[62:65]
	v_mfma_f32_16x16x32_bf16 v[66:69], v[150:153], v[34:37], v[66:69]
	ds_read_b128 v[34:37], v0 offset:40960
	s_waitcnt lgkmcnt(0)
	v_mfma_f32_16x16x32_bf16 v[62:65], v[14:17], v[34:37], v[46:49]
	v_mfma_f32_16x16x32_bf16 v[58:61], v[138:141], v[34:37], v[50:53]
	v_mfma_f32_16x16x32_bf16 v[54:57], v[198:201], v[34:37], v[164:167]
	v_mfma_f32_16x16x32_bf16 v[50:53], v[150:153], v[34:37], v[172:175]
	ds_read_b128 v[34:37], v0 offset:43008
	s_waitcnt lgkmcnt(0)
	v_mfma_f32_16x16x32_bf16 v[38:41], v[198:201], v[34:37], v[18:21]
	s_nop 2
	ds_read_b128 v[18:21], v0 offset:45056
	v_and_b32_e32 v0, 0xffffff80, v170
	v_add_u32_e32 v0, s0, v0
	v_mfma_f32_16x16x32_bf16 v[46:49], v[14:17], v[34:37], v[26:29]
	v_or_b32_e32 v132, v0, v142
	v_ashrrev_i32_e32 v133, 31, v132
	s_movk_i32 s0, 0x4010
	v_mfma_f32_16x16x32_bf16 v[42:45], v[138:141], v[34:37], v[22:25]
	v_cmp_gt_i32_e64 s[46:47], s13, v132
	s_movk_i32 s13, 0x3ff
	v_cmp_gt_i32_e64 s[0:1], s0, v132
	v_mfma_f32_16x16x32_bf16 v[34:37], v[150:153], v[34:37], v[176:179]
	v_cmp_lt_i32_e64 s[42:43], s13, v130
	s_waitcnt lgkmcnt(0)
	s_barrier
	v_mfma_f32_16x16x32_bf16 v[30:33], v[14:17], v[18:21], v[30:33]
	v_mfma_f32_16x16x32_bf16 v[26:29], v[138:141], v[18:21], v[180:183]
	v_mfma_f32_16x16x32_bf16 v[22:25], v[198:201], v[18:21], v[190:193]
	v_mfma_f32_16x16x32_bf16 v[18:21], v[150:153], v[18:21], v[194:197]
	v_mfma_f32_16x16x32_bf16 v[14:17], v[14:17], v[144:147], v[10:13]
	v_mfma_f32_16x16x32_bf16 v[10:13], v[138:141], v[144:147], v[134:137]
	v_mfma_f32_16x16x32_bf16 v[6:9], v[198:201], v[144:147], v[6:9]
	s_nop 1
	v_lshlrev_b64 v[134:135], 10, v[132:133]
	v_lshl_add_u64 v[136:137], s[30:31], 0, v[134:135]
	v_lshl_add_u64 v[134:135], v[132:133], 1, s[6:7]
	v_mfma_f32_16x16x32_bf16 v[2:5], v[150:153], v[144:147], v[2:5]
	s_and_saveexec_b64 s[16:17], s[42:43]
	s_xor_b64 s[16:17], exec, s[16:17]
	s_cbranch_execz .LBB0_437
	s_cmpk_gt_u32 s62, 0x5ff
	s_mov_b64 s[36:37], -1
	s_cbranch_scc0 .LBB0_427
	s_and_saveexec_b64 s[36:37], s[0:1]
	s_cbranch_execz .LBB0_426
	v_mov_b32_e32 v131, v1
	v_lshl_add_u64 v[138:139], v[130:131], 1, v[136:137]
	v_add_co_u32_e32 v138, vcc, 0x305f000, v138
	v_cvt_pk_bf16_f32 v140, v126, v127
	v_cvt_pk_bf16_f32 v141, v128, v129
	v_addc_co_u32_e32 v139, vcc, 0, v139, vcc
	global_store_dwordx2 v[138:139], v[140:141], off offset:1024

; #define MFMA16(a, b, c) __builtin_amdgcn_mfma_f32_16x16x32_bf16((a), (b), (c), 0, 0, 0)
; template <class Epi>
; DEVI void gemm_tile256b(const bf16_t* __restrict__ A, int lda, const bf16_t* __restrict__ Bt, int K,
;                         int m0, int n0, char* smem, Epi epi) {
;     ...
;   for (int kt = 0; kt < nk; ++kt) {
;     const char* base = smem + (kt & 1) * 32768;
;     const bool more = kt + 1 < nk;
;     if (more) {
; #pragma unroll
;       for (int i = 0; i < 8; ++i) ra[i] = *(const u32x4*)(ag + (size_t)(i * 32) * lda + (kt + 1) * 64);
;     }
; #pragma unroll
;     for (int i = 0; i < 4; ++i) b1[i] = *(const bf16x8*)(bp + ((size_t)i * kb32 + kt * 2 + 1) * 512);
;     {
;       bf16x8 af[8];
; #pragma unroll
;       for (int i = 0; i < 8; ++i) af[i] = *(const bf16x8*)(base + a_rd + i * 2048);
; #pragma unroll
;       for (int mi = 0; mi < 8; ++mi)
; #pragma unroll
;         for (int ni = 0; ni < 4; ++ni) acc[mi][ni] = MFMA16(b0[ni], af[mi], acc[mi][ni]);
;     }
;     if (more) {
; #pragma unroll
;       for (int i = 0; i < 4; ++i) b0[i] = *(const bf16x8*)(bp + ((size_t)i * kb32 + kt * 2 + 2) * 512);
;     }
;     {
;       bf16x8 af[8];
; #pragma unroll
;       for (int i = 0; i < 8; ++i) af[i] = *(const bf16x8*)(base + ((a_rd + i * 2048) ^ 64));
; #pragma unroll
;       for (int mi = 0; mi < 8; ++mi)
; #pragma unroll
;         for (int ni = 0; ni < 4; ++ni) acc[mi][ni] = MFMA16(b1[ni], af[mi], acc[mi][ni]);
;     }
;     if (more) {
;       char* nb = smem + ((kt + 1) & 1) * 32768 + lds_w;
; #pragma unroll
;       for (int i = 0; i < 8; ++i) *(u32x4*)(nb + i * 4096) = ra[i];
;     }
;     __syncthreads();
;   }
.LBB0_1367:
	s_setprio 1
	s_add_i32 s10, s1, 0xffff8000
	s_and_b32 s10, s10, 0x8000
	s_add_i32 s10, s10, 32
	v_add_u32_e32 v0, s10, v173
	ds_read_b128 v[146:149], v0
	ds_read_b128 v[150:153], v0 offset:2048
	v_lshl_add_u64 v[154:155], v[164:165], 0, s[28:29]
	v_add_co_u32_e32 v156, vcc, s11, v154
	s_waitcnt vmcnt(3) lgkmcnt(1)
	v_mfma_f32_16x16x32_bf16 v[130:133], v[2:5], v[146:149], v[130:133]
	v_addc_co_u32_e32 v157, vcc, 0, v155, vcc
	v_add_co_u32_e32 v158, vcc, s13, v154
	s_waitcnt vmcnt(2)
	v_mfma_f32_16x16x32_bf16 v[126:129], v[14:17], v[146:149], v[126:129]
	v_addc_co_u32_e32 v159, vcc, 0, v155, vcc
	v_add_co_u32_e32 v160, vcc, s16, v154
	s_waitcnt vmcnt(1)
	v_mfma_f32_16x16x32_bf16 v[122:125], v[10:13], v[146:149], v[122:125]
	v_addc_co_u32_e32 v161, vcc, 0, v155, vcc
	v_add_co_u32_e32 v182, vcc, s17, v154
	s_waitcnt vmcnt(0)
	v_mfma_f32_16x16x32_bf16 v[118:121], v[6:9], v[146:149], v[118:121]
	v_addc_co_u32_e32 v183, vcc, 0, v155, vcc
	s_waitcnt lgkmcnt(0)
	v_mfma_f32_16x16x32_bf16 v[114:117], v[2:5], v[150:153], v[114:117]
	v_lshl_add_u64 v[164:165], v[164:165], 0, s[64:65]
	v_mfma_f32_16x16x32_bf16 v[106:109], v[14:17], v[150:153], v[106:109]
	v_mfma_f32_16x16x32_bf16 v[102:105], v[10:13], v[150:153], v[102:105]
	s_nop 0
	v_mfma_f32_16x16x32_bf16 v[98:101], v[6:9], v[150:153], v[98:101]
	ds_read_b128 v[146:149], v0 offset:4096
	ds_read_b128 v[150:153], v0 offset:6144
	s_waitcnt lgkmcnt(1)
	v_mfma_f32_16x16x32_bf16 v[94:97], v[2:5], v[146:149], v[94:97]
	v_lshl_add_u64 v[166:167], v[166:167], 0, s[60:61]
	v_mfma_f32_16x16x32_bf16 v[86:89], v[14:17], v[146:149], v[86:89]
	v_mfma_f32_16x16x32_bf16 v[82:85], v[10:13], v[146:149], v[82:85]
	s_nop 0
	v_mfma_f32_16x16x32_bf16 v[78:81], v[6:9], v[146:149], v[78:81]
	s_nop 0
	s_waitcnt lgkmcnt(0)
	v_mfma_f32_16x16x32_bf16 v[74:77], v[2:5], v[150:153], v[74:77]
	v_mfma_f32_16x16x32_bf16 v[70:73], v[14:17], v[150:153], v[70:73]
	v_mfma_f32_16x16x32_bf16 v[62:65], v[10:13], v[150:153], v[62:65]
	v_mfma_f32_16x16x32_bf16 v[66:69], v[6:9], v[150:153], v[66:69]
	ds_read_b128 v[146:149], v0 offset:8192
	ds_read_b128 v[150:153], v0 offset:10240
	s_waitcnt lgkmcnt(1)
	v_mfma_f32_16x16x32_bf16 v[46:49], v[2:5], v[146:149], v[46:49]
	v_mfma_f32_16x16x32_bf16 v[50:53], v[14:17], v[146:149], v[50:53]
	v_mfma_f32_16x16x32_bf16 v[58:61], v[10:13], v[146:149], v[58:61]
	v_mfma_f32_16x16x32_bf16 v[54:57], v[6:9], v[146:149], v[54:57]
	s_waitcnt lgkmcnt(0)
	v_mfma_f32_16x16x32_bf16 v[26:29], v[2:5], v[150:153], v[26:29]
	v_mfma_f32_16x16x32_bf16 v[22:25], v[14:17], v[150:153], v[22:25]
	v_mfma_f32_16x16x32_bf16 v[18:21], v[10:13], v[150:153], v[18:21]
	v_mfma_f32_16x16x32_bf16 v[42:45], v[6:9], v[150:153], v[42:45]
	ds_read_b128 v[146:149], v0 offset:12288
	ds_read_b128 v[150:153], v0 offset:14336
	v_add_u32_e32 v0, s10, v171
	s_and_b32 s10, s1, 0x8000
	s_waitcnt lgkmcnt(1)
	v_mfma_f32_16x16x32_bf16 v[30:33], v[2:5], v[146:149], v[30:33]
	s_add_i32 s1, s1, 0x8000
	s_cmp_eq_u32 s1, 0x80000
	v_mfma_f32_16x16x32_bf16 v[38:41], v[14:17], v[146:149], v[38:41]
	v_mfma_f32_16x16x32_bf16 v[34:37], v[10:13], v[146:149], v[34:37]
	v_mfma_f32_16x16x32_bf16 v[142:145], v[6:9], v[146:149], v[142:145]
	s_setprio 0
	global_load_dwordx4 v[146:149], v[156:157], off offset:1024
	ds_read_b128 v[174:177], v0
	ds_read_b128 v[178:181], v0 offset:2048
	s_waitcnt lgkmcnt(2)
	v_mfma_f32_16x16x32_bf16 v[138:141], v[2:5], v[150:153], v[138:141]
	global_load_dwordx4 v[2:5], v[156:157], off offset:2048
	v_mfma_f32_16x16x32_bf16 v[134:137], v[14:17], v[150:153], v[134:137]
	v_mfma_f32_16x16x32_bf16 v[110:113], v[10:13], v[150:153], v[110:113]
	v_mfma_f32_16x16x32_bf16 v[90:93], v[6:9], v[150:153], v[90:93]
	global_load_dwordx4 v[150:153], v[158:159], off offset:1024
	global_load_dwordx4 v[14:17], v[158:159], off offset:2048
	global_load_dwordx4 v[154:157], v[160:161], off offset:1024
	global_load_dwordx4 v[10:13], v[160:161], off offset:2048
	s_nop 0
	global_load_dwordx4 v[158:161], v[182:183], off offset:1024
	global_load_dwordx4 v[6:9], v[182:183], off offset:2048
	v_lshrrev_b32_e32 v195, 6, v206
	v_lshl_add_u64 v[190:191], v[166:167], 0, s[28:29]
	v_lshrrev_b32_e32 v194, 3, v206
	v_readfirstlane_b32 s99, v195
	v_and_b32_e32 v194, 7, v194
	s_and_b32 s98, s1, 0x8000
	s_xor_b32 s98, s98, 0x8000
	v_lshlrev_b32_e32 v194, 4, v194
	s_lshl_b32 s99, s99, 10
	v_xor_b32_e32 v190, v194, v190
	s_add_u32 s98, s98, s99
	s_add_u32 s98, s98, 32
	s_mov_b32 s101, 0
	s_mov_b32 s100, 0x0
	v_lshl_add_u64 v[192:193], v[190:191], 0, s[100:101]
	s_mov_b32 m0, s98
	s_nop 0
	global_load_lds_dwordx4 v[192:193], off
	s_add_u32 s100, s54, 0x0
	v_lshl_add_u64 v[192:193], v[190:191], 0, s[100:101]
	s_add_u32 m0, s98, 0x1000
	s_nop 0
	global_load_lds_dwordx4 v[192:193], off
	s_add_u32 s100, s53, 0x0
	v_lshl_add_u64 v[192:193], v[190:191], 0, s[100:101]
	s_add_u32 m0, s98, 0x2000
	s_nop 0
	global_load_lds_dwordx4 v[192:193], off
	s_add_u32 s100, s52, 0x0
	v_lshl_add_u64 v[192:193], v[190:191], 0, s[100:101]
	s_add_u32 m0, s98, 0x3000
	s_nop 0
	global_load_lds_dwordx4 v[192:193], off
	s_add_u32 s100, s56, 0x0
	v_lshl_add_u64 v[192:193], v[190:191], 0, s[100:101]
	s_add_u32 m0, s98, 0x4000
	s_nop 0
	global_load_lds_dwordx4 v[192:193], off
	s_add_u32 s100, s57, 0x0
	v_lshl_add_u64 v[192:193], v[190:191], 0, s[100:101]
	s_add_u32 m0, s98, 0x5000
	s_nop 0
	global_load_lds_dwordx4 v[192:193], off
	s_add_u32 s100, s3, 0x0
	v_lshl_add_u64 v[192:193], v[190:191], 0, s[100:101]
	s_add_u32 m0, s98, 0x6000
	s_nop 0
	global_load_lds_dwordx4 v[192:193], off
	s_add_u32 s100, s19, 0x0
	v_lshl_add_u64 v[192:193], v[190:191], 0, s[100:101]
	s_add_u32 m0, s98, 0x7000
	s_nop 0
	global_load_lds_dwordx4 v[192:193], off
	s_setprio 1
	s_waitcnt vmcnt(15) lgkmcnt(1)
; #define MFMA16(a, b, c) __builtin_amdgcn_mfma_f32_16x16x32_bf16((a), (b), (c), 0, 0, 0)
; template <class Epi>
; DEVI void gemm_tile256b(const bf16_t* __restrict__ A, int lda, const bf16_t* __restrict__ Bt, int K,
;                         int m0, int n0, char* smem, Epi epi) {
;     ...
;   for (int kt = 0; kt < nk; ++kt) {
;     const char* base = smem + (kt & 1) * 32768;
;     const bool more = kt + 1 < nk;
;     if (more) {
; #pragma unroll
;       for (int i = 0; i < 8; ++i) ra[i] = *(const u32x4*)(ag + (size_t)(i * 32) * lda + (kt + 1) * 64);
;     }
; #pragma unroll
;     for (int i = 0; i < 4; ++i) b1[i] = *(const bf16x8*)(bp + ((size_t)i * kb32 + kt * 2 + 1) * 512);
;     {
;       bf16x8 af[8];
; #pragma unroll
;       for (int i = 0; i < 8; ++i) af[i] = *(const bf16x8*)(base + a_rd + i * 2048);
; #pragma unroll
;       for (int mi = 0; mi < 8; ++mi)
; #pragma unroll
;         for (int ni = 0; ni < 4; ++ni) acc[mi][ni] = MFMA16(b0[ni], af[mi], acc[mi][ni]);
;     }
;     if (more) {
; #pragma unroll
;       for (int i = 0; i < 4; ++i) b0[i] = *(const bf16x8*)(bp + ((size_t)i * kb32 + kt * 2 + 2) * 512);
;     }
;     {
;       bf16x8 af[8];
; #pragma unroll
;       for (int i = 0; i < 8; ++i) af[i] = *(const bf16x8*)(base + ((a_rd + i * 2048) ^ 64));
; #pragma unroll
;       for (int mi = 0; mi < 8; ++mi)
; #pragma unroll
;         for (int ni = 0; ni < 4; ++ni) acc[mi][ni] = MFMA16(b1[ni], af[mi], acc[mi][ni]);
;     }
;     if (more) {
;       char* nb = smem + ((kt + 1) & 1) * 32768 + lds_w;
; #pragma unroll
;       for (int i = 0; i < 8; ++i) *(u32x4*)(nb + i * 4096) = ra[i];
;     }
;     __syncthreads();
;   }
	v_mfma_f32_16x16x32_bf16 v[130:133], v[146:149], v[174:177], v[130:133]
	s_waitcnt vmcnt(13)
	v_mfma_f32_16x16x32_bf16 v[126:129], v[150:153], v[174:177], v[126:129]
	s_waitcnt vmcnt(11)
	v_mfma_f32_16x16x32_bf16 v[122:125], v[154:157], v[174:177], v[122:125]
	s_waitcnt vmcnt(9)
	v_mfma_f32_16x16x32_bf16 v[118:121], v[158:161], v[174:177], v[118:121]
	s_waitcnt lgkmcnt(0)
	v_mfma_f32_16x16x32_bf16 v[114:117], v[146:149], v[178:181], v[114:117]
	v_mfma_f32_16x16x32_bf16 v[106:109], v[150:153], v[178:181], v[106:109]
	v_mfma_f32_16x16x32_bf16 v[102:105], v[154:157], v[178:181], v[102:105]
	v_mfma_f32_16x16x32_bf16 v[98:101], v[158:161], v[178:181], v[98:101]
	ds_read_b128 v[174:177], v0 offset:4096
	ds_read_b128 v[178:181], v0 offset:6144
	s_waitcnt lgkmcnt(1)
	v_mfma_f32_16x16x32_bf16 v[94:97], v[146:149], v[174:177], v[94:97]
	v_mfma_f32_16x16x32_bf16 v[86:89], v[150:153], v[174:177], v[86:89]
	v_mfma_f32_16x16x32_bf16 v[82:85], v[154:157], v[174:177], v[82:85]
	v_mfma_f32_16x16x32_bf16 v[78:81], v[158:161], v[174:177], v[78:81]
	s_waitcnt lgkmcnt(0)
	v_mfma_f32_16x16x32_bf16 v[74:77], v[146:149], v[178:181], v[74:77]
	v_mfma_f32_16x16x32_bf16 v[70:73], v[150:153], v[178:181], v[70:73]
	v_mfma_f32_16x16x32_bf16 v[62:65], v[154:157], v[178:181], v[62:65]
	v_mfma_f32_16x16x32_bf16 v[66:69], v[158:161], v[178:181], v[66:69]
	ds_read_b128 v[178:181], v0 offset:8192
	ds_read_b128 v[182:185], v0 offset:10240
	s_waitcnt lgkmcnt(1)
	v_mfma_f32_16x16x32_bf16 v[46:49], v[146:149], v[178:181], v[46:49]
	v_mfma_f32_16x16x32_bf16 v[50:53], v[150:153], v[178:181], v[50:53]
	v_mfma_f32_16x16x32_bf16 v[58:61], v[154:157], v[178:181], v[58:61]
	v_mfma_f32_16x16x32_bf16 v[54:57], v[158:161], v[178:181], v[54:57]
	s_waitcnt lgkmcnt(0)
	v_mfma_f32_16x16x32_bf16 v[26:29], v[146:149], v[182:185], v[26:29]
	v_mfma_f32_16x16x32_bf16 v[22:25], v[150:153], v[182:185], v[22:25]
	v_mfma_f32_16x16x32_bf16 v[18:21], v[154:157], v[182:185], v[18:21]
	v_mfma_f32_16x16x32_bf16 v[42:45], v[158:161], v[182:185], v[42:45]
	ds_read_b128 v[178:181], v0 offset:12288
	ds_read_b128 v[182:185], v0 offset:14336
	s_nop 0
	s_nop 0
	s_nop 0
	s_nop 0
	s_nop 0
	s_waitcnt lgkmcnt(1)
	v_mfma_f32_16x16x32_bf16 v[30:33], v[146:149], v[178:181], v[30:33]
	v_mfma_f32_16x16x32_bf16 v[38:41], v[150:153], v[178:181], v[38:41]
	v_mfma_f32_16x16x32_bf16 v[34:37], v[154:157], v[178:181], v[34:37]
	s_setprio 0
	s_waitcnt vmcnt(0) lgkmcnt(0)
	s_barrier
	v_mfma_f32_16x16x32_bf16 v[142:145], v[158:161], v[178:181], v[142:145]
	v_mfma_f32_16x16x32_bf16 v[138:141], v[146:149], v[182:185], v[138:141]
	v_mfma_f32_16x16x32_bf16 v[134:137], v[150:153], v[182:185], v[134:137]
	v_mfma_f32_16x16x32_bf16 v[110:113], v[154:157], v[182:185], v[110:113]
	v_mfma_f32_16x16x32_bf16 v[90:93], v[158:161], v[182:185], v[90:93]
	s_cmp_eq_u32 s1, 0x80000
	s_cbranch_scc0 .LBB0_1367
	s_setprio 0
	v_add_u32_e32 v0, 32, v173
	ds_read_b128 v[146:149], v0 offset:32768
	s_movk_i32 s1, 0x7000
	s_movk_i32 s10, 0x1800
	s_waitcnt lgkmcnt(0)
	v_mfma_f32_16x16x32_bf16 v[130:133], v[2:5], v[146:149], v[130:133]
	v_mfma_f32_16x16x32_bf16 v[150:153], v[14:17], v[146:149], v[126:129]
	v_mfma_f32_16x16x32_bf16 v[154:157], v[10:13], v[146:149], v[122:125]
	v_mfma_f32_16x16x32_bf16 v[146:149], v[6:9], v[146:149], v[118:121]
	s_nop 2
	ds_read_b128 v[118:121], v0 offset:34816
	s_waitcnt lgkmcnt(0)
	v_mfma_f32_16x16x32_bf16 v[158:161], v[2:5], v[118:121], v[114:117]
	s_nop 2
	ds_read_b128 v[114:117], v0 offset:36864
	s_waitcnt lgkmcnt(0)
	v_mfma_f32_16x16x32_bf16 v[94:97], v[2:5], v[114:117], v[94:97]
	v_mfma_f32_16x16x32_bf16 v[86:89], v[14:17], v[114:117], v[86:89]
	v_mfma_f32_16x16x32_bf16 v[82:85], v[10:13], v[114:117], v[82:85]
	v_mfma_f32_16x16x32_bf16 v[78:81], v[6:9], v[114:117], v[78:81]
	ds_read_b128 v[114:117], v0 offset:38912
	s_waitcnt lgkmcnt(0)
	v_mfma_f32_16x16x32_bf16 v[74:77], v[2:5], v[114:117], v[74:77]
	v_mfma_f32_16x16x32_bf16 v[70:73], v[14:17], v[114:117], v[70:73]
	v_mfma_f32_16x16x32_bf16 v[62:65], v[10:13], v[114:117], v[62:65]
	v_mfma_f32_16x16x32_bf16 v[66:69], v[6:9], v[114:117], v[66:69]
	ds_read_b128 v[114:117], v0 offset:40960
	s_waitcnt lgkmcnt(0)
	v_mfma_f32_16x16x32_bf16 v[172:175], v[6:9], v[114:117], v[54:57]
	s_nop 2
	ds_read_b128 v[54:57], v0 offset:43008
	s_waitcnt lgkmcnt(0)
	v_mfma_f32_16x16x32_bf16 v[176:179], v[6:9], v[54:57], v[42:45]
	s_nop 2
	ds_read_b128 v[42:45], v0 offset:45056
	s_waitcnt lgkmcnt(0)
	v_mfma_f32_16x16x32_bf16 v[190:193], v[10:13], v[42:45], v[34:37]
	s_nop 2
	ds_read_b128 v[34:37], v0 offset:47104
	v_add_u32_e32 v0, 32, v171
	v_mfma_f32_16x16x32_bf16 v[106:109], v[14:17], v[118:121], v[106:109]
	v_mfma_f32_16x16x32_bf16 v[50:53], v[14:17], v[114:117], v[50:53]
	v_mfma_f32_16x16x32_bf16 v[22:25], v[14:17], v[54:57], v[22:25]
	v_mfma_f32_16x16x32_bf16 v[180:183], v[14:17], v[42:45], v[38:41]
	s_waitcnt lgkmcnt(0)
; #define MFMA16(a, b, c) __builtin_amdgcn_mfma_f32_16x16x32_bf16((a), (b), (c), 0, 0, 0)
; template <class Epi>
; DEVI void gemm_tile256b(const bf16_t* __restrict__ A, int lda, const bf16_t* __restrict__ Bt, int K,
;                         int m0, int n0, char* smem, Epi epi) {
;     ...
;     for (int i = 0; i < 4; ++i) b1[i] = *(const bf16x8*)(bp + ((size_t)i * kb32 + kt * 2 + 1) * 512);
;     {
;       bf16x8 af[8];
; #pragma unroll
;       for (int i = 0; i < 8; ++i) af[i] = *(const bf16x8*)(base + a_rd + i * 2048);
; #pragma unroll
;       for (int mi = 0; mi < 8; ++mi)
; #pragma unroll
;         for (int ni = 0; ni < 4; ++ni) acc[mi][ni] = MFMA16(b0[ni], af[mi], acc[mi][ni]);
;     }
;     if (more) {
; #pragma unroll
;       for (int i = 0; i < 4; ++i) b0[i] = *(const bf16x8*)(bp + ((size_t)i * kb32 + kt * 2 + 2) * 512);
;     }
;     {
;       bf16x8 af[8];
; #pragma unroll
;       for (int i = 0; i < 8; ++i) af[i] = *(const bf16x8*)(base + ((a_rd + i * 2048) ^ 64));
; #pragma unroll
;       for (int mi = 0; mi < 8; ++mi)
; #pragma unroll
;         for (int ni = 0; ni < 4; ++ni) acc[mi][ni] = MFMA16(b1[ni], af[mi], acc[mi][ni]);
;     }
;     if (more) {
;       char* nb = smem + ((kt + 1) & 1) * 32768 + lds_w;
; #pragma unroll
;       for (int i = 0; i < 8; ++i) *(u32x4*)(nb + i * 4096) = ra[i];
;     }
;     __syncthreads();
;   }
; #pragma unroll
;   for (int mi = 0; mi < 8; ++mi)
; #pragma unroll
;     for (int ni = 0; ni < 4; ++ni)
;       epi(m0 + wm * 128 + mi * 16 + l15, n0 + wn * 64 + ni * 16 + quad * 4, acc[mi][ni]);
;   DEVI void operator()(int m, int n, f32x4 v) const {
;     if (m >= L) return;
;     if (n < 3072) {
;       *(u32x2*)(raw + (size_t)m * 3072 + n) = u32x2{pack2(v[0], v[1]), pack2(v[2], v[3])};
;     } else if (n < 3088) {
;       *(f32x4*)(ba + (size_t)m * 16 + (n - 3072)) = v;
;     }
	v_mfma_f32_16x16x32_bf16 v[134:137], v[14:17], v[34:37], v[134:137]
	v_add_co_u32_e32 v14, vcc, s1, v162
	s_mov_b32 s1, 0xf000
	s_nop 0
	v_addc_co_u32_e32 v15, vcc, 0, v163, vcc
	v_mfma_f32_16x16x32_bf16 v[102:105], v[10:13], v[118:121], v[102:105]
	global_load_dwordx4 v[14:17], v[14:15], off offset:3072
	v_mfma_f32_16x16x32_bf16 v[46:49], v[2:5], v[114:117], v[46:49]
	v_mfma_f32_16x16x32_bf16 v[164:167], v[10:13], v[114:117], v[58:61]
	v_mfma_f32_16x16x32_bf16 v[26:29], v[2:5], v[54:57], v[26:29]
	v_mfma_f32_16x16x32_bf16 v[18:21], v[10:13], v[54:57], v[18:21]
	v_mfma_f32_16x16x32_bf16 v[30:33], v[2:5], v[42:45], v[30:33]
	v_mfma_f32_16x16x32_bf16 v[2:5], v[2:5], v[34:37], v[138:141]
	v_mfma_f32_16x16x32_bf16 v[138:141], v[10:13], v[34:37], v[110:113]
	v_add_co_u32_e32 v10, vcc, s1, v162
	s_mov_b32 s1, 0x17000
	s_nop 0
	v_addc_co_u32_e32 v11, vcc, 0, v163, vcc
	global_load_dwordx4 v[10:13], v[10:11], off offset:3072
	v_mfma_f32_16x16x32_bf16 v[98:101], v[6:9], v[118:121], v[98:101]
	v_mfma_f32_16x16x32_bf16 v[142:145], v[6:9], v[42:45], v[142:145]
	v_mfma_f32_16x16x32_bf16 v[194:197], v[6:9], v[34:37], v[90:93]
	ds_read_b128 v[6:9], v0 offset:32768
	v_add_co_u32_e32 v34, vcc, s1, v162
	s_mov_b32 s1, 0x1f000
	s_nop 0
	v_addc_co_u32_e32 v35, vcc, 0, v163, vcc
	global_load_dwordx4 v[198:201], v[34:35], off offset:3072
	v_add_co_u32_e32 v34, vcc, s1, v162
	s_waitcnt vmcnt(1) lgkmcnt(0)
	v_mfma_f32_16x16x32_bf16 v[122:125], v[10:13], v[6:9], v[150:153]
	v_addc_co_u32_e32 v35, vcc, 0, v163, vcc
	s_nop 1
	global_load_dwordx4 v[150:153], v[34:35], off offset:3072
	v_mfma_f32_16x16x32_bf16 v[126:129], v[14:17], v[6:9], v[130:133]
	s_waitcnt vmcnt(1)
	v_mfma_f32_16x16x32_bf16 v[118:121], v[198:201], v[6:9], v[154:157]
	s_nop 0
	v_lshl_or_b32 v130, v170, 2, v168
	s_waitcnt vmcnt(0)
	v_mfma_f32_16x16x32_bf16 v[114:117], v[150:153], v[6:9], v[146:149]
	ds_read_b128 v[6:9], v0 offset:34816
	s_nop 1
	ds_read_b128 v[146:149], v0 offset:47104
	s_waitcnt lgkmcnt(1)
	v_mfma_f32_16x16x32_bf16 v[110:113], v[14:17], v[6:9], v[158:161]
	v_mfma_f32_16x16x32_bf16 v[106:109], v[10:13], v[6:9], v[106:109]
	v_mfma_f32_16x16x32_bf16 v[102:105], v[198:201], v[6:9], v[102:105]
	v_mfma_f32_16x16x32_bf16 v[98:101], v[150:153], v[6:9], v[98:101]
	ds_read_b128 v[6:9], v0 offset:36864
	s_waitcnt lgkmcnt(0)
	v_mfma_f32_16x16x32_bf16 v[94:97], v[14:17], v[6:9], v[94:97]
	v_mfma_f32_16x16x32_bf16 v[90:93], v[10:13], v[6:9], v[86:89]
	v_mfma_f32_16x16x32_bf16 v[86:89], v[198:201], v[6:9], v[82:85]
	v_mfma_f32_16x16x32_bf16 v[82:85], v[150:153], v[6:9], v[78:81]
	ds_read_b128 v[6:9], v0 offset:38912
	s_waitcnt lgkmcnt(0)
	v_mfma_f32_16x16x32_bf16 v[78:81], v[14:17], v[6:9], v[74:77]
	v_mfma_f32_16x16x32_bf16 v[74:77], v[10:13], v[6:9], v[70:73]
	v_mfma_f32_16x16x32_bf16 v[70:73], v[198:201], v[6:9], v[62:65]
	v_mfma_f32_16x16x32_bf16 v[66:69], v[150:153], v[6:9], v[66:69]
	ds_read_b128 v[6:9], v0 offset:40960
	s_waitcnt lgkmcnt(0)
	v_mfma_f32_16x16x32_bf16 v[62:65], v[14:17], v[6:9], v[46:49]
	v_mfma_f32_16x16x32_bf16 v[58:61], v[10:13], v[6:9], v[50:53]
	v_mfma_f32_16x16x32_bf16 v[54:57], v[198:201], v[6:9], v[164:167]
	v_mfma_f32_16x16x32_bf16 v[50:53], v[150:153], v[6:9], v[172:175]
	ds_read_b128 v[6:9], v0 offset:43008
	s_waitcnt lgkmcnt(0)
	v_mfma_f32_16x16x32_bf16 v[46:49], v[14:17], v[6:9], v[26:29]
	v_mfma_f32_16x16x32_bf16 v[42:45], v[10:13], v[6:9], v[22:25]
	v_mfma_f32_16x16x32_bf16 v[38:41], v[198:201], v[6:9], v[18:21]
	v_mfma_f32_16x16x32_bf16 v[34:37], v[150:153], v[6:9], v[176:179]
	ds_read_b128 v[6:9], v0 offset:45056
	v_and_b32_e32 v0, 0xffffff80, v169
	v_add_u32_e32 v0, s0, v0
	v_and_or_b32 v132, v169, 15, v0
	v_ashrrev_i32_e32 v133, 31, v132
	s_waitcnt lgkmcnt(0)
	v_mfma_f32_16x16x32_bf16 v[30:33], v[14:17], v[6:9], v[30:33]
	s_movk_i32 s0, 0x4010
	v_cmp_gt_i32_e64 s[0:1], s0, v132
	v_mfma_f32_16x16x32_bf16 v[14:17], v[14:17], v[146:149], v[2:5]
	s_barrier
	s_nop 1
	v_lshlrev_b64 v[2:3], 6, v[132:133]
	v_mfma_f32_16x16x32_bf16 v[26:29], v[10:13], v[6:9], v[180:183]
	v_mfma_f32_16x16x32_bf16 v[10:13], v[10:13], v[146:149], v[134:137]
	s_nop 2
	v_lshl_add_u64 v[136:137], s[6:7], 0, v[2:3]
	v_mov_b64_e32 v[2:3], s[30:31]
	v_mfma_f32_16x16x32_bf16 v[22:25], v[198:201], v[6:9], v[190:193]
	v_mad_i64_i32 v[134:135], s[10:11], v132, s10, v[2:3]
	v_mfma_f32_16x16x32_bf16 v[18:21], v[150:153], v[6:9], v[142:145]
	v_mfma_f32_16x16x32_bf16 v[6:9], v[198:201], v[146:149], v[138:141]
	v_mfma_f32_16x16x32_bf16 v[2:5], v[150:153], v[146:149], v[194:197]
	s_and_saveexec_b64 s[10:11], s[0:1]
	s_cbranch_execz .LBB0_1375
	s_movk_i32 s13, 0xbff
	v_cmp_lt_i32_e32 vcc, s13, v130
	s_and_saveexec_b64 s[16:17], vcc
	s_xor_b64 s[16:17], exec, s[16:17]
	s_cbranch_execz .LBB0_1373
	s_movk_i32 s13, 0xc10
	v_cmp_gt_u32_e32 vcc, s13, v168
	s_and_saveexec_b64 s[34:35], vcc
	s_cbranch_execz .LBB0_1372
	v_mov_b32_e32 v131, v1
	v_lshl_add_u64 v[138:139], v[130:131], 2, v[136:137]
	v_add_co_u32_e32 v138, vcc, 0xffffd000, v138
	s_nop 1
	v_addc_co_u32_e32 v139, vcc, -1, v139, vcc
	global_store_dwordx4 v[138:139], v[126:129], off

; #define MFMA16(a, b, c) __builtin_amdgcn_mfma_f32_16x16x32_bf16((a), (b), (c), 0, 0, 0)
; template <class Epi>
; DEVI void gemm_tile256b(const bf16_t* __restrict__ A, int lda, const bf16_t* __restrict__ Bt, int K,
;                         int m0, int n0, char* smem, Epi epi) {
;     ...
;   for (int kt = 0; kt < nk; ++kt) {
;     const char* base = smem + (kt & 1) * 32768;
;     const bool more = kt + 1 < nk;
;     if (more) {
; #pragma unroll
;       for (int i = 0; i < 8; ++i) ra[i] = *(const u32x4*)(ag + (size_t)(i * 32) * lda + (kt + 1) * 64);
;     }
; #pragma unroll
;     for (int i = 0; i < 4; ++i) b1[i] = *(const bf16x8*)(bp + ((size_t)i * kb32 + kt * 2 + 1) * 512);
;     {
;       bf16x8 af[8];
; #pragma unroll
;       for (int i = 0; i < 8; ++i) af[i] = *(const bf16x8*)(base + a_rd + i * 2048);
; #pragma unroll
;       for (int mi = 0; mi < 8; ++mi)
; #pragma unroll
;         for (int ni = 0; ni < 4; ++ni) acc[mi][ni] = MFMA16(b0[ni], af[mi], acc[mi][ni]);
;     }
;     if (more) {
; #pragma unroll
;       for (int i = 0; i < 4; ++i) b0[i] = *(const bf16x8*)(bp + ((size_t)i * kb32 + kt * 2 + 2) * 512);
;     }
;     {
;       bf16x8 af[8];
; #pragma unroll
;       for (int i = 0; i < 8; ++i) af[i] = *(const bf16x8*)(base + ((a_rd + i * 2048) ^ 64));
; #pragma unroll
;       for (int mi = 0; mi < 8; ++mi)
; #pragma unroll
;         for (int ni = 0; ni < 4; ++ni) acc[mi][ni] = MFMA16(b1[ni], af[mi], acc[mi][ni]);
;     }
;     if (more) {
;       char* nb = smem + ((kt + 1) & 1) * 32768 + lds_w;
; #pragma unroll
;       for (int i = 0; i < 8; ++i) *(u32x4*)(nb + i * 4096) = ra[i];
;     }
;     __syncthreads();
.LBB0_1838:
	s_setprio 1
	s_add_i32 s13, s1, 0xffff8000
	s_and_b32 s13, s13, 0x8000
	s_add_i32 s13, s13, 32
	v_add_u32_e32 v0, s13, v173
	ds_read_b128 v[146:149], v0
	ds_read_b128 v[150:153], v0 offset:2048
	v_lshl_add_u64 v[154:155], v[164:165], 0, s[28:29]
	s_mov_b32 s16, 0x3280000
	v_add_co_u32_e32 v156, vcc, s16, v154
	s_waitcnt vmcnt(3) lgkmcnt(1)
	v_mfma_f32_16x16x32_bf16 v[122:125], v[14:17], v[146:149], v[122:125]
	v_addc_co_u32_e32 v157, vcc, 0, v155, vcc
	s_mov_b32 s16, 0x32a0000
	s_waitcnt vmcnt(2)
	v_mfma_f32_16x16x32_bf16 v[114:117], v[10:13], v[146:149], v[114:117]
	v_add_co_u32_e32 v158, vcc, s16, v154
	s_mov_b32 s16, 0x32c0000
	s_waitcnt vmcnt(1)
	v_mfma_f32_16x16x32_bf16 v[110:113], v[6:9], v[146:149], v[110:113]
	v_addc_co_u32_e32 v159, vcc, 0, v155, vcc
	v_add_co_u32_e32 v160, vcc, s16, v154
	s_waitcnt vmcnt(0)
	v_mfma_f32_16x16x32_bf16 v[106:109], v[2:5], v[146:149], v[106:109]
	v_addc_co_u32_e32 v161, vcc, 0, v155, vcc
	s_mov_b32 s16, 0x32e0000
	s_waitcnt lgkmcnt(0)
	v_mfma_f32_16x16x32_bf16 v[102:105], v[14:17], v[150:153], v[102:105]
	v_add_co_u32_e32 v182, vcc, s16, v154
	v_lshl_add_u64 v[164:165], v[164:165], 0, s[64:65]
	v_mfma_f32_16x16x32_bf16 v[90:93], v[10:13], v[150:153], v[90:93]
	v_addc_co_u32_e32 v183, vcc, 0, v155, vcc
	v_mfma_f32_16x16x32_bf16 v[78:81], v[6:9], v[150:153], v[78:81]
	v_mfma_f32_16x16x32_bf16 v[74:77], v[2:5], v[150:153], v[74:77]
	ds_read_b128 v[146:149], v0 offset:4096
	ds_read_b128 v[150:153], v0 offset:6144
	s_waitcnt lgkmcnt(1)
	v_mfma_f32_16x16x32_bf16 v[70:73], v[14:17], v[146:149], v[70:73]
	v_mfma_f32_16x16x32_bf16 v[66:69], v[10:13], v[146:149], v[66:69]
	v_mfma_f32_16x16x32_bf16 v[58:61], v[6:9], v[146:149], v[58:61]
	v_mfma_f32_16x16x32_bf16 v[46:49], v[2:5], v[146:149], v[46:49]
	s_waitcnt lgkmcnt(0)
	v_mfma_f32_16x16x32_bf16 v[34:37], v[14:17], v[150:153], v[34:37]
	v_mfma_f32_16x16x32_bf16 v[22:25], v[10:13], v[150:153], v[22:25]
	v_mfma_f32_16x16x32_bf16 v[30:33], v[6:9], v[150:153], v[30:33]
	v_mfma_f32_16x16x32_bf16 v[42:45], v[2:5], v[150:153], v[42:45]
	ds_read_b128 v[146:149], v0 offset:8192
	ds_read_b128 v[150:153], v0 offset:10240
	s_waitcnt lgkmcnt(1)
	v_mfma_f32_16x16x32_bf16 v[18:21], v[14:17], v[146:149], v[18:21]
	v_mfma_f32_16x16x32_bf16 v[26:29], v[10:13], v[146:149], v[26:29]
	v_mfma_f32_16x16x32_bf16 v[38:41], v[6:9], v[146:149], v[38:41]
	v_mfma_f32_16x16x32_bf16 v[50:53], v[2:5], v[146:149], v[50:53]
	s_waitcnt lgkmcnt(0)
	v_mfma_f32_16x16x32_bf16 v[54:57], v[14:17], v[150:153], v[54:57]
	v_mfma_f32_16x16x32_bf16 v[62:65], v[10:13], v[150:153], v[62:65]
	v_mfma_f32_16x16x32_bf16 v[98:101], v[6:9], v[150:153], v[98:101]
	v_mfma_f32_16x16x32_bf16 v[118:121], v[2:5], v[150:153], v[118:121]
	ds_read_b128 v[146:149], v0 offset:12288
	ds_read_b128 v[150:153], v0 offset:14336
	v_add_u32_e32 v0, s13, v171
	s_waitcnt lgkmcnt(1)
	v_mfma_f32_16x16x32_bf16 v[86:89], v[14:17], v[146:149], v[86:89]
	v_mfma_f32_16x16x32_bf16 v[94:97], v[10:13], v[146:149], v[94:97]
	v_mfma_f32_16x16x32_bf16 v[82:85], v[6:9], v[146:149], v[82:85]
	v_mfma_f32_16x16x32_bf16 v[142:145], v[2:5], v[146:149], v[142:145]
	s_setprio 0
	global_load_dwordx4 v[146:149], v[156:157], off offset:1024
	ds_read_b128 v[174:177], v0
	ds_read_b128 v[178:181], v0 offset:2048
	s_waitcnt lgkmcnt(2)
	v_mfma_f32_16x16x32_bf16 v[138:141], v[14:17], v[150:153], v[138:141]
	global_load_dwordx4 v[14:17], v[156:157], off offset:2048
	v_mfma_f32_16x16x32_bf16 v[134:137], v[10:13], v[150:153], v[134:137]
	v_mfma_f32_16x16x32_bf16 v[130:133], v[6:9], v[150:153], v[130:133]
	v_mfma_f32_16x16x32_bf16 v[126:129], v[2:5], v[150:153], v[126:129]
	global_load_dwordx4 v[150:153], v[158:159], off offset:1024
	global_load_dwordx4 v[10:13], v[158:159], off offset:2048
	global_load_dwordx4 v[154:157], v[160:161], off offset:1024
	global_load_dwordx4 v[6:9], v[160:161], off offset:2048
	s_nop 0
	global_load_dwordx4 v[158:161], v[182:183], off offset:1024
	global_load_dwordx4 v[2:5], v[182:183], off offset:2048
	v_lshrrev_b32_e32 v195, 6, v206
	v_lshl_add_u64 v[190:191], v[166:167], 0, s[28:29]
	v_lshrrev_b32_e32 v194, 3, v206
	v_readfirstlane_b32 s99, v195
	v_and_b32_e32 v194, 7, v194
	s_and_b32 s98, s1, 0x8000
	v_lshlrev_b32_e32 v194, 4, v194
	s_lshl_b32 s99, s99, 10
	v_xor_b32_e32 v190, v194, v190
	s_add_u32 s98, s98, s99
	s_add_u32 s98, s98, 32
	s_mov_b32 s101, 0
	s_mov_b32 s100, 0x3b93080
	v_lshl_add_u64 v[192:193], v[190:191], 0, s[100:101]
	s_mov_b32 m0, s98
	s_nop 0
	global_load_lds_dwordx4 v[192:193], off
	s_mov_b32 s100, 0x3bd3080
	v_lshl_add_u64 v[192:193], v[190:191], 0, s[100:101]
	s_add_u32 m0, s98, 0x1000
	s_nop 0
	global_load_lds_dwordx4 v[192:193], off
	s_mov_b32 s100, 0x3c13080
	v_lshl_add_u64 v[192:193], v[190:191], 0, s[100:101]
	s_add_u32 m0, s98, 0x2000
	s_nop 0
	global_load_lds_dwordx4 v[192:193], off
	s_mov_b32 s100, 0x3c53080
	v_lshl_add_u64 v[192:193], v[190:191], 0, s[100:101]
	s_add_u32 m0, s98, 0x3000
	s_nop 0
	global_load_lds_dwordx4 v[192:193], off
	s_mov_b32 s100, 0x3c93080
	v_lshl_add_u64 v[192:193], v[190:191], 0, s[100:101]
	s_add_u32 m0, s98, 0x4000
	s_nop 0
	global_load_lds_dwordx4 v[192:193], off
	s_mov_b32 s100, 0x3cd3080
	v_lshl_add_u64 v[192:193], v[190:191], 0, s[100:101]
	s_add_u32 m0, s98, 0x5000
	s_nop 0
	global_load_lds_dwordx4 v[192:193], off
	s_mov_b32 s100, 0x3d13080
	v_lshl_add_u64 v[192:193], v[190:191], 0, s[100:101]
	s_add_u32 m0, s98, 0x6000
	s_nop 0
	global_load_lds_dwordx4 v[192:193], off
	s_mov_b32 s100, 0x3d53080
	v_lshl_add_u64 v[192:193], v[190:191], 0, s[100:101]
	s_add_u32 m0, s98, 0x7000
	s_nop 0
	global_load_lds_dwordx4 v[192:193], off
	s_setprio 1
	s_nop 0
	s_nop 0
	s_waitcnt vmcnt(15) lgkmcnt(1)
; #define MFMA16(a, b, c) __builtin_amdgcn_mfma_f32_16x16x32_bf16((a), (b), (c), 0, 0, 0)
; template <class Epi>
; DEVI void gemm_tile256b(const bf16_t* __restrict__ A, int lda, const bf16_t* __restrict__ Bt, int K,
;                         int m0, int n0, char* smem, Epi epi) {
;     ...
;     {
;       bf16x8 af[8];
; #pragma unroll
;       for (int i = 0; i < 8; ++i) af[i] = *(const bf16x8*)(base + ((a_rd + i * 2048) ^ 64));
; #pragma unroll
;       for (int mi = 0; mi < 8; ++mi)
; #pragma unroll
;         for (int ni = 0; ni < 4; ++ni) acc[mi][ni] = MFMA16(b1[ni], af[mi], acc[mi][ni]);
;     }
;     if (more) {
;       char* nb = smem + ((kt + 1) & 1) * 32768 + lds_w;
; #pragma unroll
;       for (int i = 0; i < 8; ++i) *(u32x4*)(nb + i * 4096) = ra[i];
;     }
;     __syncthreads();
	v_mfma_f32_16x16x32_bf16 v[122:125], v[146:149], v[174:177], v[122:125]
	s_waitcnt vmcnt(13)
	v_mfma_f32_16x16x32_bf16 v[114:117], v[150:153], v[174:177], v[114:117]
	s_waitcnt vmcnt(11)
	v_mfma_f32_16x16x32_bf16 v[110:113], v[154:157], v[174:177], v[110:113]
	s_waitcnt vmcnt(9)
	v_mfma_f32_16x16x32_bf16 v[106:109], v[158:161], v[174:177], v[106:109]
	s_waitcnt lgkmcnt(0)
	v_mfma_f32_16x16x32_bf16 v[102:105], v[146:149], v[178:181], v[102:105]
	v_mfma_f32_16x16x32_bf16 v[90:93], v[150:153], v[178:181], v[90:93]
	v_mfma_f32_16x16x32_bf16 v[78:81], v[154:157], v[178:181], v[78:81]
	s_nop 0
	v_mfma_f32_16x16x32_bf16 v[74:77], v[158:161], v[178:181], v[74:77]
	ds_read_b128 v[174:177], v0 offset:4096
	ds_read_b128 v[178:181], v0 offset:6144
	s_waitcnt lgkmcnt(1)
	v_mfma_f32_16x16x32_bf16 v[70:73], v[146:149], v[174:177], v[70:73]
	s_and_b32 s13, s1, 0x8000
	v_mfma_f32_16x16x32_bf16 v[66:69], v[150:153], v[174:177], v[66:69]
	s_add_i32 s1, s1, 0x8000
	v_lshl_add_u64 v[166:167], v[166:167], 0, s[60:61]
	s_cmp_eq_u32 s1, 0x200000
	v_mfma_f32_16x16x32_bf16 v[58:61], v[154:157], v[174:177], v[58:61]
	v_mfma_f32_16x16x32_bf16 v[46:49], v[158:161], v[174:177], v[46:49]
	s_waitcnt lgkmcnt(0)
	v_mfma_f32_16x16x32_bf16 v[34:37], v[146:149], v[178:181], v[34:37]
	v_mfma_f32_16x16x32_bf16 v[22:25], v[150:153], v[178:181], v[22:25]
	v_mfma_f32_16x16x32_bf16 v[30:33], v[154:157], v[178:181], v[30:33]
	v_mfma_f32_16x16x32_bf16 v[42:45], v[158:161], v[178:181], v[42:45]
	ds_read_b128 v[174:177], v0 offset:8192
	ds_read_b128 v[178:181], v0 offset:10240
	s_waitcnt lgkmcnt(1)
	v_mfma_f32_16x16x32_bf16 v[18:21], v[146:149], v[174:177], v[18:21]
	v_mfma_f32_16x16x32_bf16 v[26:29], v[150:153], v[174:177], v[26:29]
	v_mfma_f32_16x16x32_bf16 v[38:41], v[154:157], v[174:177], v[38:41]
	v_mfma_f32_16x16x32_bf16 v[50:53], v[158:161], v[174:177], v[50:53]
	s_waitcnt lgkmcnt(0)
	v_mfma_f32_16x16x32_bf16 v[54:57], v[146:149], v[178:181], v[54:57]
	v_mfma_f32_16x16x32_bf16 v[62:65], v[150:153], v[178:181], v[62:65]
	v_mfma_f32_16x16x32_bf16 v[98:101], v[154:157], v[178:181], v[98:101]
	v_mfma_f32_16x16x32_bf16 v[118:121], v[158:161], v[178:181], v[118:121]
	ds_read_b128 v[178:181], v0 offset:12288
	ds_read_b128 v[182:185], v0 offset:14336
	s_nop 0
	s_nop 0
	s_nop 0
	s_nop 0
	s_nop 0
	s_waitcnt lgkmcnt(1)
	v_mfma_f32_16x16x32_bf16 v[86:89], v[146:149], v[178:181], v[86:89]
	v_mfma_f32_16x16x32_bf16 v[94:97], v[150:153], v[178:181], v[94:97]
	v_mfma_f32_16x16x32_bf16 v[82:85], v[154:157], v[178:181], v[82:85]
	s_setprio 0
	s_waitcnt vmcnt(0) lgkmcnt(0)
	s_barrier
	v_mfma_f32_16x16x32_bf16 v[142:145], v[158:161], v[178:181], v[142:145]
	v_mfma_f32_16x16x32_bf16 v[138:141], v[146:149], v[182:185], v[138:141]
	v_mfma_f32_16x16x32_bf16 v[134:137], v[150:153], v[182:185], v[134:137]
	v_mfma_f32_16x16x32_bf16 v[130:133], v[154:157], v[182:185], v[130:133]
	v_mfma_f32_16x16x32_bf16 v[126:129], v[158:161], v[182:185], v[126:129]
	s_cbranch_scc0 .LBB0_1838
	s_setprio 0
	v_add_u32_e32 v0, 32, v173
	ds_read_b128 v[146:149], v0 offset:32768
	ds_read_b128 v[150:153], v0 offset:34816
	s_waitcnt lgkmcnt(1)
	v_mfma_f32_16x16x32_bf16 v[122:125], v[14:17], v[146:149], v[122:125]
	v_mfma_f32_16x16x32_bf16 v[114:117], v[10:13], v[146:149], v[114:117]
	v_mfma_f32_16x16x32_bf16 v[110:113], v[6:9], v[146:149], v[110:113]
	v_mfma_f32_16x16x32_bf16 v[106:109], v[2:5], v[146:149], v[106:109]
	s_waitcnt lgkmcnt(0)
	v_mfma_f32_16x16x32_bf16 v[102:105], v[14:17], v[150:153], v[102:105]
	v_mfma_f32_16x16x32_bf16 v[90:93], v[10:13], v[150:153], v[90:93]
	v_mfma_f32_16x16x32_bf16 v[78:81], v[6:9], v[150:153], v[78:81]
	v_mfma_f32_16x16x32_bf16 v[74:77], v[2:5], v[150:153], v[74:77]
	ds_read_b128 v[146:149], v0 offset:36864
	ds_read_b128 v[150:153], v0 offset:38912
	s_waitcnt lgkmcnt(1)
	v_mfma_f32_16x16x32_bf16 v[70:73], v[14:17], v[146:149], v[70:73]
	v_mfma_f32_16x16x32_bf16 v[66:69], v[10:13], v[146:149], v[66:69]
	v_mfma_f32_16x16x32_bf16 v[58:61], v[6:9], v[146:149], v[58:61]
	v_mfma_f32_16x16x32_bf16 v[46:49], v[2:5], v[146:149], v[46:49]
	s_waitcnt lgkmcnt(0)
	v_mfma_f32_16x16x32_bf16 v[34:37], v[14:17], v[150:153], v[34:37]
	v_mfma_f32_16x16x32_bf16 v[22:25], v[10:13], v[150:153], v[22:25]
	v_mfma_f32_16x16x32_bf16 v[30:33], v[6:9], v[150:153], v[30:33]
	v_mfma_f32_16x16x32_bf16 v[42:45], v[2:5], v[150:153], v[42:45]
	ds_read_b128 v[146:149], v0 offset:40960
	ds_read_b128 v[150:153], v0 offset:43008
	s_waitcnt lgkmcnt(1)
	v_mfma_f32_16x16x32_bf16 v[18:21], v[14:17], v[146:149], v[18:21]
	v_mfma_f32_16x16x32_bf16 v[26:29], v[10:13], v[146:149], v[26:29]
	v_mfma_f32_16x16x32_bf16 v[38:41], v[6:9], v[146:149], v[38:41]
	v_mfma_f32_16x16x32_bf16 v[50:53], v[2:5], v[146:149], v[50:53]
	s_waitcnt lgkmcnt(0)
	v_mfma_f32_16x16x32_bf16 v[146:149], v[14:17], v[150:153], v[54:57]
	v_mfma_f32_16x16x32_bf16 v[154:157], v[10:13], v[150:153], v[62:65]
	s_nop 1
	ds_read_b128 v[54:57], v0 offset:45056
	ds_read_b128 v[62:65], v0 offset:47104
	v_add_u32_e32 v0, 32, v171
	s_waitcnt lgkmcnt(1)
	v_mfma_f32_16x16x32_bf16 v[176:179], v[6:9], v[54:57], v[82:85]
	s_nop 2
	v_add_co_u32_e32 v82, vcc, 0x1f000, v162
	v_mfma_f32_16x16x32_bf16 v[164:167], v[14:17], v[54:57], v[86:89]
	s_nop 0
	v_addc_co_u32_e32 v83, vcc, 0, v163, vcc
	v_mfma_f32_16x16x32_bf16 v[172:175], v[10:13], v[54:57], v[94:97]
	v_mfma_f32_16x16x32_bf16 v[142:145], v[2:5], v[54:57], v[142:145]
	v_add_co_u32_e32 v54, vcc, 0x3f000, v162
	s_nop 1
	v_addc_co_u32_e32 v55, vcc, 0, v163, vcc
	s_waitcnt lgkmcnt(0)
; #define MFMA16(a, b, c) __builtin_amdgcn_mfma_f32_16x16x32_bf16((a), (b), (c), 0, 0, 0)
; template <class Epi>
; DEVI void gemm_tile256b(const bf16_t* __restrict__ A, int lda, const bf16_t* __restrict__ Bt, int K,
;                         int m0, int n0, char* smem, Epi epi) {
;     ...
;     {
;       bf16x8 af[8];
; #pragma unroll
;       for (int i = 0; i < 8; ++i) af[i] = *(const bf16x8*)(base + ((a_rd + i * 2048) ^ 64));
; #pragma unroll
;       for (int mi = 0; mi < 8; ++mi)
; #pragma unroll
;         for (int ni = 0; ni < 4; ++ni) acc[mi][ni] = MFMA16(b1[ni], af[mi], acc[mi][ni]);
;     }
;     if (more) {
;       char* nb = smem + ((kt + 1) & 1) * 32768 + lds_w;
; #pragma unroll
;       for (int i = 0; i < 8; ++i) *(u32x4*)(nb + i * 4096) = ra[i];
;     }
;     __syncthreads();
;   }
; #pragma unroll
;   for (int mi = 0; mi < 8; ++mi)
; #pragma unroll
;     for (int ni = 0; ni < 4; ++ni)
;       epi(m0 + wm * 128 + mi * 16 + l15, n0 + wn * 64 + ni * 16 + quad * 4, acc[mi][ni]);
;   DEVI void operator()(int m, int n, f32x4 v) const {
;     if (m >= L) return;
;     float* h = hfrow(p, m) + n;
;     const float* src = (first && m >= 16) ? p.in[0] + (size_t)(m - 16) * 1024 + n : h;
;     f32x4 o = *(const f32x4*)src;
;     o = o * ALPHA + v;
;     *(f32x4*)h = o;
;   }
	v_mfma_f32_16x16x32_bf16 v[14:17], v[14:17], v[62:65], v[138:141]
	s_nop 2
	global_load_dwordx4 v[138:141], v[82:83], off offset:3072
	v_mfma_f32_16x16x32_bf16 v[10:13], v[10:13], v[62:65], v[134:137]
	s_nop 2
	global_load_dwordx4 v[134:137], v[54:55], off offset:3072
	v_add_co_u32_e32 v82, vcc, 0x5f000, v162
	v_mfma_f32_16x16x32_bf16 v[158:161], v[6:9], v[150:153], v[98:101]
	s_nop 0
	v_addc_co_u32_e32 v83, vcc, 0, v163, vcc
	ds_read_b128 v[54:57], v0 offset:32768
	v_mfma_f32_16x16x32_bf16 v[6:9], v[6:9], v[62:65], v[130:133]
	s_nop 2
	global_load_dwordx4 v[130:133], v[82:83], off offset:3072
	v_add_co_u32_e32 v82, vcc, 0x7f000, v162
	v_mfma_f32_16x16x32_bf16 v[150:153], v[2:5], v[150:153], v[118:121]
	s_nop 0
	v_addc_co_u32_e32 v83, vcc, 0, v163, vcc
	global_load_dwordx4 v[180:183], v[82:83], off offset:3072
	v_mfma_f32_16x16x32_bf16 v[2:5], v[2:5], v[62:65], v[126:129]
	ds_read_b128 v[62:65], v0 offset:34816
	s_waitcnt vmcnt(3) lgkmcnt(1)
	v_mfma_f32_16x16x32_bf16 v[126:129], v[138:141], v[54:57], v[122:125]
	s_waitcnt vmcnt(2)
	v_mfma_f32_16x16x32_bf16 v[122:125], v[134:137], v[54:57], v[114:117]
	s_waitcnt vmcnt(1)
	v_mfma_f32_16x16x32_bf16 v[118:121], v[130:133], v[54:57], v[110:113]
	s_waitcnt vmcnt(0)
	v_mfma_f32_16x16x32_bf16 v[114:117], v[180:183], v[54:57], v[106:109]
	s_waitcnt lgkmcnt(0)
	v_mfma_f32_16x16x32_bf16 v[110:113], v[138:141], v[62:65], v[102:105]
	v_mfma_f32_16x16x32_bf16 v[106:109], v[134:137], v[62:65], v[90:93]
	v_mfma_f32_16x16x32_bf16 v[102:105], v[130:133], v[62:65], v[78:81]
	v_mfma_f32_16x16x32_bf16 v[98:101], v[180:183], v[62:65], v[74:77]
	ds_read_b128 v[54:57], v0 offset:36864
	ds_read_b128 v[62:65], v0 offset:38912
	s_waitcnt lgkmcnt(1)
	v_mfma_f32_16x16x32_bf16 v[94:97], v[138:141], v[54:57], v[70:73]
	s_waitcnt lgkmcnt(0)
	v_mfma_f32_16x16x32_bf16 v[74:77], v[134:137], v[62:65], v[22:25]
	v_mfma_f32_16x16x32_bf16 v[70:73], v[130:133], v[62:65], v[30:33]
	s_nop 1
	ds_read_b128 v[22:25], v0 offset:40960
	ds_read_b128 v[30:33], v0 offset:43008
	v_mfma_f32_16x16x32_bf16 v[90:93], v[134:137], v[54:57], v[66:69]
	v_mfma_f32_16x16x32_bf16 v[82:85], v[180:183], v[54:57], v[46:49]
	v_mfma_f32_16x16x32_bf16 v[78:81], v[138:141], v[62:65], v[34:37]
	v_mfma_f32_16x16x32_bf16 v[66:69], v[180:183], v[62:65], v[42:45]
	s_waitcnt lgkmcnt(1)
	v_mfma_f32_16x16x32_bf16 v[62:65], v[138:141], v[22:25], v[18:21]
	s_waitcnt lgkmcnt(0)
	v_mfma_f32_16x16x32_bf16 v[46:49], v[138:141], v[30:33], v[146:149]
	s_nop 0
	ds_read_b128 v[18:21], v0 offset:45056
	s_nop 0
	ds_read_b128 v[146:149], v0 offset:47104
	v_and_b32_e32 v0, 0xffffff80, v168
	v_add_u32_e32 v0, s0, v0
	v_mfma_f32_16x16x32_bf16 v[86:89], v[130:133], v[54:57], v[58:61]
	s_movk_i32 s0, 0x4010
	s_waitcnt lgkmcnt(0)
	s_barrier
	v_mfma_f32_16x16x32_bf16 v[58:61], v[134:137], v[22:25], v[26:29]
	v_mfma_f32_16x16x32_bf16 v[54:57], v[130:133], v[22:25], v[38:41]
	v_mfma_f32_16x16x32_bf16 v[50:53], v[180:183], v[22:25], v[50:53]
	v_mfma_f32_16x16x32_bf16 v[42:45], v[134:137], v[30:33], v[154:157]
	v_mfma_f32_16x16x32_bf16 v[38:41], v[130:133], v[30:33], v[158:161]
	v_mfma_f32_16x16x32_bf16 v[34:37], v[180:183], v[30:33], v[150:153]
	v_mfma_f32_16x16x32_bf16 v[30:33], v[138:141], v[18:21], v[164:167]
	v_mfma_f32_16x16x32_bf16 v[26:29], v[134:137], v[18:21], v[172:175]
	v_mfma_f32_16x16x32_bf16 v[22:25], v[130:133], v[18:21], v[176:179]
	v_mfma_f32_16x16x32_bf16 v[18:21], v[180:183], v[18:21], v[142:145]
	v_mfma_f32_16x16x32_bf16 v[14:17], v[138:141], v[146:149], v[14:17]
	v_mfma_f32_16x16x32_bf16 v[10:13], v[134:137], v[146:149], v[10:13]
	v_mfma_f32_16x16x32_bf16 v[6:9], v[130:133], v[146:149], v[6:9]
	v_and_or_b32 v132, v168, 15, v0
	v_lshl_or_b32 v130, v169, 2, v170
	v_cmp_gt_i32_e32 vcc, s0, v132
	v_mfma_f32_16x16x32_bf16 v[2:5], v[180:183], v[146:149], v[2:5]
	v_ashrrev_i32_e32 v131, 31, v130
	s_and_saveexec_b64 s[0:1], vcc
	s_cbranch_execz .LBB0_1841
	v_lshlrev_b32_e32 v134, 10, v132
	v_add_u32_e32 v136, -16, v132
	v_mov_b32_e32 v137, v1
	v_ashrrev_i32_e32 v135, 31, v134
	v_lshlrev_b64 v[136:137], 12, v[136:137]
	v_lshl_add_u64 v[134:135], v[134:135], 2, s[34:35]
	v_lshl_add_u64 v[136:137], s[26:27], 0, v[136:137]
	v_cmp_gt_i32_e32 vcc, 16, v132
	s_nop 1
	v_cndmask_b32_e32 v135, v137, v135, vcc
	v_cndmask_b32_e32 v134, v136, v134, vcc
	v_lshl_add_u64 v[138:139], v[130:131], 2, v[134:135]
	global_load_dwordx4 v[134:137], v[138:139], off
	s_waitcnt vmcnt(0)
	v_pk_fma_f32 v[128:129], v[136:137], s[66:67], v[128:129] op_sel_hi:[1,0,1]
	v_pk_fma_f32 v[126:127], v[134:135], s[66:67], v[126:127] op_sel_hi:[1,0,1]
	global_store_dwordx4 v[138:139], v[126:129], off
	global_load_dwordx4 v[126:129], v[138:139], off offset:64
	s_waitcnt vmcnt(0)
	v_pk_fma_f32 v[124:125], v[128:129], s[66:67], v[124:125] op_sel_hi:[1,0,1]
	v_pk_fma_f32 v[122:123], v[126:127], s[66:67], v[122:123] op_sel_hi:[1,0,1]
	global_store_dwordx4 v[138:139], v[122:125], off offset:64
	global_load_dwordx4 v[122:125], v[138:139], off offset:128
	s_waitcnt vmcnt(0)
	v_pk_fma_f32 v[120:121], v[124:125], s[66:67], v[120:121] op_sel_hi:[1,0,1]
	v_pk_fma_f32 v[118:119], v[122:123], s[66:67], v[118:119] op_sel_hi:[1,0,1]
	global_store_dwordx4 v[138:139], v[118:121], off offset:128
	global_load_dwordx4 v[118:121], v[138:139], off offset:192
	s_waitcnt vmcnt(0)
	v_pk_fma_f32 v[116:117], v[120:121], s[66:67], v[116:117] op_sel_hi:[1,0,1]
	v_pk_fma_f32 v[114:115], v[118:119], s[66:67], v[114:115] op_sel_hi:[1,0,1]
	global_store_dwordx4 v[138:139], v[114:117], off offset:192

; #define MFMA16(a, b, c) __builtin_amdgcn_mfma_f32_16x16x32_bf16((a), (b), (c), 0, 0, 0)
; template <class Epi>
; DEVI void gemm_tile256b(const bf16_t* __restrict__ A, int lda, const bf16_t* __restrict__ Bt, int K,
;                         int m0, int n0, char* smem, Epi epi) {
;     ...
;   for (int kt = 0; kt < nk; ++kt) {
;     const char* base = smem + (kt & 1) * 32768;
;     const bool more = kt + 1 < nk;
;     if (more) {
; #pragma unroll
;       for (int i = 0; i < 8; ++i) ra[i] = *(const u32x4*)(ag + (size_t)(i * 32) * lda + (kt + 1) * 64);
;     }
; #pragma unroll
;     for (int i = 0; i < 4; ++i) b1[i] = *(const bf16x8*)(bp + ((size_t)i * kb32 + kt * 2 + 1) * 512);
;     {
;       bf16x8 af[8];
; #pragma unroll
;       for (int i = 0; i < 8; ++i) af[i] = *(const bf16x8*)(base + a_rd + i * 2048);
; #pragma unroll
;       for (int mi = 0; mi < 8; ++mi)
; #pragma unroll
;         for (int ni = 0; ni < 4; ++ni) acc[mi][ni] = MFMA16(b0[ni], af[mi], acc[mi][ni]);
;     }
;     if (more) {
; #pragma unroll
;       for (int i = 0; i < 4; ++i) b0[i] = *(const bf16x8*)(bp + ((size_t)i * kb32 + kt * 2 + 2) * 512);
;     }
;     {
;       bf16x8 af[8];
; #pragma unroll
;       for (int i = 0; i < 8; ++i) af[i] = *(const bf16x8*)(base + ((a_rd + i * 2048) ^ 64));
; #pragma unroll
;       for (int mi = 0; mi < 8; ++mi)
; #pragma unroll
;         for (int ni = 0; ni < 4; ++ni) acc[mi][ni] = MFMA16(b1[ni], af[mi], acc[mi][ni]);
;     }
;     if (more) {
;       char* nb = smem + ((kt + 1) & 1) * 32768 + lds_w;
; #pragma unroll
;       for (int i = 0; i < 8; ++i) *(u32x4*)(nb + i * 4096) = ra[i];
;     }
;     __syncthreads();
.LBB0_1873:
	s_setprio 1
	s_add_i32 s10, s1, 0xffff8000
	s_and_b32 s10, s10, 0x8000
	s_add_i32 s10, s10, 32
	v_add_u32_e32 v0, s10, v173
	ds_read_b128 v[146:149], v0
	ds_read_b128 v[150:153], v0 offset:2048
	v_lshl_add_u64 v[154:155], v[164:165], 0, s[28:29]
	s_mov_b32 s11, 0x2a80000
	v_add_co_u32_e32 v156, vcc, s11, v154
	s_waitcnt vmcnt(3) lgkmcnt(1)
	v_mfma_f32_16x16x32_bf16 v[134:137], v[10:13], v[146:149], v[134:137]
	v_addc_co_u32_e32 v157, vcc, 0, v155, vcc
	s_mov_b32 s11, 0x2a88000
	s_waitcnt vmcnt(2)
	v_mfma_f32_16x16x32_bf16 v[130:133], v[14:17], v[146:149], v[130:133]
	v_add_co_u32_e32 v158, vcc, s11, v154
	s_mov_b32 s11, 0x2a90000
	s_waitcnt vmcnt(1)
	v_mfma_f32_16x16x32_bf16 v[126:129], v[6:9], v[146:149], v[126:129]
	v_addc_co_u32_e32 v159, vcc, 0, v155, vcc
	v_add_co_u32_e32 v160, vcc, s11, v154
	s_waitcnt vmcnt(0)
	v_mfma_f32_16x16x32_bf16 v[122:125], v[2:5], v[146:149], v[122:125]
	v_addc_co_u32_e32 v161, vcc, 0, v155, vcc
	s_mov_b32 s11, 0x2a98000
	s_waitcnt lgkmcnt(0)
	v_mfma_f32_16x16x32_bf16 v[114:117], v[10:13], v[150:153], v[114:117]
	v_add_co_u32_e32 v182, vcc, s11, v154
	v_mfma_f32_16x16x32_bf16 v[110:113], v[14:17], v[150:153], v[110:113]
	v_addc_co_u32_e32 v183, vcc, 0, v155, vcc
	v_mfma_f32_16x16x32_bf16 v[106:109], v[6:9], v[150:153], v[106:109]
	s_nop 0
	v_mfma_f32_16x16x32_bf16 v[102:105], v[2:5], v[150:153], v[102:105]
	ds_read_b128 v[146:149], v0 offset:4096
	ds_read_b128 v[150:153], v0 offset:6144
	s_waitcnt lgkmcnt(1)
	v_mfma_f32_16x16x32_bf16 v[98:101], v[10:13], v[146:149], v[98:101]
	v_lshl_add_u64 v[164:165], v[164:165], 0, s[64:65]
	v_mfma_f32_16x16x32_bf16 v[94:97], v[14:17], v[146:149], v[94:97]
	v_mfma_f32_16x16x32_bf16 v[86:89], v[6:9], v[146:149], v[86:89]
	s_nop 0
	v_mfma_f32_16x16x32_bf16 v[82:85], v[2:5], v[146:149], v[82:85]
	s_nop 0
	s_waitcnt lgkmcnt(0)
	v_mfma_f32_16x16x32_bf16 v[74:77], v[10:13], v[150:153], v[74:77]
	v_mfma_f32_16x16x32_bf16 v[70:73], v[14:17], v[150:153], v[70:73]
	s_nop 0
	v_lshl_add_u64 v[166:167], v[166:167], 0, s[60:61]
	v_mfma_f32_16x16x32_bf16 v[62:65], v[6:9], v[150:153], v[62:65]
	v_mfma_f32_16x16x32_bf16 v[66:69], v[2:5], v[150:153], v[66:69]
	ds_read_b128 v[146:149], v0 offset:8192
	ds_read_b128 v[150:153], v0 offset:10240
	s_waitcnt lgkmcnt(1)
	v_mfma_f32_16x16x32_bf16 v[46:49], v[10:13], v[146:149], v[46:49]
	v_mfma_f32_16x16x32_bf16 v[50:53], v[14:17], v[146:149], v[50:53]
	v_mfma_f32_16x16x32_bf16 v[58:61], v[6:9], v[146:149], v[58:61]
	v_mfma_f32_16x16x32_bf16 v[54:57], v[2:5], v[146:149], v[54:57]
	s_waitcnt lgkmcnt(0)
	v_mfma_f32_16x16x32_bf16 v[26:29], v[10:13], v[150:153], v[26:29]
	v_mfma_f32_16x16x32_bf16 v[22:25], v[14:17], v[150:153], v[22:25]
	v_mfma_f32_16x16x32_bf16 v[18:21], v[6:9], v[150:153], v[18:21]
	v_mfma_f32_16x16x32_bf16 v[42:45], v[2:5], v[150:153], v[42:45]
	ds_read_b128 v[146:149], v0 offset:12288
	ds_read_b128 v[150:153], v0 offset:14336
	v_add_u32_e32 v0, s10, v171
	s_and_b32 s10, s1, 0x8000
	s_waitcnt lgkmcnt(1)
	v_mfma_f32_16x16x32_bf16 v[34:37], v[10:13], v[146:149], v[34:37]
	s_add_i32 s1, s1, 0x8000
	s_cmp_eq_u32 s1, 0x80000
	v_mfma_f32_16x16x32_bf16 v[38:41], v[14:17], v[146:149], v[38:41]
	v_mfma_f32_16x16x32_bf16 v[30:33], v[6:9], v[146:149], v[30:33]
	v_mfma_f32_16x16x32_bf16 v[142:145], v[2:5], v[146:149], v[142:145]
	s_setprio 0
	global_load_dwordx4 v[146:149], v[156:157], off offset:1024
	ds_read_b128 v[174:177], v0
	ds_read_b128 v[178:181], v0 offset:2048
	s_waitcnt lgkmcnt(2)
	v_mfma_f32_16x16x32_bf16 v[138:141], v[10:13], v[150:153], v[138:141]
	global_load_dwordx4 v[10:13], v[156:157], off offset:2048
	v_mfma_f32_16x16x32_bf16 v[118:121], v[14:17], v[150:153], v[118:121]
	v_mfma_f32_16x16x32_bf16 v[90:93], v[6:9], v[150:153], v[90:93]
	v_mfma_f32_16x16x32_bf16 v[78:81], v[2:5], v[150:153], v[78:81]
	global_load_dwordx4 v[150:153], v[158:159], off offset:1024
	global_load_dwordx4 v[14:17], v[158:159], off offset:2048
	global_load_dwordx4 v[154:157], v[160:161], off offset:1024
	global_load_dwordx4 v[6:9], v[160:161], off offset:2048
	s_nop 0
	global_load_dwordx4 v[158:161], v[182:183], off offset:1024
	global_load_dwordx4 v[2:5], v[182:183], off offset:2048
	v_lshrrev_b32_e32 v195, 6, v206
	v_lshl_add_u64 v[190:191], v[166:167], 0, s[28:29]
	v_lshrrev_b32_e32 v194, 3, v206
	v_readfirstlane_b32 s99, v195
	v_and_b32_e32 v194, 7, v194
	s_and_b32 s98, s1, 0x8000
	s_xor_b32 s98, s98, 0x8000
	v_lshlrev_b32_e32 v194, 4, v194
	s_lshl_b32 s99, s99, 10
	v_xor_b32_e32 v190, v194, v190
	s_add_u32 s98, s98, s99
	s_add_u32 s98, s98, 32
	s_mov_b32 s101, 0
	s_mov_b32 s100, 0x0
	v_lshl_add_u64 v[192:193], v[190:191], 0, s[100:101]
	s_mov_b32 m0, s98
	s_nop 0
	global_load_lds_dwordx4 v[192:193], off
	s_add_u32 s100, s54, 0x0
	v_lshl_add_u64 v[192:193], v[190:191], 0, s[100:101]
	s_add_u32 m0, s98, 0x1000
	s_nop 0
	global_load_lds_dwordx4 v[192:193], off
	s_add_u32 s100, s53, 0x0
	v_lshl_add_u64 v[192:193], v[190:191], 0, s[100:101]
	s_add_u32 m0, s98, 0x2000
	s_nop 0
	global_load_lds_dwordx4 v[192:193], off
	s_add_u32 s100, s52, 0x0
	v_lshl_add_u64 v[192:193], v[190:191], 0, s[100:101]
	s_add_u32 m0, s98, 0x3000
	s_nop 0
	global_load_lds_dwordx4 v[192:193], off
	s_add_u32 s100, s56, 0x0
	v_lshl_add_u64 v[192:193], v[190:191], 0, s[100:101]
	s_add_u32 m0, s98, 0x4000
	s_nop 0
	global_load_lds_dwordx4 v[192:193], off
	s_add_u32 s100, s57, 0x0
	v_lshl_add_u64 v[192:193], v[190:191], 0, s[100:101]
	s_add_u32 m0, s98, 0x5000
	s_nop 0
	global_load_lds_dwordx4 v[192:193], off
	s_add_u32 s100, s3, 0x0
	v_lshl_add_u64 v[192:193], v[190:191], 0, s[100:101]
	s_add_u32 m0, s98, 0x6000
	s_nop 0
	global_load_lds_dwordx4 v[192:193], off
	s_add_u32 s100, s19, 0x0
	v_lshl_add_u64 v[192:193], v[190:191], 0, s[100:101]
	s_add_u32 m0, s98, 0x7000
	s_nop 0
	global_load_lds_dwordx4 v[192:193], off
	s_setprio 1
	s_waitcnt vmcnt(15) lgkmcnt(1)
; #define MFMA16(a, b, c) __builtin_amdgcn_mfma_f32_16x16x32_bf16((a), (b), (c), 0, 0, 0)
; template <class Epi>
; DEVI void gemm_tile256b(const bf16_t* __restrict__ A, int lda, const bf16_t* __restrict__ Bt, int K,
;                         int m0, int n0, char* smem, Epi epi) {
;     ...
;     {
;       bf16x8 af[8];
; #pragma unroll
;       for (int i = 0; i < 8; ++i) af[i] = *(const bf16x8*)(base + ((a_rd + i * 2048) ^ 64));
; #pragma unroll
;       for (int mi = 0; mi < 8; ++mi)
; #pragma unroll
;         for (int ni = 0; ni < 4; ++ni) acc[mi][ni] = MFMA16(b1[ni], af[mi], acc[mi][ni]);
;     }
;     if (more) {
;       char* nb = smem + ((kt + 1) & 1) * 32768 + lds_w;
; #pragma unroll
;       for (int i = 0; i < 8; ++i) *(u32x4*)(nb + i * 4096) = ra[i];
;     }
;     __syncthreads();
;   }
; #pragma unroll
;   for (int mi = 0; mi < 8; ++mi)
; #pragma unroll
;     for (int ni = 0; ni < 4; ++ni)
;       epi(m0 + wm * 128 + mi * 16 + l15, n0 + wn * 64 + ni * 16 + quad * 4, acc[mi][ni]);
	v_mfma_f32_16x16x32_bf16 v[134:137], v[146:149], v[174:177], v[134:137]
	s_waitcnt vmcnt(13)
	v_mfma_f32_16x16x32_bf16 v[130:133], v[150:153], v[174:177], v[130:133]
	s_waitcnt vmcnt(11)
	v_mfma_f32_16x16x32_bf16 v[126:129], v[154:157], v[174:177], v[126:129]
	s_waitcnt vmcnt(9)
	v_mfma_f32_16x16x32_bf16 v[122:125], v[158:161], v[174:177], v[122:125]
	s_waitcnt lgkmcnt(0)
	v_mfma_f32_16x16x32_bf16 v[114:117], v[146:149], v[178:181], v[114:117]
	v_mfma_f32_16x16x32_bf16 v[110:113], v[150:153], v[178:181], v[110:113]
	v_mfma_f32_16x16x32_bf16 v[106:109], v[154:157], v[178:181], v[106:109]
	v_mfma_f32_16x16x32_bf16 v[102:105], v[158:161], v[178:181], v[102:105]
	ds_read_b128 v[174:177], v0 offset:4096
	ds_read_b128 v[178:181], v0 offset:6144
	s_waitcnt lgkmcnt(1)
	v_mfma_f32_16x16x32_bf16 v[98:101], v[146:149], v[174:177], v[98:101]
	v_mfma_f32_16x16x32_bf16 v[94:97], v[150:153], v[174:177], v[94:97]
	v_mfma_f32_16x16x32_bf16 v[86:89], v[154:157], v[174:177], v[86:89]
	v_mfma_f32_16x16x32_bf16 v[82:85], v[158:161], v[174:177], v[82:85]
	s_waitcnt lgkmcnt(0)
	v_mfma_f32_16x16x32_bf16 v[74:77], v[146:149], v[178:181], v[74:77]
	v_mfma_f32_16x16x32_bf16 v[70:73], v[150:153], v[178:181], v[70:73]
	v_mfma_f32_16x16x32_bf16 v[62:65], v[154:157], v[178:181], v[62:65]
	v_mfma_f32_16x16x32_bf16 v[66:69], v[158:161], v[178:181], v[66:69]
	ds_read_b128 v[178:181], v0 offset:8192
	ds_read_b128 v[182:185], v0 offset:10240
	s_waitcnt lgkmcnt(1)
	v_mfma_f32_16x16x32_bf16 v[46:49], v[146:149], v[178:181], v[46:49]
	v_mfma_f32_16x16x32_bf16 v[50:53], v[150:153], v[178:181], v[50:53]
	v_mfma_f32_16x16x32_bf16 v[58:61], v[154:157], v[178:181], v[58:61]
	v_mfma_f32_16x16x32_bf16 v[54:57], v[158:161], v[178:181], v[54:57]
	s_waitcnt lgkmcnt(0)
	v_mfma_f32_16x16x32_bf16 v[26:29], v[146:149], v[182:185], v[26:29]
	v_mfma_f32_16x16x32_bf16 v[22:25], v[150:153], v[182:185], v[22:25]
	v_mfma_f32_16x16x32_bf16 v[18:21], v[154:157], v[182:185], v[18:21]
	v_mfma_f32_16x16x32_bf16 v[42:45], v[158:161], v[182:185], v[42:45]
	ds_read_b128 v[178:181], v0 offset:12288
	ds_read_b128 v[182:185], v0 offset:14336
	s_nop 0
	s_nop 0
	s_nop 0
	s_nop 0
	s_nop 0
	s_waitcnt lgkmcnt(1)
	v_mfma_f32_16x16x32_bf16 v[34:37], v[146:149], v[178:181], v[34:37]
	v_mfma_f32_16x16x32_bf16 v[38:41], v[150:153], v[178:181], v[38:41]
	v_mfma_f32_16x16x32_bf16 v[30:33], v[154:157], v[178:181], v[30:33]
	s_setprio 0
	s_waitcnt vmcnt(0) lgkmcnt(0)
	s_barrier
	v_mfma_f32_16x16x32_bf16 v[142:145], v[158:161], v[178:181], v[142:145]
	v_mfma_f32_16x16x32_bf16 v[138:141], v[146:149], v[182:185], v[138:141]
	v_mfma_f32_16x16x32_bf16 v[118:121], v[150:153], v[182:185], v[118:121]
	v_mfma_f32_16x16x32_bf16 v[90:93], v[154:157], v[182:185], v[90:93]
	v_mfma_f32_16x16x32_bf16 v[78:81], v[158:161], v[182:185], v[78:81]
	s_cmp_eq_u32 s1, 0x80000
	s_cbranch_scc0 .LBB0_1873
	s_setprio 0
	v_add_u32_e32 v0, 32, v173
	ds_read_b128 v[146:149], v0 offset:32768
	s_movk_i32 s1, 0x7000
	s_waitcnt lgkmcnt(0)
	v_mfma_f32_16x16x32_bf16 v[134:137], v[10:13], v[146:149], v[134:137]
	v_mfma_f32_16x16x32_bf16 v[130:133], v[14:17], v[146:149], v[130:133]
	v_mfma_f32_16x16x32_bf16 v[150:153], v[6:9], v[146:149], v[126:129]
	v_mfma_f32_16x16x32_bf16 v[146:149], v[2:5], v[146:149], v[122:125]
	s_nop 2
	ds_read_b128 v[122:125], v0 offset:34816
	s_waitcnt lgkmcnt(0)
	v_mfma_f32_16x16x32_bf16 v[164:167], v[2:5], v[122:125], v[102:105]
	s_nop 2
	ds_read_b128 v[102:105], v0 offset:36864
	s_waitcnt lgkmcnt(0)
	v_mfma_f32_16x16x32_bf16 v[176:179], v[14:17], v[102:105], v[94:97]
	s_nop 2
	ds_read_b128 v[94:97], v0 offset:38912
	s_waitcnt lgkmcnt(0)
	v_mfma_f32_16x16x32_bf16 v[74:77], v[10:13], v[94:97], v[74:77]
	v_mfma_f32_16x16x32_bf16 v[70:73], v[14:17], v[94:97], v[70:73]
	v_mfma_f32_16x16x32_bf16 v[62:65], v[6:9], v[94:97], v[62:65]
	v_mfma_f32_16x16x32_bf16 v[66:69], v[2:5], v[94:97], v[66:69]
	ds_read_b128 v[94:97], v0 offset:40960
	s_waitcnt lgkmcnt(0)
	v_mfma_f32_16x16x32_bf16 v[190:193], v[2:5], v[94:97], v[54:57]
	s_nop 2
	ds_read_b128 v[54:57], v0 offset:43008
	s_waitcnt lgkmcnt(0)
	v_mfma_f32_16x16x32_bf16 v[194:197], v[2:5], v[54:57], v[42:45]
	s_nop 2
	ds_read_b128 v[42:45], v0 offset:45056
	s_waitcnt lgkmcnt(0)
	v_mfma_f32_16x16x32_bf16 v[226:229], v[6:9], v[42:45], v[30:33]
	s_nop 2
	ds_read_b128 v[30:33], v0 offset:47104
	v_add_u32_e32 v0, 32, v171
	v_mfma_f32_16x16x32_bf16 v[114:117], v[10:13], v[122:125], v[114:117]
	v_mfma_f32_16x16x32_bf16 v[154:157], v[14:17], v[122:125], v[110:113]
	v_mfma_f32_16x16x32_bf16 v[172:175], v[10:13], v[102:105], v[98:101]
	v_mfma_f32_16x16x32_bf16 v[46:49], v[10:13], v[94:97], v[46:49]
	v_mfma_f32_16x16x32_bf16 v[50:53], v[14:17], v[94:97], v[50:53]
	v_mfma_f32_16x16x32_bf16 v[26:29], v[10:13], v[54:57], v[26:29]
	v_mfma_f32_16x16x32_bf16 v[22:25], v[14:17], v[54:57], v[22:25]
	v_mfma_f32_16x16x32_bf16 v[198:201], v[10:13], v[42:45], v[34:37]
	v_mfma_f32_16x16x32_bf16 v[202:205], v[14:17], v[42:45], v[38:41]
	s_waitcnt lgkmcnt(0)
	v_mfma_f32_16x16x32_bf16 v[10:13], v[10:13], v[30:33], v[138:141]
	v_mfma_f32_16x16x32_bf16 v[138:141], v[14:17], v[30:33], v[118:121]
	v_add_co_u32_e32 v14, vcc, s1, v162
	s_mov_b32 s1, 0xf000
	s_nop 0
	v_addc_co_u32_e32 v15, vcc, 0, v163, vcc
	global_load_dwordx4 v[14:17], v[14:15], off offset:3072
	v_mfma_f32_16x16x32_bf16 v[158:161], v[6:9], v[122:125], v[106:109]
	v_add_co_u32_e32 v34, vcc, s1, v162
	s_mov_b32 s1, 0x17000
	v_mfma_f32_16x16x32_bf16 v[86:89], v[6:9], v[102:105], v[86:89]
	v_addc_co_u32_e32 v35, vcc, 0, v163, vcc
	global_load_dwordx4 v[230:233], v[34:35], off offset:3072
	v_mfma_f32_16x16x32_bf16 v[82:85], v[2:5], v[102:105], v[82:85]
	v_add_co_u32_e32 v34, vcc, s1, v162
	s_mov_b32 s1, 0x1f000
	v_mfma_f32_16x16x32_bf16 v[180:183], v[6:9], v[94:97], v[58:61]
	v_addc_co_u32_e32 v35, vcc, 0, v163, vcc
	v_mfma_f32_16x16x32_bf16 v[18:21], v[6:9], v[54:57], v[18:21]
	v_mfma_f32_16x16x32_bf16 v[142:145], v[2:5], v[42:45], v[142:145]
	v_mfma_f32_16x16x32_bf16 v[6:9], v[6:9], v[30:33], v[90:93]
	v_mfma_f32_16x16x32_bf16 v[2:5], v[2:5], v[30:33], v[78:81]
	ds_read_b128 v[30:33], v0 offset:32768
	s_waitcnt vmcnt(1) lgkmcnt(0)
; #define MFMA16(a, b, c) __builtin_amdgcn_mfma_f32_16x16x32_bf16((a), (b), (c), 0, 0, 0)
; template <class Epi>
; DEVI void gemm_tile256b(const bf16_t* __restrict__ A, int lda, const bf16_t* __restrict__ Bt, int K,
;                         int m0, int n0, char* smem, Epi epi) {
;     ...
;     {
;       bf16x8 af[8];
; #pragma unroll
;       for (int i = 0; i < 8; ++i) af[i] = *(const bf16x8*)(base + ((a_rd + i * 2048) ^ 64));
; #pragma unroll
;       for (int mi = 0; mi < 8; ++mi)
; #pragma unroll
;         for (int ni = 0; ni < 4; ++ni) acc[mi][ni] = MFMA16(b1[ni], af[mi], acc[mi][ni]);
;     }
;     if (more) {
;       char* nb = smem + ((kt + 1) & 1) * 32768 + lds_w;
; #pragma unroll
;       for (int i = 0; i < 8; ++i) *(u32x4*)(nb + i * 4096) = ra[i];
;     }
;     __syncthreads();
;   }
; #pragma unroll
;   for (int mi = 0; mi < 8; ++mi)
; #pragma unroll
;     for (int ni = 0; ni < 4; ++ni)
;       epi(m0 + wm * 128 + mi * 16 + l15, n0 + wn * 64 + ni * 16 + quad * 4, acc[mi][ni]);
;   DEVI void operator()(int m, int n, f32x4 v) const {
;     if (m >= L) return;
;     float a = fmaxf(v[0], 0.f), b = fmaxf(v[1], 0.f), c = fmaxf(v[2], 0.f), d = fmaxf(v[3], 0.f);
;     *(u32x2*)(hid + (size_t)m * 4096 + n) = u32x2{pack2(a * a, b * b), pack2(c * c, d * d)};
;   }
	v_mfma_f32_16x16x32_bf16 v[126:129], v[14:17], v[30:33], v[134:137]
	s_nop 2
	global_load_dwordx4 v[134:137], v[34:35], off offset:3072
	v_add_co_u32_e32 v34, vcc, s1, v162
	s_waitcnt vmcnt(1)
	v_mfma_f32_16x16x32_bf16 v[122:125], v[230:233], v[30:33], v[130:133]
	v_addc_co_u32_e32 v35, vcc, 0, v163, vcc
	s_nop 1
	v_lshl_or_b32 v130, v169, 2, v170
	s_waitcnt vmcnt(0)
	v_mfma_f32_16x16x32_bf16 v[118:121], v[134:137], v[30:33], v[150:153]
	s_nop 2
	global_load_dwordx4 v[150:153], v[34:35], off offset:3072
	v_ashrrev_i32_e32 v131, 31, v130
	s_waitcnt vmcnt(0)
	v_mfma_f32_16x16x32_bf16 v[110:113], v[150:153], v[30:33], v[146:149]
	ds_read_b128 v[30:33], v0 offset:34816
	s_waitcnt lgkmcnt(0)
	v_mfma_f32_16x16x32_bf16 v[114:117], v[14:17], v[30:33], v[114:117]
	v_mfma_f32_16x16x32_bf16 v[106:109], v[230:233], v[30:33], v[154:157]
	v_mfma_f32_16x16x32_bf16 v[102:105], v[134:137], v[30:33], v[158:161]
	v_mfma_f32_16x16x32_bf16 v[98:101], v[150:153], v[30:33], v[164:167]
	ds_read_b128 v[30:33], v0 offset:36864
	s_waitcnt lgkmcnt(0)
	v_mfma_f32_16x16x32_bf16 v[94:97], v[14:17], v[30:33], v[172:175]
	v_mfma_f32_16x16x32_bf16 v[90:93], v[230:233], v[30:33], v[176:179]
	v_mfma_f32_16x16x32_bf16 v[86:89], v[134:137], v[30:33], v[86:89]
	v_mfma_f32_16x16x32_bf16 v[82:85], v[150:153], v[30:33], v[82:85]
	ds_read_b128 v[30:33], v0 offset:38912
	s_waitcnt lgkmcnt(0)
	v_mfma_f32_16x16x32_bf16 v[78:81], v[14:17], v[30:33], v[74:77]
	v_mfma_f32_16x16x32_bf16 v[74:77], v[230:233], v[30:33], v[70:73]
	v_mfma_f32_16x16x32_bf16 v[70:73], v[134:137], v[30:33], v[62:65]
	v_mfma_f32_16x16x32_bf16 v[66:69], v[150:153], v[30:33], v[66:69]
	ds_read_b128 v[30:33], v0 offset:40960
	s_waitcnt lgkmcnt(0)
	v_mfma_f32_16x16x32_bf16 v[62:65], v[14:17], v[30:33], v[46:49]
	v_mfma_f32_16x16x32_bf16 v[58:61], v[230:233], v[30:33], v[50:53]
	v_mfma_f32_16x16x32_bf16 v[54:57], v[134:137], v[30:33], v[180:183]
	v_mfma_f32_16x16x32_bf16 v[50:53], v[150:153], v[30:33], v[190:193]
	ds_read_b128 v[30:33], v0 offset:43008
	s_waitcnt lgkmcnt(0)
	v_mfma_f32_16x16x32_bf16 v[38:41], v[134:137], v[30:33], v[18:21]
	s_nop 2
	ds_read_b128 v[18:21], v0 offset:45056
	v_mfma_f32_16x16x32_bf16 v[46:49], v[14:17], v[30:33], v[26:29]
	v_mfma_f32_16x16x32_bf16 v[42:45], v[230:233], v[30:33], v[22:25]
	v_mfma_f32_16x16x32_bf16 v[34:37], v[150:153], v[30:33], v[194:197]
	s_waitcnt lgkmcnt(0)
	v_mfma_f32_16x16x32_bf16 v[30:33], v[14:17], v[18:21], v[198:201]
	v_mfma_f32_16x16x32_bf16 v[26:29], v[230:233], v[18:21], v[202:205]
	v_mfma_f32_16x16x32_bf16 v[22:25], v[134:137], v[18:21], v[226:229]
	v_mfma_f32_16x16x32_bf16 v[18:21], v[150:153], v[18:21], v[142:145]
	s_nop 2
	ds_read_b128 v[142:145], v0 offset:47104
	s_waitcnt lgkmcnt(0)
	v_mfma_f32_16x16x32_bf16 v[14:17], v[14:17], v[142:145], v[10:13]
	v_and_b32_e32 v0, 0xffffff80, v168
	v_add_u32_e32 v0, s0, v0
	v_and_or_b32 v132, v168, 15, v0
	v_mfma_f32_16x16x32_bf16 v[10:13], v[230:233], v[142:145], v[138:141]
	s_movk_i32 s0, 0x4010
	v_cmp_gt_i32_e32 vcc, s0, v132
	v_mfma_f32_16x16x32_bf16 v[6:9], v[134:137], v[142:145], v[6:9]
	s_barrier
	v_mfma_f32_16x16x32_bf16 v[2:5], v[150:153], v[142:145], v[2:5]
	s_and_saveexec_b64 s[0:1], vcc
	s_cbranch_execz .LBB0_1876
	v_max_f32_e32 v0, v126, v126
	v_max_f32_e32 v126, 0, v0
	v_max_f32_e32 v0, v127, v127
	v_max_f32_e32 v127, 0, v0
	v_max_f32_e32 v0, v128, v128
	v_max_f32_e32 v128, 0, v0
	v_max_f32_e32 v0, v129, v129
	v_max_f32_e32 v129, 0, v0
	v_max_f32_e32 v0, v122, v122
	v_max_f32_e32 v122, 0, v0
	v_max_f32_e32 v0, v123, v123
	v_max_f32_e32 v123, 0, v0
	v_max_f32_e32 v0, v124, v124
	v_max_f32_e32 v124, 0, v0
	v_max_f32_e32 v0, v125, v125
	v_max_f32_e32 v125, 0, v0
	v_max_f32_e32 v0, v118, v118
	v_max_f32_e32 v118, 0, v0
	v_max_f32_e32 v0, v119, v119
	v_max_f32_e32 v119, 0, v0
	v_max_f32_e32 v0, v120, v120
	v_max_f32_e32 v120, 0, v0
	v_max_f32_e32 v0, v121, v121
	v_max_f32_e32 v121, 0, v0
	v_max_f32_e32 v0, v110, v110
	v_max_f32_e32 v110, 0, v0
	v_max_f32_e32 v0, v111, v111
	v_max_f32_e32 v111, 0, v0
	v_max_f32_e32 v0, v112, v112
	v_ashrrev_i32_e32 v133, 31, v132
	v_max_f32_e32 v112, 0, v0
	v_max_f32_e32 v0, v113, v113
	v_lshlrev_b64 v[134:135], 13, v[132:133]
	v_max_f32_e32 v113, 0, v0
	v_lshl_add_u64 v[134:135], s[30:31], 0, v[134:135]
	v_pk_mul_f32 v[126:127], v[126:127], v[126:127]
	v_pk_mul_f32 v[128:129], v[128:129], v[128:129]
	v_pk_mul_f32 v[122:123], v[122:123], v[122:123]
	v_pk_mul_f32 v[124:125], v[124:125], v[124:125]
	v_pk_mul_f32 v[118:119], v[118:119], v[118:119]
	v_pk_mul_f32 v[120:121], v[120:121], v[120:121]
	v_pk_mul_f32 v[110:111], v[110:111], v[110:111]
	v_pk_mul_f32 v[112:113], v[112:113], v[112:113]
	v_cvt_pk_bf16_f32 v126, v126, v127
	v_cvt_pk_bf16_f32 v127, v128, v129
	v_lshl_add_u64 v[128:129], v[130:131], 1, v[134:135]
	v_cvt_pk_bf16_f32 v122, v122, v123
	v_cvt_pk_bf16_f32 v123, v124, v125
	v_cvt_pk_bf16_f32 v118, v118, v119
	v_cvt_pk_bf16_f32 v119, v120, v121
	v_cvt_pk_bf16_f32 v110, v110, v111
	v_cvt_pk_bf16_f32 v111, v112, v113
	global_store_dwordx2 v[128:129], v[126:127], off
	global_store_dwordx2 v[128:129], v[122:123], off offset:32
	global_store_dwordx2 v[128:129], v[118:119], off offset:64
	global_store_dwordx2 v[128:129], v[110:111], off offset:96
